# v4_nt
# speedup vs baseline: 1.0313x; 1.0313x over previous
; #define LAS __attribute__((address_space(3)))
; #define LDS_WAIT() asm volatile("s_waitcnt lgkmcnt(0)" ::: "memory")
; __device__ __forceinline__ void transpose_item_f8(const float* W, int N, unsigned char* WT, int nkt, int k0, int n0, int r0, int kt8, int koff, LAS float* scr, int lane) {
;     const size_t dst_off = ((size_t)(r0 >> 8) * nkt + kt8) * 32768 + (size_t)(r0 & 255) * 128 + koff;
;     const int l15 = lane & 15, lq = lane >> 4;
;     f32x4 v[16];
; #pragma unroll
;     for (int i = 0; i < 16; ++i) v[i] = *(const f32x4*)(W + (size_t)(k0 + 4 * i + lq) * N + n0 + 4 * l15);
; #pragma unroll
;     for (int i = 0; i < 16; ++i) { LAS float* d = scr + (4 * i + lq) * 65 + 4 * l15; d[0] = v[i][0]; d[1] = v[i][1]; d[2] = v[i][2]; d[3] = v[i][3]; }
;     LDS_WAIT();
;     const int c = lane & 3;
; #pragma unroll
;     for (int j = 0; j < 4; ++j) { const int n = (lane >> 2) + 16 * j; const LAS float* s = scr + (16 * c) * 65 + n; u32x4 o;
; #pragma unroll
;         for (int q = 0; q < 4; ++q) { int w = __builtin_amdgcn_cvt_pk_fp8_f32(s[(4 * q) * 65] * 1024.f, s[(4 * q + 1) * 65] * 1024.f, 0, false);
;             w = __builtin_amdgcn_cvt_pk_fp8_f32(s[(4 * q + 2) * 65] * 1024.f, s[(4 * q + 3) * 65] * 1024.f, w, true); o[q] = (unsigned)w; }
; __device__ __forceinline__ void phase0(const Params& p, LAS unsigned char* lds, int gw, int NGW, int wave, int lane, int G) {
;     ...
;     for (int it = gw; it < I0; it += NGW) {
;         const int nb = it % 192, kb = it / 192;
;         if (nb < 64) transpose_item(p.in[2], DIN, (bf16_t*)(ws + WS_W_IN), 64, kb * 64, nb * 64, nb * 64, kb, scr, lane);
;         else transpose_item_f8(p.in[2], DIN, ws + WS_W_IN + ((size_t)32 << 20), 32, kb * 64, nb * 64, (nb - 64) * 64, kb >> 1, (kb & 1) * 64, scr, lane);
.LBB0_23:
	s_mul_hi_i32 s4, s64, 0x2aaaaaab
	s_lshr_b32 s5, s4, 31
	s_ashr_i32 s4, s4, 5
	s_add_i32 s4, s4, s5
	s_mul_i32 s5, s4, 0xffffff40
	s_lshl_b32 s65, s4, 6
	s_mul_i32 s6, s4, 0xffffd000
	s_add_i32 s5, s64, s5
	s_add_i32 s6, s16, s6
	v_or_b32_e32 v71, s65, v30
	s_cmp_gt_i32 s5, 63
	s_mov_b64 s[10:11], -1
	v_or_b32_e32 v70, 4, v71
	v_or_b32_e32 v69, 8, v71
	v_or_b32_e32 v68, 12, v71
	v_or_b32_e32 v67, 16, v71
	v_or_b32_e32 v66, 20, v71
	v_or_b32_e32 v65, 24, v71
	v_or_b32_e32 v64, 28, v71
	v_or_b32_e32 v63, 32, v71
	v_or_b32_e32 v62, 36, v71
	v_or_b32_e32 v25, 40, v71
	v_or_b32_e32 v27, 44, v71
	v_or_b32_e32 v29, 48, v71
	v_or_b32_e32 v23, 52, v71
	v_or_b32_e32 v21, 56, v71
	v_or_b32_e32 v19, 60, v71
	v_add_u32_e32 v15, 0x3cf0, v33
	v_add_u32_e32 v17, 0x3cf8, v33
	s_cbranch_scc0 .LBB0_25
	s_mov_b32 s7, s3
	v_lshl_add_u64 v[132:133], s[6:7], 2, v[12:13]
	v_mad_i64_i32 v[72:73], s[10:11], v71, s63, v[132:133]
	v_mad_i64_i32 v[76:77], s[10:11], v70, s63, v[132:133]
	v_mad_i64_i32 v[80:81], s[10:11], v69, s63, v[132:133]
	v_mad_i64_i32 v[84:85], s[10:11], v68, s63, v[132:133]
	v_mad_i64_i32 v[88:89], s[10:11], v67, s63, v[132:133]
	v_mad_i64_i32 v[92:93], s[10:11], v66, s63, v[132:133]
	v_mad_i64_i32 v[96:97], s[10:11], v65, s63, v[132:133]
	v_mad_i64_i32 v[100:101], s[10:11], v64, s63, v[132:133]
	v_mad_i64_i32 v[104:105], s[10:11], v63, s63, v[132:133]
	v_mad_i64_i32 v[108:109], s[10:11], v62, s63, v[132:133]
	v_mad_i64_i32 v[112:113], s[10:11], v25, s63, v[132:133]
	v_mad_i64_i32 v[116:117], s[10:11], v27, s63, v[132:133]
	v_mad_i64_i32 v[120:121], s[10:11], v29, s63, v[132:133]
	v_mad_i64_i32 v[124:125], s[10:11], v23, s63, v[132:133]
	v_mad_i64_i32 v[128:129], s[10:11], v21, s63, v[132:133]
	global_load_dwordx4 v[72:75], v[72:73], off nt
	s_nop 0
	global_load_dwordx4 v[76:79], v[76:77], off nt
	s_nop 0
	global_load_dwordx4 v[80:83], v[80:81], off nt
	s_nop 0
	global_load_dwordx4 v[84:87], v[84:85], off nt
	s_nop 0
	global_load_dwordx4 v[88:91], v[88:89], off nt
	s_nop 0
	global_load_dwordx4 v[92:95], v[92:93], off nt
	s_nop 0
	global_load_dwordx4 v[96:99], v[96:97], off nt
	s_nop 0
	global_load_dwordx4 v[100:103], v[100:101], off nt
	v_mad_i64_i32 v[132:133], s[10:11], v19, s63, v[132:133]
	global_load_dwordx4 v[104:107], v[104:105], off nt
	s_nop 0
	global_load_dwordx4 v[108:111], v[108:109], off nt
	s_nop 0
	global_load_dwordx4 v[112:115], v[112:113], off nt
	s_nop 0
	global_load_dwordx4 v[116:119], v[116:117], off nt
	s_nop 0
	global_load_dwordx4 v[120:123], v[120:121], off nt
	s_nop 0
	global_load_dwordx4 v[124:127], v[124:125], off nt
	s_nop 0
	global_load_dwordx4 v[128:131], v[128:129], off nt
	v_mov_b32_e32 v136, v1
	global_load_dwordx4 v[132:135], v[132:133], off nt
	v_mov_b32_e32 v137, v1
	v_mov_b32_e32 v138, v1
	v_mov_b32_e32 v139, v1
	s_add_i32 s7, s6, 0xfffff000
	s_ashr_i32 s10, s4, 1
	s_lshr_b32 s7, s7, 3
	s_and_b32 s65, s65, 64
	s_and_b32 s7, s7, 0x3e0
	s_ashr_i32 s11, s10, 31
	s_add_u32 s10, s7, s10
	s_addc_u32 s11, 0, s11
	s_and_b32 s7, s33, 0x6000
	s_lshl_b64 s[10:11], s[10:11], 15
	s_add_u32 s10, s8, s10
	s_addc_u32 s11, s9, s11
	s_add_u32 s7, s10, s7
	s_addc_u32 s11, s11, 0
	s_add_u32 s10, s7, s65
	s_addc_u32 s11, s11, 0
	s_waitcnt vmcnt(15)
	ds_write2_b32 v33, v72, v73 offset1:1
	ds_write2_b32 v33, v74, v75 offset0:2 offset1:3
	s_waitcnt vmcnt(14)
	ds_write2_b32 v34, v76, v77 offset1:1
	ds_write2_b32 v35, v78, v79 offset1:1
	s_waitcnt vmcnt(13)
	ds_write2_b32 v36, v80, v81 offset1:1
	ds_write2_b32 v37, v82, v83 offset1:1
	s_waitcnt vmcnt(12)
	ds_write2_b32 v38, v84, v85 offset1:1
	ds_write2_b32 v39, v86, v87 offset1:1
	s_waitcnt vmcnt(11)
	ds_write2_b32 v40, v88, v89 offset1:1
	ds_write2_b32 v41, v90, v91 offset1:1
	s_waitcnt vmcnt(10)
	ds_write2_b32 v42, v92, v93 offset1:1
	ds_write2_b32 v43, v94, v95 offset1:1
	s_waitcnt vmcnt(9)
	ds_write2_b32 v44, v96, v97 offset1:1
	ds_write2_b32 v45, v98, v99 offset1:1
	s_waitcnt vmcnt(8)
	ds_write2_b32 v46, v100, v101 offset1:1
	ds_write2_b32 v47, v102, v103 offset1:1
	s_waitcnt vmcnt(7)
	ds_write2_b32 v48, v104, v105 offset1:1
	ds_write2_b32 v49, v106, v107 offset1:1
	s_waitcnt vmcnt(6)
	ds_write2_b32 v50, v108, v109 offset1:1
	ds_write2_b32 v51, v110, v111 offset1:1
	s_waitcnt vmcnt(5)
	ds_write2_b32 v52, v112, v113 offset1:1
	ds_write2_b32 v53, v114, v115 offset1:1
	s_waitcnt vmcnt(4)
	ds_write2_b32 v54, v116, v117 offset1:1
	ds_write2_b32 v55, v118, v119 offset1:1
	s_waitcnt vmcnt(3)
	ds_write2_b32 v56, v120, v121 offset1:1
	ds_write2_b32 v57, v122, v123 offset1:1
	s_waitcnt vmcnt(2)
	ds_write2_b32 v58, v124, v125 offset1:1
	ds_write2_b32 v59, v126, v127 offset1:1
	s_waitcnt vmcnt(1)
	ds_write2_b32 v60, v128, v129 offset1:1
	ds_write2_b32 v61, v130, v131 offset1:1
	s_waitcnt vmcnt(0)
	ds_write2_b32 v15, v132, v133 offset1:1
	ds_write2_b32 v17, v134, v135 offset1:1
	s_waitcnt lgkmcnt(0)
	ds_read2_b32 v[72:73], v31 offset1:16
	ds_read2_b32 v[74:75], v31 offset0:65 offset1:81
	v_add_u32_e32 v104, 0x400, v31
	ds_read2_b32 v[76:77], v31 offset0:130 offset1:146
	ds_read2_b32 v[78:79], v31 offset0:195 offset1:211
	ds_read2_b32 v[80:81], v104 offset0:4 offset1:20
	ds_read2_b32 v[82:83], v104 offset0:69 offset1:85
	s_waitcnt lgkmcnt(5)
	v_mul_f32_e32 v72, 0x44800000, v72
	s_waitcnt lgkmcnt(4)
	v_mul_f32_e32 v74, 0x44800000, v74
	v_cvt_pk_fp8_f32 v136, v72, v74
	s_waitcnt lgkmcnt(3)
	v_mul_f32_e32 v72, 0x44800000, v76
	s_waitcnt lgkmcnt(2)
	v_mul_f32_e32 v74, 0x44800000, v78
	ds_read2_b32 v[84:85], v104 offset0:134 offset1:150
	ds_read2_b32 v[86:87], v104 offset0:199 offset1:215
	v_add_u32_e32 v105, 0x800, v31
	v_cvt_pk_fp8_f32 v136, v72, v74 op_sel:[0,0,1]
	s_waitcnt lgkmcnt(3)
; #define LAS __attribute__((address_space(3)))
; #define LDS_WAIT() asm volatile("s_waitcnt lgkmcnt(0)" ::: "memory")
; __device__ __forceinline__ void transpose_item_f8(const float* W, int N, unsigned char* WT, int nkt, int k0, int n0, int r0, int kt8, int koff, LAS float* scr, int lane) {
;     ...
;     const int c = lane & 3;
; #pragma unroll
;     for (int j = 0; j < 4; ++j) { const int n = (lane >> 2) + 16 * j; const LAS float* s = scr + (16 * c) * 65 + n; u32x4 o;
; #pragma unroll
;         for (int q = 0; q < 4; ++q) { int w = __builtin_amdgcn_cvt_pk_fp8_f32(s[(4 * q) * 65] * 1024.f, s[(4 * q + 1) * 65] * 1024.f, 0, false);
;             w = __builtin_amdgcn_cvt_pk_fp8_f32(s[(4 * q + 2) * 65] * 1024.f, s[(4 * q + 3) * 65] * 1024.f, w, true); o[q] = (unsigned)w; }
;         *(u32x4*)(WT + dst_off + (size_t)n * 128 + 16 * c) = o; }
;     LDS_WAIT();
	v_mul_f32_e32 v72, 0x44800000, v80
	s_waitcnt lgkmcnt(2)
	v_mul_f32_e32 v74, 0x44800000, v82
	ds_read2_b32 v[88:89], v105 offset0:8 offset1:24
	ds_read2_b32 v[90:91], v105 offset0:73 offset1:89
	v_cvt_pk_fp8_f32 v137, v72, v74
	s_waitcnt lgkmcnt(3)
	v_mul_f32_e32 v72, 0x44800000, v84
	s_waitcnt lgkmcnt(2)
	v_mul_f32_e32 v74, 0x44800000, v86
	ds_read2_b32 v[92:93], v105 offset0:138 offset1:154
	ds_read2_b32 v[94:95], v105 offset0:203 offset1:219
	v_add_u32_e32 v108, 0xc00, v31
	v_cvt_pk_fp8_f32 v137, v72, v74 op_sel:[0,0,1]
	s_waitcnt lgkmcnt(3)
	v_mul_f32_e32 v72, 0x44800000, v88
	s_waitcnt lgkmcnt(2)
	v_mul_f32_e32 v74, 0x44800000, v90
	ds_read2_b32 v[96:97], v108 offset0:12 offset1:28
	ds_read2_b32 v[98:99], v108 offset0:77 offset1:93
	v_cvt_pk_fp8_f32 v138, v72, v74
	s_waitcnt lgkmcnt(3)
	v_mul_f32_e32 v72, 0x44800000, v92
	s_waitcnt lgkmcnt(2)
	v_mul_f32_e32 v74, 0x44800000, v94
	ds_read2_b32 v[100:101], v108 offset0:142 offset1:158
	ds_read2_b32 v[102:103], v108 offset0:207 offset1:223
	v_cvt_pk_fp8_f32 v138, v72, v74 op_sel:[0,0,1]
	s_waitcnt lgkmcnt(3)
	v_mul_f32_e32 v72, 0x44800000, v96
	s_waitcnt lgkmcnt(2)
	v_mul_f32_e32 v74, 0x44800000, v98
	v_cvt_pk_fp8_f32 v139, v72, v74
	v_mul_f32_e32 v73, 0x44800000, v73
	v_mul_f32_e32 v74, 0x44800000, v75
	v_mov_b32_e32 v72, v1
	v_cvt_pk_fp8_f32 v72, v73, v74
	s_waitcnt lgkmcnt(1)
	v_mul_f32_e32 v73, 0x44800000, v100
	s_waitcnt lgkmcnt(0)
	v_mul_f32_e32 v74, 0x44800000, v102
	v_cvt_pk_fp8_f32 v139, v73, v74 op_sel:[0,0,1]
	v_mul_f32_e32 v73, 0x44800000, v77
	v_mul_f32_e32 v74, 0x44800000, v79
	v_cvt_pk_fp8_f32 v72, v73, v74 op_sel:[0,0,1]
	v_mul_f32_e32 v74, 0x44800000, v81
	v_mul_f32_e32 v75, 0x44800000, v83
	v_mov_b32_e32 v73, v1
	v_cvt_pk_fp8_f32 v73, v74, v75
	v_mul_f32_e32 v74, 0x44800000, v85
	v_mul_f32_e32 v75, 0x44800000, v87
	v_mul_f32_e32 v78, 0x44800000, v91
	v_cvt_pk_fp8_f32 v73, v74, v75 op_sel:[0,0,1]
	v_mul_f32_e32 v75, 0x44800000, v89
	v_mov_b32_e32 v74, v1
	v_cvt_pk_fp8_f32 v74, v75, v78
	v_mul_f32_e32 v82, 0x44800000, v97
	v_mul_f32_e32 v83, 0x44800000, v99
	v_mov_b32_e32 v75, v1
	v_cvt_pk_fp8_f32 v75, v82, v83
	v_mul_f32_e32 v78, 0x44800000, v93
	v_mul_f32_e32 v79, 0x44800000, v95
	v_cvt_pk_fp8_f32 v74, v78, v79 op_sel:[0,0,1]
	v_mul_f32_e32 v78, 0x44800000, v101
	v_mul_f32_e32 v79, 0x44800000, v103
	v_cvt_pk_fp8_f32 v75, v78, v79 op_sel:[0,0,1]
	v_lshl_add_u64 v[80:81], s[10:11], 0, v[2:3]
	ds_read2_b32 v[78:79], v31 offset0:32 offset1:48
	ds_read2_b32 v[82:83], v31 offset0:97 offset1:113
	v_lshl_add_u64 v[76:77], v[80:81], 0, v[4:5]
	global_store_dwordx4 v[76:77], v[136:139], off
	v_lshl_add_u64 v[76:77], v[80:81], 0, v[6:7]
	global_store_dwordx4 v[76:77], v[72:75], off
	ds_read2_b32 v[84:85], v31 offset0:162 offset1:178
	ds_read2_b32 v[86:87], v31 offset0:227 offset1:243
	s_waitcnt lgkmcnt(3)
	v_mul_f32_e32 v73, 0x44800000, v78
	s_waitcnt lgkmcnt(2)
	v_mul_f32_e32 v74, 0x44800000, v82
	v_mov_b32_e32 v72, v1
	ds_read2_b32 v[76:77], v104 offset0:36 offset1:52
	ds_read2_b32 v[88:89], v104 offset0:101 offset1:117
	v_cvt_pk_fp8_f32 v72, v73, v74
	s_waitcnt lgkmcnt(3)
	v_mul_f32_e32 v73, 0x44800000, v84
	s_waitcnt lgkmcnt(2)
	v_mul_f32_e32 v74, 0x44800000, v86
	ds_read2_b32 v[90:91], v104 offset0:166 offset1:182
	ds_read2_b32 v[92:93], v104 offset0:231 offset1:247
	v_cvt_pk_fp8_f32 v72, v73, v74 op_sel:[0,0,1]
	s_waitcnt lgkmcnt(3)
	v_mul_f32_e32 v74, 0x44800000, v76
	s_waitcnt lgkmcnt(2)
	v_mul_f32_e32 v75, 0x44800000, v88
	v_mov_b32_e32 v73, v1
	ds_read2_b32 v[94:95], v105 offset0:40 offset1:56
	ds_read2_b32 v[96:97], v105 offset0:105 offset1:121
	v_cvt_pk_fp8_f32 v73, v74, v75
	ds_read2_b32 v[98:99], v105 offset0:170 offset1:186
	ds_read2_b32 v[100:101], v105 offset0:235 offset1:251
	ds_read2_b32 v[102:103], v108 offset0:44 offset1:60
	ds_read2_b32 v[104:105], v108 offset0:109 offset1:125
	s_waitcnt lgkmcnt(7)
	v_mul_f32_e32 v74, 0x44800000, v90
	s_waitcnt lgkmcnt(6)
	v_mul_f32_e32 v75, 0x44800000, v92
	v_cvt_pk_fp8_f32 v73, v74, v75 op_sel:[0,0,1]
	s_waitcnt lgkmcnt(5)
	v_mul_f32_e32 v75, 0x44800000, v94
	s_waitcnt lgkmcnt(4)
	v_mul_f32_e32 v76, 0x44800000, v96
	v_mov_b32_e32 v74, v1
	ds_read2_b32 v[106:107], v108 offset0:174 offset1:190
	ds_read2_b32 v[108:109], v108 offset0:239 offset1:255
	v_cvt_pk_fp8_f32 v74, v75, v76
	v_mov_b32_e32 v75, v1
	s_waitcnt lgkmcnt(3)
	v_mul_f32_e32 v82, 0x44800000, v102
	s_waitcnt lgkmcnt(2)
	v_mul_f32_e32 v84, 0x44800000, v104
	v_cvt_pk_fp8_f32 v75, v82, v84
	v_mul_f32_e32 v76, 0x44800000, v98
	v_mul_f32_e32 v78, 0x44800000, v100
	v_cvt_pk_fp8_f32 v74, v76, v78 op_sel:[0,0,1]
	s_waitcnt lgkmcnt(1)
	v_mul_f32_e32 v76, 0x44800000, v106
	s_waitcnt lgkmcnt(0)
	v_mul_f32_e32 v78, 0x44800000, v108
	v_cvt_pk_fp8_f32 v75, v76, v78 op_sel:[0,0,1]
	v_mul_f32_e32 v78, 0x44800000, v79
	v_mul_f32_e32 v79, 0x44800000, v83
	v_mov_b32_e32 v76, v1
	v_cvt_pk_fp8_f32 v76, v78, v79
	v_mul_f32_e32 v78, 0x44800000, v77
	v_mul_f32_e32 v79, 0x44800000, v89
	v_mov_b32_e32 v77, v1
	v_cvt_pk_fp8_f32 v77, v78, v79
	v_mul_f32_e32 v78, 0x44800000, v85
	v_mul_f32_e32 v79, 0x44800000, v87
	v_cvt_pk_fp8_f32 v76, v78, v79 op_sel:[0,0,1]
	v_mul_f32_e32 v78, 0x44800000, v91
	v_mul_f32_e32 v79, 0x44800000, v93
	v_cvt_pk_fp8_f32 v77, v78, v79 op_sel:[0,0,1]
	v_mul_f32_e32 v79, 0x44800000, v95
	v_mul_f32_e32 v82, 0x44800000, v97
	v_mov_b32_e32 v78, v1
	v_cvt_pk_fp8_f32 v78, v79, v82
	v_mul_f32_e32 v84, 0x44800000, v103
	v_mul_f32_e32 v85, 0x44800000, v105
	v_mov_b32_e32 v79, v1
	v_cvt_pk_fp8_f32 v79, v84, v85
	v_mul_f32_e32 v82, 0x44800000, v99
	v_mul_f32_e32 v83, 0x44800000, v101
	v_cvt_pk_fp8_f32 v78, v82, v83 op_sel:[0,0,1]
	v_mul_f32_e32 v82, 0x44800000, v107
	v_mul_f32_e32 v83, 0x44800000, v109
	v_cvt_pk_fp8_f32 v79, v82, v83 op_sel:[0,0,1]
	v_lshl_add_u64 v[82:83], v[80:81], 0, v[8:9]
	global_store_dwordx4 v[82:83], v[72:75], off
	s_mov_b64 s[10:11], 0
	s_nop 0
	v_lshl_add_u64 v[72:73], v[80:81], 0, v[10:11]
	global_store_dwordx4 v[72:73], v[76:79], off
	s_waitcnt lgkmcnt(0)
; #define LAS __attribute__((address_space(3)))
; #define LDS_WAIT() asm volatile("s_waitcnt lgkmcnt(0)" ::: "memory")
; __device__ __forceinline__ void transpose_item(const float* W, int N, bf16_t* WT, int nkt, int k0, int n0, int r0, int kbd, LAS float* scr, int lane) {
;     const size_t dst_off = ((size_t)(r0 >> 8) * nkt + kbd) * 16384 + (size_t)(r0 & 255) * 64;
;     const int l15 = lane & 15, lq = lane >> 4;
;     f32x4 v[16];
; #pragma unroll
;     for (int i = 0; i < 16; ++i) v[i] = *(const f32x4*)(W + (size_t)(k0 + 4 * i + lq) * N + n0 + 4 * l15);
; #pragma unroll
;     for (int i = 0; i < 16; ++i) { LAS float* d = scr + (4 * i + lq) * 65 + 4 * l15; d[0] = v[i][0]; d[1] = v[i][1]; d[2] = v[i][2]; d[3] = v[i][3]; }
;     LDS_WAIT();
; __device__ __forceinline__ void phase0(const Params& p, LAS unsigned char* lds, int gw, int NGW, int wave, int lane, int G) {
;     ...
;         if (nb < 64) transpose_item(p.in[2], DIN, (bf16_t*)(ws + WS_W_IN), 64, kb * 64, nb * 64, nb * 64, kb, scr, lane);
.LBB0_25:
	s_andn2_b64 vcc, exec, s[10:11]
	s_cbranch_vccnz .LBB0_22
	s_ashr_i32 s7, s6, 31
	v_lshl_add_u64 v[122:123], s[6:7], 2, v[12:13]
	v_mad_i64_i32 v[72:73], s[6:7], v71, s63, v[122:123]
	v_mad_i64_i32 v[74:75], s[6:7], v70, s63, v[122:123]
	v_mad_i64_i32 v[78:79], s[6:7], v69, s63, v[122:123]
	v_mad_i64_i32 v[68:69], s[6:7], v68, s63, v[122:123]
	global_load_dwordx4 v[70:73], v[72:73], off nt
	s_nop 0
	global_load_dwordx4 v[74:77], v[74:75], off nt
	s_nop 0
	global_load_dwordx4 v[78:81], v[78:79], off nt
	s_nop 0
	global_load_dwordx4 v[82:85], v[68:69], off nt
	v_mad_i64_i32 v[68:69], s[6:7], v67, s63, v[122:123]
	v_mad_i64_i32 v[86:87], s[6:7], v66, s63, v[122:123]
	v_mad_i64_i32 v[90:91], s[6:7], v65, s63, v[122:123]
	v_mad_i64_i32 v[64:65], s[6:7], v64, s63, v[122:123]
	global_load_dwordx4 v[66:69], v[68:69], off nt
	s_nop 0
	global_load_dwordx4 v[86:89], v[86:87], off nt
	s_nop 0
	global_load_dwordx4 v[90:93], v[90:91], off nt
	s_nop 0
	global_load_dwordx4 v[94:97], v[64:65], off nt
	v_mad_i64_i32 v[64:65], s[6:7], v63, s63, v[122:123]
	v_mad_i64_i32 v[98:99], s[6:7], v62, s63, v[122:123]
	v_mad_i64_i32 v[102:103], s[6:7], v25, s63, v[122:123]
	v_mad_i64_i32 v[106:107], s[6:7], v27, s63, v[122:123]
	v_mad_i64_i32 v[110:111], s[6:7], v29, s63, v[122:123]
	v_mad_i64_i32 v[114:115], s[6:7], v23, s63, v[122:123]
	v_mad_i64_i32 v[118:119], s[6:7], v21, s63, v[122:123]
	global_load_dwordx4 v[62:65], v[64:65], off nt
	s_nop 0
	global_load_dwordx4 v[98:101], v[98:99], off nt
	v_mad_i64_i32 v[122:123], s[6:7], v19, s63, v[122:123]
	global_load_dwordx4 v[102:105], v[102:103], off nt
	s_nop 0
	global_load_dwordx4 v[106:109], v[106:107], off nt
	s_nop 0
	global_load_dwordx4 v[110:113], v[110:111], off nt
	s_nop 0
	global_load_dwordx4 v[114:117], v[114:115], off nt
	s_nop 0
	global_load_dwordx4 v[118:121], v[118:119], off nt
	s_ashr_i32 s6, s5, 2
	global_load_dwordx4 v[122:125], v[122:123], off nt
	s_and_b32 s10, s61, 0x3000
	s_ashr_i32 s5, s4, 31
	s_ashr_i32 s7, s6, 31
	s_lshl_b32 s10, s10, 1
	s_add_u32 s10, s30, s10
	s_addc_u32 s11, s31, 0
	s_lshl_b64 s[6:7], s[6:7], 21
	s_lshl_b64 s[4:5], s[4:5], 15
	s_add_u32 s6, s10, s6
	s_addc_u32 s7, s11, s7
	s_add_u32 s4, s6, s4
	v_add_u32_e32 v29, 0x400, v32
	s_addc_u32 s5, s7, s5
	v_mov_b32_e32 v19, v1
	v_mov_b32_e32 v21, v1
	v_mov_b32_e32 v23, v1
	v_mov_b32_e32 v25, v1
	v_mov_b32_e32 v27, v1
	s_waitcnt vmcnt(15)
	ds_write2_b32 v33, v70, v71 offset1:1
	ds_write2_b32 v33, v72, v73 offset0:2 offset1:3
	s_waitcnt vmcnt(14)
	ds_write2_b32 v34, v74, v75 offset1:1
	ds_write2_b32 v35, v76, v77 offset1:1
	s_waitcnt vmcnt(13)
	ds_write2_b32 v36, v78, v79 offset1:1
	ds_write2_b32 v37, v80, v81 offset1:1
	s_waitcnt vmcnt(12)
	ds_write2_b32 v38, v82, v83 offset1:1
	ds_write2_b32 v39, v84, v85 offset1:1
	s_waitcnt vmcnt(11)
	ds_write2_b32 v40, v66, v67 offset1:1
	ds_write2_b32 v41, v68, v69 offset1:1
	s_waitcnt vmcnt(10)
	ds_write2_b32 v42, v86, v87 offset1:1
	ds_write2_b32 v43, v88, v89 offset1:1
	s_waitcnt vmcnt(9)
	ds_write2_b32 v44, v90, v91 offset1:1
	ds_write2_b32 v45, v92, v93 offset1:1
	s_waitcnt vmcnt(8)
	ds_write2_b32 v46, v94, v95 offset1:1
	ds_write2_b32 v47, v96, v97 offset1:1
	s_waitcnt vmcnt(7)
	ds_write2_b32 v48, v62, v63 offset1:1
	ds_write2_b32 v49, v64, v65 offset1:1
	s_waitcnt vmcnt(6)
	ds_write2_b32 v50, v98, v99 offset1:1
	ds_write2_b32 v51, v100, v101 offset1:1
	s_waitcnt vmcnt(5)
	ds_write2_b32 v52, v102, v103 offset1:1
	ds_write2_b32 v53, v104, v105 offset1:1
	s_waitcnt vmcnt(4)
	ds_write2_b32 v54, v106, v107 offset1:1
	ds_write2_b32 v55, v108, v109 offset1:1
	s_waitcnt vmcnt(3)
	ds_write2_b32 v56, v110, v111 offset1:1
	ds_write2_b32 v57, v112, v113 offset1:1
	s_waitcnt vmcnt(2)
	ds_write2_b32 v58, v114, v115 offset1:1
	ds_write2_b32 v59, v116, v117 offset1:1
	s_waitcnt vmcnt(1)
	ds_write2_b32 v60, v118, v119 offset1:1
	ds_write2_b32 v61, v120, v121 offset1:1
	s_waitcnt vmcnt(0)
	ds_write2_b32 v15, v122, v123 offset1:1
	ds_write2_b32 v17, v124, v125 offset1:1
	s_waitcnt lgkmcnt(0)
	ds_read2_b32 v[62:63], v32 offset1:65
	s_waitcnt lgkmcnt(0)
	v_cvt_pk_bf16_f32 v62, v62, v63
	ds_read2_b32 v[64:65], v32 offset0:130 offset1:195
	v_mov_b32_e32 v15, v1
	s_waitcnt lgkmcnt(0)
; #define LAS __attribute__((address_space(3)))
; __device__ __forceinline__ unsigned cvt_pk_bf16(float lo, float hi) { unsigned r; asm volatile("v_cvt_pk_bf16_f32 %0, %1, %2" : "=v"(r) : "v"(lo), "v"(hi)); return r; }
; #define LDS_WAIT() asm volatile("s_waitcnt lgkmcnt(0)" ::: "memory")
; __device__ __forceinline__ void transpose_item(const float* W, int N, bf16_t* WT, int nkt, int k0, int n0, int r0, int kbd, LAS float* scr, int lane) {
;     ...
;     LDS_WAIT();
;     const int c = lane & 7;
; #pragma unroll
;     for (int j = 0; j < 8; ++j) { const int n = (lane >> 3) + 8 * j; const LAS float* s = scr + (8 * c) * 65 + n;
;         u32x4 o; o.x = cvt_pk_bf16(s[0], s[65]); o.y = cvt_pk_bf16(s[2 * 65], s[3 * 65]); o.z = cvt_pk_bf16(s[4 * 65], s[5 * 65]); o.w = cvt_pk_bf16(s[6 * 65], s[7 * 65]);
;         *(u32x4*)(WT + dst_off + (size_t)n * 64 + 8 * c) = o; }
;     LDS_WAIT();
	v_cvt_pk_bf16_f32 v63, v64, v65
	ds_read2_b32 v[64:65], v29 offset0:4 offset1:69
	v_lshl_add_u64 v[68:69], s[4:5], 0, v[0:1]
	s_waitcnt lgkmcnt(0)
	v_cvt_pk_bf16_f32 v64, v64, v65
	ds_read2_b32 v[66:67], v29 offset0:134 offset1:199
	s_waitcnt lgkmcnt(0)
	v_cvt_pk_bf16_f32 v65, v66, v67
	v_lshl_add_u64 v[70:71], v[68:69], 0, v[14:15]
	ds_read2_b32 v[66:67], v32 offset0:8 offset1:73
	global_store_dwordx4 v[70:71], v[62:65], off
	v_mov_b32_e32 v17, v1
	v_lshl_add_u64 v[70:71], v[68:69], 0, v[16:17]
	s_waitcnt lgkmcnt(0)
	v_cvt_pk_bf16_f32 v62, v66, v67
	ds_read2_b32 v[64:65], v32 offset0:138 offset1:203
	s_waitcnt lgkmcnt(0)
	v_cvt_pk_bf16_f32 v63, v64, v65
	ds_read2_b32 v[64:65], v29 offset0:12 offset1:77
	s_waitcnt lgkmcnt(0)
	v_cvt_pk_bf16_f32 v64, v64, v65
	ds_read2_b32 v[66:67], v29 offset0:142 offset1:207
	s_waitcnt lgkmcnt(0)
	v_cvt_pk_bf16_f32 v65, v66, v67
	ds_read2_b32 v[66:67], v32 offset0:16 offset1:81
	global_store_dwordx4 v[70:71], v[62:65], off
	v_lshl_add_u64 v[70:71], v[68:69], 0, v[18:19]
	s_waitcnt lgkmcnt(0)
	v_cvt_pk_bf16_f32 v62, v66, v67
	ds_read2_b32 v[64:65], v32 offset0:146 offset1:211
	s_waitcnt lgkmcnt(0)
	v_cvt_pk_bf16_f32 v63, v64, v65
	ds_read2_b32 v[64:65], v29 offset0:20 offset1:85
	s_waitcnt lgkmcnt(0)
	v_cvt_pk_bf16_f32 v64, v64, v65
	ds_read2_b32 v[66:67], v29 offset0:150 offset1:215
	s_waitcnt lgkmcnt(0)
	v_cvt_pk_bf16_f32 v65, v66, v67
	ds_read2_b32 v[66:67], v32 offset0:24 offset1:89
	global_store_dwordx4 v[70:71], v[62:65], off
	v_lshl_add_u64 v[70:71], v[68:69], 0, v[20:21]
	s_waitcnt lgkmcnt(0)
	v_cvt_pk_bf16_f32 v62, v66, v67
	ds_read2_b32 v[64:65], v32 offset0:154 offset1:219
	s_waitcnt lgkmcnt(0)
	v_cvt_pk_bf16_f32 v63, v64, v65
	ds_read2_b32 v[64:65], v29 offset0:28 offset1:93
	s_waitcnt lgkmcnt(0)
	v_cvt_pk_bf16_f32 v64, v64, v65
	ds_read2_b32 v[66:67], v29 offset0:158 offset1:223
	s_waitcnt lgkmcnt(0)
	v_cvt_pk_bf16_f32 v65, v66, v67
	ds_read2_b32 v[66:67], v32 offset0:32 offset1:97
	global_store_dwordx4 v[70:71], v[62:65], off
	v_lshl_add_u64 v[70:71], v[68:69], 0, v[22:23]
	s_waitcnt lgkmcnt(0)
	v_cvt_pk_bf16_f32 v62, v66, v67
	ds_read2_b32 v[64:65], v32 offset0:162 offset1:227
	s_waitcnt lgkmcnt(0)
	v_cvt_pk_bf16_f32 v63, v64, v65
	ds_read2_b32 v[64:65], v29 offset0:36 offset1:101
	s_waitcnt lgkmcnt(0)
	v_cvt_pk_bf16_f32 v64, v64, v65
	ds_read2_b32 v[66:67], v29 offset0:166 offset1:231
	s_waitcnt lgkmcnt(0)
	v_cvt_pk_bf16_f32 v65, v66, v67
	ds_read2_b32 v[66:67], v32 offset0:40 offset1:105
	global_store_dwordx4 v[70:71], v[62:65], off
	v_lshl_add_u64 v[70:71], v[68:69], 0, v[24:25]
	s_waitcnt lgkmcnt(0)
	v_cvt_pk_bf16_f32 v62, v66, v67
	ds_read2_b32 v[64:65], v32 offset0:170 offset1:235
	s_waitcnt lgkmcnt(0)
	v_cvt_pk_bf16_f32 v63, v64, v65
	ds_read2_b32 v[64:65], v29 offset0:44 offset1:109
	s_waitcnt lgkmcnt(0)
	v_cvt_pk_bf16_f32 v64, v64, v65
	ds_read2_b32 v[66:67], v29 offset0:174 offset1:239
	s_waitcnt lgkmcnt(0)
	v_cvt_pk_bf16_f32 v65, v66, v67
	ds_read2_b32 v[66:67], v32 offset0:48 offset1:113
	global_store_dwordx4 v[70:71], v[62:65], off
	v_lshl_add_u64 v[70:71], v[68:69], 0, v[26:27]
	s_waitcnt lgkmcnt(0)
	v_cvt_pk_bf16_f32 v62, v66, v67
	ds_read2_b32 v[64:65], v32 offset0:178 offset1:243
	s_waitcnt lgkmcnt(0)
	v_cvt_pk_bf16_f32 v63, v64, v65
	ds_read2_b32 v[64:65], v29 offset0:52 offset1:117
	s_waitcnt lgkmcnt(0)
	v_cvt_pk_bf16_f32 v64, v64, v65
	ds_read2_b32 v[66:67], v29 offset0:182 offset1:247
	s_waitcnt lgkmcnt(0)
	v_cvt_pk_bf16_f32 v65, v66, v67
	ds_read2_b32 v[66:67], v32 offset0:56 offset1:121
	global_store_dwordx4 v[70:71], v[62:65], off
	s_waitcnt lgkmcnt(0)
	s_nop 0
	v_cvt_pk_bf16_f32 v62, v66, v67
	ds_read2_b32 v[64:65], v32 offset0:186 offset1:251
	s_waitcnt lgkmcnt(0)
	v_cvt_pk_bf16_f32 v63, v64, v65
	ds_read2_b32 v[64:65], v29 offset0:60 offset1:125
	s_waitcnt lgkmcnt(0)
	v_cvt_pk_bf16_f32 v64, v64, v65
	ds_read2_b32 v[66:67], v29 offset0:190 offset1:255
	v_mov_b32_e32 v29, v1
	s_waitcnt lgkmcnt(0)
	v_cvt_pk_bf16_f32 v65, v66, v67
	v_lshl_add_u64 v[66:67], v[68:69], 0, v[28:29]
	global_store_dwordx4 v[66:67], v[62:65], off
	s_waitcnt lgkmcnt(0)
	s_branch .LBB0_22

; __device__ __forceinline__ void phase0(const Params& p, LAS unsigned char* lds, int gw, int NGW, int wave, int lane, int G) {
;     ...
;       for (int row = gw; row < MT; row += NGW) {
;           const f32x4* xr = (const f32x4*)(x + (size_t)row * DM) + lane; f32x4 v[16]; float ss = 0.f;
;           const f32x4* gp = (const f32x4*)g + lane; asm volatile("" : "+v"(gp), "+v"(xr));
; #pragma unroll
;           for (int j = 0; j < 16; ++j) { v[j] = xr[64 * j]; ss += (v[j][0] * v[j][0] + v[j][1] * v[j][1]) + (v[j][2] * v[j][2] + v[j][3] * v[j][3]); }
;           const float rs = rsqrtf(wave_sum(ss) * (1.f / DM) + EPSN);
.LBB0_29:
	v_cmp_lt_i32_e32 vcc, v83, v82
	v_lshl_add_u64 v[2:3], s[58:59], 0, v[66:67]
	v_mov_b64_e32 v[0:1], v[70:71]
	v_cndmask_b32_e32 v6, v79, v83, vcc
	v_cmp_lt_i32_e32 vcc, v84, v82
	v_mov_b64_e32 v[72:73], v[64:65]
	flat_load_dwordx4 v[60:63], v[0:1] nt
	flat_load_dwordx4 v[56:59], v[0:1] offset:1024 nt
	flat_load_dwordx4 v[48:51], v[0:1] offset:2048 nt
	flat_load_dwordx4 v[40:43], v[0:1] offset:3072 nt
	v_cndmask_b32_e32 v7, v79, v84, vcc
	v_cmp_lt_i32_e32 vcc, v85, v82
	v_lshl_add_u64 v[4:5], s[58:59], 0, v[68:69]
	v_lshlrev_b32_e32 v137, 2, v6
	v_cndmask_b32_e32 v8, v79, v85, vcc
	v_cmp_lt_i32_e32 vcc, v86, v82
	v_lshlrev_b32_e32 v138, 2, v7
	v_lshlrev_b32_e32 v139, 2, v8
	v_cndmask_b32_e32 v9, v79, v86, vcc
	v_cmp_lt_i32_e32 vcc, v87, v82
	v_lshlrev_b32_e32 v140, 2, v9
	v_mov_b32_e32 v135, 0
	v_cndmask_b32_e32 v10, v79, v87, vcc
	v_cmp_lt_i32_e32 vcc, v88, v82
	v_lshlrev_b32_e32 v141, 2, v10
	v_mov_b32_e32 v136, 0
	v_cndmask_b32_e32 v11, v79, v88, vcc
	v_add_co_u32_e32 v80, vcc, s15, v2
	v_lshlrev_b32_e32 v142, 2, v11
	s_nop 0
	v_addc_co_u32_e32 v81, vcc, 0, v3, vcc
	v_add_co_u32_e32 v74, vcc, s17, v2
	s_add_i32 s30, s30, s60
	s_nop 0
	v_addc_co_u32_e32 v75, vcc, 0, v3, vcc
	v_add_co_u32_e32 v76, vcc, s16, v4
	v_lshl_add_u64 v[66:67], v[66:67], 0, s[4:5]
	s_nop 0
	v_addc_co_u32_e32 v77, vcc, 0, v5, vcc
	v_add_co_u32_e32 v2, vcc, s3, v0
	v_lshl_add_u64 v[68:69], v[68:69], 0, s[6:7]
	s_nop 0
	v_addc_co_u32_e32 v3, vcc, 0, v1, vcc
	v_add_co_u32_e32 v4, vcc, s8, v0
	v_lshl_add_u64 v[70:71], v[70:71], 0, s[10:11]
	s_nop 0
	v_addc_co_u32_e32 v5, vcc, 0, v1, vcc
	v_add_co_u32_e32 v6, vcc, s9, v0
	s_cmpk_gt_i32 s30, 0x1fff
	s_nop 0
	v_addc_co_u32_e32 v7, vcc, 0, v1, vcc
	flat_load_dwordx4 v[90:93], v[72:73]
	flat_load_dwordx4 v[52:55], v[2:3] nt
	flat_load_dwordx4 v[32:35], v[2:3] offset:3072 nt
	flat_load_dwordx4 v[20:23], v[4:5] offset:2048 nt
	flat_load_dwordx4 v[8:11], v[6:7] offset:1024 nt
	flat_load_dwordx4 v[36:39], v[2:3] offset:2048 nt
	flat_load_dwordx4 v[44:47], v[2:3] offset:1024 nt
	flat_load_dwordx4 v[24:27], v[4:5] offset:1024 nt
	flat_load_dwordx4 v[28:31], v[4:5] nt
	flat_load_dwordx4 v[12:15], v[6:7] nt
	flat_load_dwordx4 v[16:19], v[4:5] offset:3072 nt
	s_nop 0
	flat_load_dwordx4 v[0:3], v[6:7] offset:3072 nt
	s_nop 0
	flat_load_dwordx4 v[4:7], v[6:7] offset:2048 nt
	s_waitcnt vmcnt(0) lgkmcnt(0)
	v_pk_mul_f32 v[94:95], v[62:63], v[62:63]
	v_pk_mul_f32 v[96:97], v[60:61], v[60:61]
	v_pk_mul_f32 v[98:99], v[58:59], v[58:59]
	v_pk_mul_f32 v[100:101], v[56:57], v[56:57]
	v_pk_mov_b32 v[104:105], v[96:97], v[94:95] op_sel:[1,0]
	v_mov_b32_e32 v97, v95
	v_pk_mov_b32 v[94:95], v[100:101], v[98:99] op_sel:[1,0]
	v_mov_b32_e32 v101, v99
	v_mul_f32_e32 v78, v49, v49
	v_mul_f32_e32 v102, v51, v51
	v_pk_add_f32 v[96:97], v[104:105], v[96:97]
	v_pk_add_f32 v[94:95], v[94:95], v[100:101]
	v_mul_f32_e32 v123, v42, v42
	v_mul_f32_e32 v125, v43, v43
	v_mul_f32_e32 v143, v40, v40
	v_mul_f32_e32 v144, v41, v41
	v_pk_fma_f32 v[120:121], v[48:49], v[48:49], v[78:79] op_sel_hi:[1,1,0]
	v_pk_fma_f32 v[102:103], v[50:51], v[50:51], v[102:103] op_sel_hi:[1,1,0]
	v_pk_add_f32 v[96:97], v[96:97], v[96:97] op_sel:[0,1] op_sel_hi:[1,0]
	v_pk_add_f32 v[94:95], v[94:95], v[94:95] op_sel:[0,1] op_sel_hi:[1,0]
	v_mov_b32_e32 v121, v123
	v_mov_b32_e32 v103, v125
	v_mov_b32_e32 v97, v143
	v_mov_b32_e32 v95, v144
	v_pk_add_f32 v[102:103], v[120:121], v[102:103]
	v_pk_add_f32 v[94:95], v[96:97], v[94:95]
	v_pk_mul_f32 v[98:99], v[54:55], v[54:55]
	v_pk_mul_f32 v[106:107], v[52:53], v[52:53]
	v_pk_mul_f32 v[108:109], v[34:35], v[34:35]
	v_pk_mov_b32 v[100:101], v[106:107], v[98:99] op_sel:[1,0]
	v_mov_b32_e32 v107, v99
	v_pk_mul_f32 v[110:111], v[32:33], v[32:33]
	v_pk_mul_f32 v[112:113], v[22:23], v[22:23]
	v_pk_mul_f32 v[114:115], v[20:21], v[20:21]
	v_pk_mul_f32 v[116:117], v[10:11], v[10:11]
	v_pk_mul_f32 v[118:119], v[8:9], v[8:9]
	v_mul_f32_e32 v78, v45, v45
	v_mul_f32_e32 v122, v47, v47
	v_pk_add_f32 v[100:101], v[100:101], v[106:107]
	v_pk_add_f32 v[94:95], v[94:95], v[102:103]
	v_mul_f32_e32 v145, v38, v38
	v_mul_f32_e32 v146, v39, v39
	v_mul_f32_e32 v153, v36, v36
	v_mul_f32_e32 v154, v37, v37
	v_pk_mov_b32 v[98:99], v[110:111], v[108:109] op_sel:[1,0]
	v_mov_b32_e32 v111, v109
	v_pk_mov_b32 v[104:105], v[114:115], v[112:113] op_sel:[1,0]
	v_mov_b32_e32 v115, v113
	v_pk_mov_b32 v[108:109], v[118:119], v[116:117] op_sel:[1,0]
	v_mov_b32_e32 v119, v117
	v_pk_fma_f32 v[112:113], v[44:45], v[44:45], v[78:79] op_sel_hi:[1,1,0]
	v_pk_fma_f32 v[116:117], v[46:47], v[46:47], v[122:123] op_sel_hi:[1,1,0]
	v_pk_add_f32 v[100:101], v[100:101], v[100:101] op_sel:[0,1] op_sel_hi:[1,0]
	v_pk_add_f32 v[94:95], v[94:95], v[94:95] op_sel:[0,1] op_sel_hi:[1,0]
	v_mov_b32_e32 v113, v145
	v_mov_b32_e32 v117, v146
	v_mov_b32_e32 v101, v154
	v_mov_b32_e32 v95, v153
	v_pk_add_f32 v[106:107], v[108:109], v[118:119]
	v_pk_add_f32 v[108:109], v[112:113], v[116:117]
	v_pk_add_f32 v[94:95], v[94:95], v[100:101]
	v_mul_f32_e32 v124, v29, v29
	v_mul_f32_e32 v126, v31, v31
	v_pk_add_f32 v[98:99], v[98:99], v[110:111]
	v_pk_add_f32 v[94:95], v[94:95], v[108:109]
	v_mul_f32_e32 v147, v26, v26
	v_mul_f32_e32 v148, v27, v27
	v_mul_f32_e32 v155, v24, v24
	v_mul_f32_e32 v156, v25, v25
	v_pk_fma_f32 v[122:123], v[28:29], v[28:29], v[124:125] op_sel_hi:[1,1,0]
	v_pk_fma_f32 v[124:125], v[30:31], v[30:31], v[126:127] op_sel_hi:[1,1,0]
	v_pk_add_f32 v[98:99], v[98:99], v[98:99] op_sel:[0,1] op_sel_hi:[1,0]
	v_pk_add_f32 v[94:95], v[94:95], v[94:95] op_sel:[0,1] op_sel_hi:[1,0]
	v_mov_b32_e32 v123, v147
	v_mov_b32_e32 v125, v148
	v_mov_b32_e32 v99, v156
	v_mov_b32_e32 v95, v155
; __device__ __forceinline__ unsigned cvt_pk_bf16(float lo, float hi) { unsigned r; asm volatile("v_cvt_pk_bf16_f32 %0, %1, %2" : "=v"(r) : "v"(lo), "v"(hi)); return r; }
; __device__ __forceinline__ void phase0(const Params& p, LAS unsigned char* lds, int gw, int NGW, int wave, int lane, int G) {
;     ...
;           for (int j = 0; j < 16; ++j) { v[j] = xr[64 * j]; ss += (v[j][0] * v[j][0] + v[j][1] * v[j][1]) + (v[j][2] * v[j][2] + v[j][3] * v[j][3]); }
;           const float rs = rsqrtf(wave_sum(ss) * (1.f / DM) + EPSN);
;           u32x2* o = (u32x2*)(A0 + (size_t)row * DM) + lane; unsigned* o8 = (unsigned*)(ws + WS_SC + (size_t)row * DM) + lane;
; #pragma unroll
;           for (int j = 0; j < 16; ++j) { const f32x4 gg = gp[64 * j]; const f32x4 a = v[j] * rs * gg; u32x2 w; w.x = cvt_pk_bf16(a[0], a[1]); w.y = cvt_pk_bf16(a[2], a[3]); o[64 * j] = w;
;               int q = __builtin_amdgcn_cvt_pk_fp8_f32(a[0] * 16.f, a[1] * 16.f, 0, false); q = __builtin_amdgcn_cvt_pk_fp8_f32(a[2] * 16.f, a[3] * 16.f, q, true); o8[64 * j] = (unsigned)q; }
	v_pk_add_f32 v[110:111], v[122:123], v[124:125]
	v_pk_add_f32 v[94:95], v[94:95], v[98:99]
	v_mul_f32_e32 v128, v17, v17
	v_mul_f32_e32 v130, v19, v19
	v_pk_add_f32 v[104:105], v[104:105], v[114:115]
	v_pk_add_f32 v[94:95], v[94:95], v[110:111]
	v_mul_f32_e32 v149, v14, v14
	v_mul_f32_e32 v150, v15, v15
	v_mul_f32_e32 v157, v12, v12
	v_mul_f32_e32 v158, v13, v13
	v_pk_fma_f32 v[126:127], v[16:17], v[16:17], v[128:129] op_sel_hi:[1,1,0]
	v_pk_fma_f32 v[128:129], v[18:19], v[18:19], v[130:131] op_sel_hi:[1,1,0]
	v_pk_add_f32 v[104:105], v[104:105], v[104:105] op_sel:[0,1] op_sel_hi:[1,0]
	v_pk_add_f32 v[94:95], v[94:95], v[94:95] op_sel:[0,1] op_sel_hi:[1,0]
	v_mov_b32_e32 v127, v149
	v_mov_b32_e32 v129, v150
	v_mov_b32_e32 v105, v158
	v_mov_b32_e32 v95, v157
	v_pk_add_f32 v[112:113], v[126:127], v[128:129]
	v_pk_add_f32 v[94:95], v[94:95], v[104:105]
	v_mul_f32_e32 v132, v5, v5
	v_mul_f32_e32 v134, v7, v7
	v_pk_add_f32 v[94:95], v[94:95], v[112:113]
	v_mul_f32_e32 v151, v2, v2
	v_mul_f32_e32 v152, v3, v3
	v_mul_f32_e32 v159, v0, v0
	v_mul_f32_e32 v160, v1, v1
	v_pk_fma_f32 v[130:131], v[4:5], v[4:5], v[132:133] op_sel_hi:[1,1,0]
	v_pk_fma_f32 v[132:133], v[6:7], v[6:7], v[134:135] op_sel_hi:[1,1,0]
	v_pk_add_f32 v[106:107], v[106:107], v[106:107] op_sel:[0,1] op_sel_hi:[1,0]
	v_pk_add_f32 v[94:95], v[94:95], v[94:95] op_sel:[0,1] op_sel_hi:[1,0]
	v_mov_b32_e32 v131, v151
	v_mov_b32_e32 v133, v152
	v_mov_b32_e32 v107, v160
	v_mov_b32_e32 v95, v159
	v_pk_add_f32 v[114:115], v[130:131], v[132:133]
	v_pk_add_f32 v[94:95], v[94:95], v[106:107]
	s_nop 0
	v_pk_add_f32 v[94:95], v[94:95], v[114:115]
	s_nop 0
	v_add_f32_e32 v78, v94, v95
	ds_bpermute_b32 v94, v137, v78
	s_waitcnt lgkmcnt(0)
	v_add_f32_e32 v78, v78, v94
	ds_bpermute_b32 v94, v138, v78
	s_waitcnt lgkmcnt(0)
	v_add_f32_e32 v78, v78, v94
	ds_bpermute_b32 v94, v139, v78
	s_waitcnt lgkmcnt(0)
	v_add_f32_e32 v78, v78, v94
	ds_bpermute_b32 v94, v140, v78
	s_waitcnt lgkmcnt(0)
	v_add_f32_e32 v78, v78, v94
	ds_bpermute_b32 v94, v141, v78
	s_waitcnt lgkmcnt(0)
	v_add_f32_e32 v78, v78, v94
	ds_bpermute_b32 v94, v142, v78
	s_waitcnt lgkmcnt(0)
	v_add_f32_e32 v78, v78, v94
	v_fmamk_f32 v78, v78, 0x39800000, v89
	v_mul_f32_e32 v94, 0x4b800000, v78
	v_cmp_gt_f32_e32 vcc, s14, v78
	s_nop 1
	v_cndmask_b32_e32 v78, v78, v94, vcc
	v_rsq_f32_e32 v78, v78
	s_nop 0
	v_mul_f32_e32 v94, 0x45800000, v78
	v_cndmask_b32_e32 v78, v78, v94, vcc
	v_pk_mul_f32 v[60:61], v[60:61], v[78:79] op_sel_hi:[1,0]
	v_pk_mul_f32 v[96:97], v[58:59], v[78:79] op_sel_hi:[1,0]
	v_pk_mul_f32 v[58:59], v[90:91], v[60:61]
	v_pk_mul_f32 v[62:63], v[62:63], v[78:79] op_sel_hi:[1,0]
	v_cvt_pk_bf16_f32 v60, v58, v59
	v_mul_f32_e32 v58, 0x41800000, v58
	v_mul_f32_e32 v59, 0x41800000, v59
	v_cvt_pk_fp8_f32 v135, v58, v59
	v_pk_mul_f32 v[94:95], v[56:57], v[78:79] op_sel_hi:[1,0]
	v_pk_mul_f32 v[56:57], v[92:93], v[62:63]
	v_pk_mul_f32 v[48:49], v[48:49], v[78:79] op_sel_hi:[1,0]
	v_cvt_pk_bf16_f32 v61, v56, v57
	v_mul_f32_e32 v56, 0x41800000, v56
	v_mul_f32_e32 v57, 0x41800000, v57
	v_cvt_pk_fp8_f32 v135, v56, v57 op_sel:[0,0,1]
	global_store_dwordx2 v[74:75], v[60:61], off offset:-4096
	v_pk_mul_f32 v[50:51], v[50:51], v[78:79] op_sel_hi:[1,0]
	v_pk_mul_f32 v[40:41], v[40:41], v[78:79] op_sel_hi:[1,0]
	global_store_dword v[76:77], v135, off
	flat_load_dwordx4 v[56:59], v[72:73] offset:1024
	v_pk_mul_f32 v[42:43], v[42:43], v[78:79] op_sel_hi:[1,0]
	v_pk_mul_f32 v[44:45], v[44:45], v[78:79] op_sel_hi:[1,0]
	v_pk_mul_f32 v[46:47], v[46:47], v[78:79] op_sel_hi:[1,0]
	v_pk_mul_f32 v[36:37], v[36:37], v[78:79] op_sel_hi:[1,0]
	v_pk_mul_f32 v[38:39], v[38:39], v[78:79] op_sel_hi:[1,0]
	v_pk_mul_f32 v[32:33], v[32:33], v[78:79] op_sel_hi:[1,0]
	v_pk_mul_f32 v[34:35], v[34:35], v[78:79] op_sel_hi:[1,0]
	v_pk_mul_f32 v[28:29], v[28:29], v[78:79] op_sel_hi:[1,0]
	v_pk_mul_f32 v[30:31], v[30:31], v[78:79] op_sel_hi:[1,0]
	v_pk_mul_f32 v[24:25], v[24:25], v[78:79] op_sel_hi:[1,0]
	v_pk_mul_f32 v[26:27], v[26:27], v[78:79] op_sel_hi:[1,0]
	v_pk_mul_f32 v[20:21], v[20:21], v[78:79] op_sel_hi:[1,0]
	v_pk_mul_f32 v[22:23], v[22:23], v[78:79] op_sel_hi:[1,0]
	v_pk_mul_f32 v[16:17], v[16:17], v[78:79] op_sel_hi:[1,0]
	v_pk_mul_f32 v[18:19], v[18:19], v[78:79] op_sel_hi:[1,0]
	v_pk_mul_f32 v[12:13], v[12:13], v[78:79] op_sel_hi:[1,0]
	v_pk_mul_f32 v[14:15], v[14:15], v[78:79] op_sel_hi:[1,0]
	v_pk_mul_f32 v[8:9], v[8:9], v[78:79] op_sel_hi:[1,0]
	v_pk_mul_f32 v[10:11], v[10:11], v[78:79] op_sel_hi:[1,0]
	v_pk_mul_f32 v[4:5], v[4:5], v[78:79] op_sel_hi:[1,0]
	v_pk_mul_f32 v[6:7], v[6:7], v[78:79] op_sel_hi:[1,0]
	v_pk_mul_f32 v[0:1], v[0:1], v[78:79] op_sel_hi:[1,0]
	v_pk_mul_f32 v[2:3], v[2:3], v[78:79] op_sel_hi:[1,0]
	s_waitcnt vmcnt(0) lgkmcnt(0)
	v_pk_mul_f32 v[56:57], v[56:57], v[94:95]
	s_nop 0
	v_cvt_pk_bf16_f32 v60, v56, v57
	v_mul_f32_e32 v56, 0x41800000, v56
	v_mul_f32_e32 v57, 0x41800000, v57
	v_cvt_pk_fp8_f32 v136, v56, v57
	v_pk_mul_f32 v[58:59], v[58:59], v[96:97]
	s_nop 0
	v_cvt_pk_bf16_f32 v61, v58, v59
	v_mul_f32_e32 v58, 0x41800000, v58
	v_mul_f32_e32 v59, 0x41800000, v59
	v_cvt_pk_fp8_f32 v136, v58, v59 op_sel:[0,0,1]
	global_store_dwordx2 v[80:81], v[60:61], off offset:512
	v_mov_b32_e32 v60, 0
	global_store_dword v[76:77], v136, off offset:256
	flat_load_dwordx4 v[56:59], v[72:73] offset:2048
	s_waitcnt vmcnt(0) lgkmcnt(0)
; __device__ __forceinline__ unsigned cvt_pk_bf16(float lo, float hi) { unsigned r; asm volatile("v_cvt_pk_bf16_f32 %0, %1, %2" : "=v"(r) : "v"(lo), "v"(hi)); return r; }
; __device__ __forceinline__ void phase0(const Params& p, LAS unsigned char* lds, int gw, int NGW, int wave, int lane, int G) {
;     ...
;           for (int j = 0; j < 16; ++j) { const f32x4 gg = gp[64 * j]; const f32x4 a = v[j] * rs * gg; u32x2 w; w.x = cvt_pk_bf16(a[0], a[1]); w.y = cvt_pk_bf16(a[2], a[3]); o[64 * j] = w;
;               int q = __builtin_amdgcn_cvt_pk_fp8_f32(a[0] * 16.f, a[1] * 16.f, 0, false); q = __builtin_amdgcn_cvt_pk_fp8_f32(a[2] * 16.f, a[3] * 16.f, q, true); o8[64 * j] = (unsigned)q; }
	v_pk_mul_f32 v[48:49], v[48:49], v[56:57]
	s_nop 0
	v_cvt_pk_bf16_f32 v56, v48, v49
	v_mul_f32_e32 v48, 0x41800000, v48
	v_mul_f32_e32 v49, 0x41800000, v49
	v_cvt_pk_fp8_f32 v60, v48, v49
	v_pk_mul_f32 v[50:51], v[50:51], v[58:59]
	v_mov_b32_e32 v58, 0
	v_cvt_pk_bf16_f32 v57, v50, v51
	v_mul_f32_e32 v50, 0x41800000, v50
	v_mul_f32_e32 v51, 0x41800000, v51
	v_cvt_pk_fp8_f32 v60, v50, v51 op_sel:[0,0,1]
	global_store_dwordx2 v[80:81], v[56:57], off offset:1024
	v_add_co_u32_e32 v56, vcc, s3, v72
	global_store_dword v[76:77], v60, off offset:512
	flat_load_dwordx4 v[48:51], v[72:73] offset:3072
	v_addc_co_u32_e32 v57, vcc, 0, v73, vcc
	s_waitcnt vmcnt(0) lgkmcnt(0)
	v_pk_mul_f32 v[40:41], v[40:41], v[48:49]
	s_nop 0
	v_cvt_pk_bf16_f32 v48, v40, v41
	v_mul_f32_e32 v40, 0x41800000, v40
	v_mul_f32_e32 v41, 0x41800000, v41
	v_cvt_pk_fp8_f32 v58, v40, v41
	v_pk_mul_f32 v[42:43], v[42:43], v[50:51]
	v_pk_mul_f32 v[50:51], v[54:55], v[78:79] op_sel_hi:[1,0]
	v_cvt_pk_bf16_f32 v49, v42, v43
	v_mul_f32_e32 v42, 0x41800000, v42
	v_mul_f32_e32 v43, 0x41800000, v43
	v_cvt_pk_fp8_f32 v58, v42, v43 op_sel:[0,0,1]
	global_store_dwordx2 v[80:81], v[48:49], off offset:1536
	v_pk_mul_f32 v[48:49], v[52:53], v[78:79] op_sel_hi:[1,0]
	global_store_dword v[76:77], v58, off offset:768
	flat_load_dwordx4 v[40:43], v[56:57]
	v_mov_b32_e32 v58, 0
	s_waitcnt vmcnt(0) lgkmcnt(0)
	v_pk_mul_f32 v[40:41], v[48:49], v[40:41]
	s_nop 0
	v_cvt_pk_bf16_f32 v48, v40, v41
	v_mul_f32_e32 v40, 0x41800000, v40
	v_mul_f32_e32 v41, 0x41800000, v41
	v_cvt_pk_fp8_f32 v58, v40, v41
	v_pk_mul_f32 v[42:43], v[50:51], v[42:43]
	s_nop 0
	v_cvt_pk_bf16_f32 v49, v42, v43
	v_mul_f32_e32 v42, 0x41800000, v42
	v_mul_f32_e32 v43, 0x41800000, v43
	v_cvt_pk_fp8_f32 v58, v42, v43 op_sel:[0,0,1]
	global_store_dwordx2 v[80:81], v[48:49], off offset:2048
	v_mov_b32_e32 v48, 0
	global_store_dword v[76:77], v58, off offset:1024
	flat_load_dwordx4 v[40:43], v[56:57] offset:1024
	s_waitcnt vmcnt(0) lgkmcnt(0)
	v_pk_mul_f32 v[40:41], v[44:45], v[40:41]
	s_nop 0
	v_cvt_pk_bf16_f32 v44, v40, v41
	v_mul_f32_e32 v40, 0x41800000, v40
	v_mul_f32_e32 v41, 0x41800000, v41
	v_cvt_pk_fp8_f32 v48, v40, v41
	v_pk_mul_f32 v[42:43], v[46:47], v[42:43]
	s_nop 0
	v_cvt_pk_bf16_f32 v45, v42, v43
	v_mul_f32_e32 v42, 0x41800000, v42
	v_mul_f32_e32 v43, 0x41800000, v43
	v_cvt_pk_fp8_f32 v48, v42, v43 op_sel:[0,0,1]
	global_store_dwordx2 v[80:81], v[44:45], off offset:2560
	v_mov_b32_e32 v44, 0
	global_store_dword v[76:77], v48, off offset:1280
	flat_load_dwordx4 v[40:43], v[56:57] offset:2048
	s_waitcnt vmcnt(0) lgkmcnt(0)
	v_pk_mul_f32 v[36:37], v[36:37], v[40:41]
	s_nop 0
	v_cvt_pk_bf16_f32 v40, v36, v37
	v_mul_f32_e32 v36, 0x41800000, v36
	v_mul_f32_e32 v37, 0x41800000, v37
	v_cvt_pk_fp8_f32 v44, v36, v37
	v_pk_mul_f32 v[38:39], v[38:39], v[42:43]
	v_mov_b32_e32 v42, 0
	v_cvt_pk_bf16_f32 v41, v38, v39
	v_mul_f32_e32 v38, 0x41800000, v38
	v_mul_f32_e32 v39, 0x41800000, v39
	v_cvt_pk_fp8_f32 v44, v38, v39 op_sel:[0,0,1]
	global_store_dwordx2 v[80:81], v[40:41], off offset:3072
	v_add_co_u32_e32 v40, vcc, s8, v72
	global_store_dword v[76:77], v44, off offset:1536
	flat_load_dwordx4 v[36:39], v[56:57] offset:3072
	v_addc_co_u32_e32 v41, vcc, 0, v73, vcc
	s_waitcnt vmcnt(0) lgkmcnt(0)
	v_pk_mul_f32 v[32:33], v[32:33], v[36:37]
	s_nop 0
	v_cvt_pk_bf16_f32 v36, v32, v33
	v_mul_f32_e32 v32, 0x41800000, v32
	v_mul_f32_e32 v33, 0x41800000, v33
	v_cvt_pk_fp8_f32 v42, v32, v33
	v_pk_mul_f32 v[34:35], v[34:35], v[38:39]
	s_nop 0
	v_cvt_pk_bf16_f32 v37, v34, v35
	v_mul_f32_e32 v34, 0x41800000, v34
	v_mul_f32_e32 v35, 0x41800000, v35
	v_cvt_pk_fp8_f32 v42, v34, v35 op_sel:[0,0,1]
	global_store_dwordx2 v[80:81], v[36:37], off offset:3584
	v_mov_b32_e32 v36, 0
	global_store_dword v[76:77], v42, off offset:1792
	flat_load_dwordx4 v[32:35], v[40:41]
	s_waitcnt vmcnt(0) lgkmcnt(0)
	v_pk_mul_f32 v[28:29], v[28:29], v[32:33]
	s_nop 0
	v_cvt_pk_bf16_f32 v32, v28, v29
	v_mul_f32_e32 v28, 0x41800000, v28
	v_mul_f32_e32 v29, 0x41800000, v29
	v_cvt_pk_fp8_f32 v36, v28, v29
	v_pk_mul_f32 v[30:31], v[30:31], v[34:35]
	s_nop 0
	v_cvt_pk_bf16_f32 v33, v30, v31
	v_mul_f32_e32 v30, 0x41800000, v30
	v_mul_f32_e32 v31, 0x41800000, v31
	v_cvt_pk_fp8_f32 v36, v30, v31 op_sel:[0,0,1]
	global_store_dwordx2 v[74:75], v[32:33], off
	v_mov_b32_e32 v32, 0
	global_store_dword v[76:77], v36, off offset:2048
	flat_load_dwordx4 v[28:31], v[40:41] offset:1024
	s_waitcnt vmcnt(0) lgkmcnt(0)
; __device__ __forceinline__ unsigned cvt_pk_bf16(float lo, float hi) { unsigned r; asm volatile("v_cvt_pk_bf16_f32 %0, %1, %2" : "=v"(r) : "v"(lo), "v"(hi)); return r; }
; __device__ __forceinline__ void phase0(const Params& p, LAS unsigned char* lds, int gw, int NGW, int wave, int lane, int G) {
;     ...
;           for (int j = 0; j < 16; ++j) { const f32x4 gg = gp[64 * j]; const f32x4 a = v[j] * rs * gg; u32x2 w; w.x = cvt_pk_bf16(a[0], a[1]); w.y = cvt_pk_bf16(a[2], a[3]); o[64 * j] = w;
;               int q = __builtin_amdgcn_cvt_pk_fp8_f32(a[0] * 16.f, a[1] * 16.f, 0, false); q = __builtin_amdgcn_cvt_pk_fp8_f32(a[2] * 16.f, a[3] * 16.f, q, true); o8[64 * j] = (unsigned)q; }
	v_pk_mul_f32 v[24:25], v[24:25], v[28:29]
	s_nop 0
	v_cvt_pk_bf16_f32 v28, v24, v25
	v_mul_f32_e32 v24, 0x41800000, v24
	v_mul_f32_e32 v25, 0x41800000, v25
	v_cvt_pk_fp8_f32 v32, v24, v25
	v_pk_mul_f32 v[26:27], v[26:27], v[30:31]
	s_nop 0
	v_cvt_pk_bf16_f32 v29, v26, v27
	v_mul_f32_e32 v26, 0x41800000, v26
	v_mul_f32_e32 v27, 0x41800000, v27
	v_cvt_pk_fp8_f32 v32, v26, v27 op_sel:[0,0,1]
	global_store_dwordx2 v[74:75], v[28:29], off offset:512
	v_mov_b32_e32 v28, 0
	global_store_dword v[76:77], v32, off offset:2304
	flat_load_dwordx4 v[24:27], v[40:41] offset:2048
	s_waitcnt vmcnt(0) lgkmcnt(0)
	v_pk_mul_f32 v[20:21], v[20:21], v[24:25]
	s_nop 0
	v_cvt_pk_bf16_f32 v24, v20, v21
	v_mul_f32_e32 v20, 0x41800000, v20
	v_mul_f32_e32 v21, 0x41800000, v21
	v_cvt_pk_fp8_f32 v28, v20, v21
	v_pk_mul_f32 v[22:23], v[22:23], v[26:27]
	v_mov_b32_e32 v26, 0
	v_cvt_pk_bf16_f32 v25, v22, v23
	v_mul_f32_e32 v22, 0x41800000, v22
	v_mul_f32_e32 v23, 0x41800000, v23
	v_cvt_pk_fp8_f32 v28, v22, v23 op_sel:[0,0,1]
	global_store_dwordx2 v[74:75], v[24:25], off offset:1024
	v_add_co_u32_e32 v24, vcc, s9, v72
	global_store_dword v[76:77], v28, off offset:2560
	flat_load_dwordx4 v[20:23], v[40:41] offset:3072
	v_addc_co_u32_e32 v25, vcc, 0, v73, vcc
	s_waitcnt vmcnt(0) lgkmcnt(0)
	v_pk_mul_f32 v[16:17], v[16:17], v[20:21]
	s_nop 0
	v_cvt_pk_bf16_f32 v20, v16, v17
	v_mul_f32_e32 v16, 0x41800000, v16
	v_mul_f32_e32 v17, 0x41800000, v17
	v_cvt_pk_fp8_f32 v26, v16, v17
	v_pk_mul_f32 v[18:19], v[18:19], v[22:23]
	s_nop 0
	v_cvt_pk_bf16_f32 v21, v18, v19
	v_mul_f32_e32 v18, 0x41800000, v18
	v_mul_f32_e32 v19, 0x41800000, v19
	v_cvt_pk_fp8_f32 v26, v18, v19 op_sel:[0,0,1]
	global_store_dwordx2 v[74:75], v[20:21], off offset:1536
	v_mov_b32_e32 v20, 0
	global_store_dword v[76:77], v26, off offset:2816
	flat_load_dwordx4 v[16:19], v[24:25]
	s_waitcnt vmcnt(0) lgkmcnt(0)
	v_pk_mul_f32 v[12:13], v[12:13], v[16:17]
	s_nop 0
	v_cvt_pk_bf16_f32 v16, v12, v13
	v_mul_f32_e32 v12, 0x41800000, v12
	v_mul_f32_e32 v13, 0x41800000, v13
	v_cvt_pk_fp8_f32 v20, v12, v13
	v_pk_mul_f32 v[14:15], v[14:15], v[18:19]
	s_nop 0
	v_cvt_pk_bf16_f32 v17, v14, v15
	v_mul_f32_e32 v14, 0x41800000, v14
	v_mul_f32_e32 v15, 0x41800000, v15
	v_cvt_pk_fp8_f32 v20, v14, v15 op_sel:[0,0,1]
	global_store_dwordx2 v[74:75], v[16:17], off offset:2048
	v_mov_b32_e32 v16, 0
	global_store_dword v[76:77], v20, off offset:3072
	flat_load_dwordx4 v[12:15], v[24:25] offset:1024
	s_waitcnt vmcnt(0) lgkmcnt(0)
	v_pk_mul_f32 v[8:9], v[8:9], v[12:13]
	s_nop 0
	v_cvt_pk_bf16_f32 v12, v8, v9
	v_mul_f32_e32 v8, 0x41800000, v8
	v_mul_f32_e32 v9, 0x41800000, v9
	v_cvt_pk_fp8_f32 v16, v8, v9
	v_pk_mul_f32 v[10:11], v[10:11], v[14:15]
	s_nop 0
	v_cvt_pk_bf16_f32 v13, v10, v11
	v_mul_f32_e32 v10, 0x41800000, v10
	v_mul_f32_e32 v11, 0x41800000, v11
	v_cvt_pk_fp8_f32 v16, v10, v11 op_sel:[0,0,1]
	global_store_dwordx2 v[74:75], v[12:13], off offset:2560
	v_mov_b32_e32 v12, 0
	global_store_dword v[76:77], v16, off offset:3328
	flat_load_dwordx4 v[8:11], v[24:25] offset:2048
	s_waitcnt vmcnt(0) lgkmcnt(0)
	v_pk_mul_f32 v[4:5], v[4:5], v[8:9]
	s_nop 0
	v_cvt_pk_bf16_f32 v8, v4, v5
	v_mul_f32_e32 v4, 0x41800000, v4
	v_mul_f32_e32 v5, 0x41800000, v5
	v_cvt_pk_fp8_f32 v12, v4, v5
	v_pk_mul_f32 v[6:7], v[6:7], v[10:11]
	s_nop 0
	v_mul_f32_e32 v4, 0x41800000, v6
	v_mul_f32_e32 v5, 0x41800000, v7
	v_cvt_pk_fp8_f32 v12, v4, v5 op_sel:[0,0,1]
	v_cvt_pk_bf16_f32 v9, v6, v7
	global_store_dwordx2 v[74:75], v[8:9], off offset:3072
	global_store_dword v[76:77], v12, off offset:3584
	flat_load_dwordx4 v[4:7], v[24:25] offset:3072
	v_mov_b32_e32 v8, 0
	s_waitcnt vmcnt(0) lgkmcnt(0)
	v_pk_mul_f32 v[0:1], v[0:1], v[4:5]
	s_nop 0
	v_mul_f32_e32 v4, 0x41800000, v0
	v_mul_f32_e32 v5, 0x41800000, v1
	v_cvt_pk_fp8_f32 v8, v4, v5
	v_pk_mul_f32 v[2:3], v[2:3], v[6:7]
	v_cvt_pk_bf16_f32 v0, v0, v1
	s_nop 0
	v_mul_f32_e32 v4, 0x41800000, v2
	v_mul_f32_e32 v5, 0x41800000, v3
	v_cvt_pk_fp8_f32 v8, v4, v5 op_sel:[0,0,1]
	v_cvt_pk_bf16_f32 v1, v2, v3
	global_store_dwordx2 v[74:75], v[0:1], off offset:3584
	global_store_dword v[76:77], v8, off offset:3840
	s_cbranch_scc0 .LBB0_29

; #define LAS __attribute__((address_space(3)))
; __device__ __forceinline__ void transpose_item(const float* W, int N, bf16_t* WT, int nkt, int k0, int n0, int r0, int kbd, LAS float* scr, int lane) {
;     const size_t dst_off = ((size_t)(r0 >> 8) * nkt + kbd) * 16384 + (size_t)(r0 & 255) * 64;
;     const int l15 = lane & 15, lq = lane >> 4;
;     f32x4 v[16];
; #pragma unroll
;     for (int i = 0; i < 16; ++i) v[i] = *(const f32x4*)(W + (size_t)(k0 + 4 * i + lq) * N + n0 + 4 * l15);
; #pragma unroll
;     for (int i = 0; i < 16; ++i) { LAS float* d = scr + (4 * i + lq) * 65 + 4 * l15; d[0] = v[i][0]; d[1] = v[i][1]; d[2] = v[i][2]; d[3] = v[i][3]; }
; __device__ __forceinline__ void phase_convert_late(const Params& p, LAS float* scr, int cw, int NCW, int lane) {
;     ...
;     for (int it = cw; it < I1 + I2 + I3 + I4 + I5 + I6; it += NCW) {
;         int r = it;
;         if (r < I6) { const int nb = r % 344, kb = r / 344; const int n0 = nb * 64; const int nn = n0 < FF ? n0 : n0 - FF; const int r0 = (nn >> 7) * 256 + (n0 < FF ? 0 : 128) + (nn & 127);
;             transpose_item(p.in[21], FF2, (bf16_t*)(ws + WS_W_UP), 64, kb * 64, n0, r0, kb, scr, lane); continue; } r -= I6;
;         if (r < I1) { const int nb = r % 32, kb = r / 32; transpose_item(p.in[11], 2048, (bf16_t*)(ws + WS_W_GLU), 32, kb * 64, nb * 64, nb * 64, kb, scr, lane); continue; } r -= I1;
;         if (r < I2) { const int g = r >> 6, q = r & 63, nb = q & 7, kb = q >> 3; transpose_item(p.in[13] + (size_t)g * 512 * 512, 512, (bf16_t*)(ws + WS_W_POOL), 32, kb * 64, nb * 64, nb * 64, g * 8 + kb, scr, lane); continue; } r -= I2;
;         if (r < I3) { const int nb = r % 64, kb = r / 64; transpose_item(p.in[16], 4096, (bf16_t*)(ws + WS_W_BS), 32, kb * 64, nb * 64, nb * 64, kb, scr, lane); continue; } r -= I3;
;         if (r < I4) { const int nb = r % 64, kb = r / 64; transpose_item(p.in[17], 4096, (bf16_t*)(ws + WS_W_BP), 32, kb * 64, nb * 64, nb * 64, kb, scr, lane); continue; } r -= I4;
;         { const int nb = r % 64, kb = r / 64; transpose_item(p.in[18], 4096, (bf16_t*)(ws + WS_W_OUT), 64, kb * 64, nb * 64, nb * 64, kb, scr, lane); }
.LBB0_314:
	s_cmpk_gt_i32 s35, 0x55ff
	s_mov_b64 s[4:5], -1
	s_cbranch_scc0 .LBB0_332
	s_cmpk_gt_u32 s35, 0x59ff
	s_cbranch_scc0 .LBB0_329
	s_cmpk_gt_u32 s35, 0x5aff
	s_cbranch_scc0 .LBB0_326
	s_cmpk_gt_u32 s35, 0x62ff
	s_cbranch_scc0 .LBB0_323
	s_and_b32 s33, s16, 0xfc0
	s_cmpk_gt_u32 s35, 0x6aff
	s_cbranch_scc0 .LBB0_320
	s_add_i32 s4, s35, 0xffff9500
	s_and_b32 s0, s4, 0xffffffc0
	v_or_b32_e32 v0, s0, v3
	s_lshl_b32 s0, s33, 2
	v_or_b32_e32 v50, 4, v0
	v_mov_b32_e32 v51, v1
	v_or_b32_e32 v56, 8, v0
	v_mov_b32_e32 v57, v1
	v_or_b32_e32 v58, 12, v0
	v_mov_b32_e32 v59, v1
	v_or_b32_e32 v64, 16, v0
	v_mov_b32_e32 v65, v1
	v_or_b32_e32 v66, 20, v0
	v_mov_b32_e32 v67, v1
	v_or_b32_e32 v72, 24, v0
	v_mov_b32_e32 v73, v1
	v_or_b32_e32 v74, 28, v0
	v_mov_b32_e32 v75, v1
	v_or_b32_e32 v80, 32, v0
	v_mov_b32_e32 v81, v1
	v_or_b32_e32 v82, 36, v0
	v_mov_b32_e32 v83, v1
	v_lshl_add_u64 v[108:109], v[20:21], 0, s[0:1]
	v_lshlrev_b64 v[48:49], 14, v[0:1]
	v_lshlrev_b64 v[50:51], 14, v[50:51]
	v_lshlrev_b64 v[56:57], 14, v[56:57]
	v_lshlrev_b64 v[58:59], 14, v[58:59]
	v_lshlrev_b64 v[64:65], 14, v[64:65]
	v_lshlrev_b64 v[66:67], 14, v[66:67]
	v_lshlrev_b64 v[72:73], 14, v[72:73]
	v_lshlrev_b64 v[74:75], 14, v[74:75]
	v_lshlrev_b64 v[80:81], 14, v[80:81]
	v_lshlrev_b64 v[82:83], 14, v[82:83]
	v_or_b32_e32 v88, 40, v0
	v_mov_b32_e32 v89, v1
	v_or_b32_e32 v90, 44, v0
	v_mov_b32_e32 v91, v1
	v_lshl_add_u64 v[48:49], v[108:109], 0, v[48:49]
	v_lshl_add_u64 v[52:53], v[108:109], 0, v[50:51]
	v_lshl_add_u64 v[56:57], v[108:109], 0, v[56:57]
	v_lshl_add_u64 v[60:61], v[108:109], 0, v[58:59]
	v_lshl_add_u64 v[64:65], v[108:109], 0, v[64:65]
	v_lshl_add_u64 v[68:69], v[108:109], 0, v[66:67]
	v_lshl_add_u64 v[72:73], v[108:109], 0, v[72:73]
	v_lshl_add_u64 v[76:77], v[108:109], 0, v[74:75]
	v_lshl_add_u64 v[80:81], v[108:109], 0, v[80:81]
	v_lshl_add_u64 v[84:85], v[108:109], 0, v[82:83]
	v_lshlrev_b64 v[88:89], 14, v[88:89]
	v_lshlrev_b64 v[90:91], 14, v[90:91]
	global_load_dwordx4 v[48:51], v[48:49], off nt
	s_nop 0
	global_load_dwordx4 v[52:55], v[52:53], off nt
	s_nop 0
	global_load_dwordx4 v[56:59], v[56:57], off nt
	s_nop 0
	global_load_dwordx4 v[60:63], v[60:61], off nt
	s_nop 0
	global_load_dwordx4 v[64:67], v[64:65], off nt
	s_nop 0
	global_load_dwordx4 v[68:71], v[68:69], off nt
	s_nop 0
	global_load_dwordx4 v[72:75], v[72:73], off nt
	s_nop 0
	global_load_dwordx4 v[76:79], v[76:77], off nt
	s_nop 0
	global_load_dwordx4 v[80:83], v[80:81], off nt
	s_nop 0
	global_load_dwordx4 v[84:87], v[84:85], off nt
	v_lshl_add_u64 v[88:89], v[108:109], 0, v[88:89]
	v_lshl_add_u64 v[92:93], v[108:109], 0, v[90:91]
	global_load_dwordx4 v[88:91], v[88:89], off nt
	s_nop 0
	global_load_dwordx4 v[92:95], v[92:93], off nt
	v_or_b32_e32 v96, 48, v0
	v_mov_b32_e32 v97, v1
	v_lshlrev_b64 v[96:97], 14, v[96:97]
	v_lshl_add_u64 v[96:97], v[108:109], 0, v[96:97]
	v_or_b32_e32 v100, 52, v0
	v_mov_b32_e32 v101, v1
	global_load_dwordx4 v[96:99], v[96:97], off nt
	v_lshlrev_b64 v[100:101], 14, v[100:101]
	v_lshl_add_u64 v[100:101], v[108:109], 0, v[100:101]
	v_or_b32_e32 v104, 56, v0
	v_mov_b32_e32 v105, v1
	global_load_dwordx4 v[100:103], v[100:101], off nt
	v_lshlrev_b64 v[104:105], 14, v[104:105]
	v_lshl_add_u64 v[104:105], v[108:109], 0, v[104:105]
	v_or_b32_e32 v0, 60, v0
	global_load_dwordx4 v[104:107], v[104:105], off nt
	v_lshlrev_b64 v[110:111], 14, v[0:1]
	v_lshl_add_u64 v[108:109], v[108:109], 0, v[110:111]
	global_load_dwordx4 v[108:111], v[108:109], off nt
	v_add_u32_e32 v0, 0xf0a0, v5
	s_lshr_b32 s0, s4, 6
	s_and_b32 s4, s18, 0x3c0
	s_add_i32 s0, s4, s0
	s_lshl_b32 s4, s33, 7
	s_and_b32 s4, s4, 0x6000
	s_add_u32 s62, s3, s4
	v_add_u32_e32 v31, 0xc800, v9
	s_addc_u32 s63, s8, 0
	s_lshl_b64 s[4:5], s[0:1], 15
	s_waitcnt vmcnt(15)
	ds_write2_b32 v7, v48, v49 offset1:1
	ds_write2_b32 v11, v50, v51 offset1:1
	s_waitcnt vmcnt(14)
	ds_write2_b32 v13, v52, v53 offset1:1
	ds_write2_b32 v15, v54, v55 offset1:1
	s_waitcnt vmcnt(13)
	ds_write2_b32 v17, v56, v57 offset1:1
	ds_write2_b32 v19, v58, v59 offset1:1
	s_waitcnt vmcnt(12)
	ds_write2_b32 v32, v60, v61 offset1:1
	ds_write2_b32 v33, v62, v63 offset1:1
	s_waitcnt vmcnt(11)
	ds_write2_b32 v34, v64, v65 offset1:1
	ds_write2_b32 v36, v66, v67 offset1:1
	s_waitcnt vmcnt(10)
	ds_write2_b32 v37, v68, v69 offset1:1
	ds_write2_b32 v38, v70, v71 offset1:1
	s_waitcnt vmcnt(9)
	ds_write2_b32 v39, v72, v73 offset1:1
	ds_write2_b32 v40, v74, v75 offset1:1
	s_waitcnt vmcnt(8)
	ds_write2_b32 v41, v76, v77 offset1:1
	ds_write2_b32 v42, v78, v79 offset1:1
	s_waitcnt vmcnt(7)
	ds_write2_b32 v43, v80, v81 offset1:1
	ds_write2_b32 v44, v82, v83 offset1:1
	s_waitcnt vmcnt(6)
	ds_write2_b32 v45, v84, v85 offset1:1
	ds_write2_b32 v46, v86, v87 offset1:1
	s_add_u32 s4, s62, s4
	s_waitcnt vmcnt(5)
	ds_write2_b32 v0, v88, v89 offset1:1
	v_add_u32_e32 v0, 0xf0a8, v5
	ds_write2_b32 v0, v90, v91 offset1:1
	v_add_u32_e32 v0, 0xf4b0, v5
	s_waitcnt vmcnt(4)
	ds_write2_b32 v0, v92, v93 offset1:1
	v_add_u32_e32 v0, 0xf4b8, v5
	ds_write2_b32 v0, v94, v95 offset1:1
	v_add_u32_e32 v0, 0xf8c0, v5
	s_waitcnt vmcnt(3)
	ds_write2_b32 v0, v96, v97 offset1:1
	v_add_u32_e32 v0, 0xf8c8, v5
	ds_write2_b32 v0, v98, v99 offset1:1
	v_add_u32_e32 v0, 0xfcd0, v5
	v_add_u32_e32 v47, 0xcc00, v9
	s_waitcnt vmcnt(2)
	ds_write2_b32 v0, v100, v101 offset1:1
	v_add_u32_e32 v0, 0xfcd8, v5
	ds_write2_b32 v0, v102, v103 offset1:1
	v_add_u32_e32 v0, 0x38e0, v7
	s_waitcnt vmcnt(1)
	ds_write2_b32 v0, v104, v105 offset1:1
	v_add_u32_e32 v0, 0x38e8, v7
	ds_write2_b32 v0, v106, v107 offset1:1
	v_add_u32_e32 v0, 0x3cf0, v7
	s_waitcnt vmcnt(0)
; #define LAS __attribute__((address_space(3)))
; __device__ __forceinline__ unsigned cvt_pk_bf16(float lo, float hi) { unsigned r; asm volatile("v_cvt_pk_bf16_f32 %0, %1, %2" : "=v"(r) : "v"(lo), "v"(hi)); return r; }
; #define LDS_WAIT() asm volatile("s_waitcnt lgkmcnt(0)" ::: "memory")
; __device__ __forceinline__ void transpose_item(const float* W, int N, bf16_t* WT, int nkt, int k0, int n0, int r0, int kbd, LAS float* scr, int lane) {
;     ...
;     for (int i = 0; i < 16; ++i) { LAS float* d = scr + (4 * i + lq) * 65 + 4 * l15; d[0] = v[i][0]; d[1] = v[i][1]; d[2] = v[i][2]; d[3] = v[i][3]; }
;     LDS_WAIT();
;     const int c = lane & 7;
; #pragma unroll
;     for (int j = 0; j < 8; ++j) { const int n = (lane >> 3) + 8 * j; const LAS float* s = scr + (8 * c) * 65 + n;
;         u32x4 o; o.x = cvt_pk_bf16(s[0], s[65]); o.y = cvt_pk_bf16(s[2 * 65], s[3 * 65]); o.z = cvt_pk_bf16(s[4 * 65], s[5 * 65]); o.w = cvt_pk_bf16(s[6 * 65], s[7 * 65]);
;         *(u32x4*)(WT + dst_off + (size_t)n * 64 + 8 * c) = o; }
;     LDS_WAIT();
; }
	ds_write2_b32 v0, v108, v109 offset1:1
	v_add_u32_e32 v0, 0x3cf8, v7
	ds_write2_b32 v0, v110, v111 offset1:1
	s_waitcnt lgkmcnt(0)
	ds_read2_b32 v[48:49], v31 offset1:65
	s_waitcnt lgkmcnt(0)
	v_cvt_pk_bf16_f32 v48, v48, v49
	ds_read2_b32 v[50:51], v31 offset0:130 offset1:195
	s_addc_u32 s5, s63, s5
	v_lshlrev_b32_e32 v0, 1, v2
	s_waitcnt lgkmcnt(0)
	v_cvt_pk_bf16_f32 v49, v50, v51
	ds_read2_b32 v[50:51], v47 offset0:4 offset1:69
	v_lshl_add_u64 v[54:55], s[4:5], 0, v[0:1]
	v_lshlrev_b32_e32 v0, 1, v4
	s_waitcnt lgkmcnt(0)
	v_cvt_pk_bf16_f32 v50, v50, v51
	ds_read2_b32 v[52:53], v47 offset0:134 offset1:199
	s_waitcnt lgkmcnt(0)
	v_cvt_pk_bf16_f32 v51, v52, v53
	v_lshl_add_u64 v[56:57], v[54:55], 0, v[0:1]
	ds_read2_b32 v[52:53], v31 offset0:8 offset1:73
	global_store_dwordx4 v[56:57], v[48:51], off
	v_lshlrev_b32_e32 v0, 1, v6
	v_lshl_add_u64 v[56:57], v[54:55], 0, v[0:1]
	s_waitcnt lgkmcnt(0)
	v_cvt_pk_bf16_f32 v48, v52, v53
	ds_read2_b32 v[50:51], v31 offset0:138 offset1:203
	s_waitcnt lgkmcnt(0)
	v_cvt_pk_bf16_f32 v49, v50, v51
	ds_read2_b32 v[50:51], v47 offset0:12 offset1:77
	s_waitcnt lgkmcnt(0)
	v_cvt_pk_bf16_f32 v50, v50, v51
	ds_read2_b32 v[52:53], v47 offset0:142 offset1:207
	s_waitcnt lgkmcnt(0)
	v_cvt_pk_bf16_f32 v51, v52, v53
	ds_read2_b32 v[52:53], v31 offset0:16 offset1:81
	global_store_dwordx4 v[56:57], v[48:51], off
	v_lshlrev_b32_e32 v0, 1, v8
	v_lshl_add_u64 v[56:57], v[54:55], 0, v[0:1]
	s_waitcnt lgkmcnt(0)
	v_cvt_pk_bf16_f32 v48, v52, v53
	ds_read2_b32 v[50:51], v31 offset0:146 offset1:211
	s_waitcnt lgkmcnt(0)
	v_cvt_pk_bf16_f32 v49, v50, v51
	ds_read2_b32 v[50:51], v47 offset0:20 offset1:85
	s_waitcnt lgkmcnt(0)
	v_cvt_pk_bf16_f32 v50, v50, v51
	ds_read2_b32 v[52:53], v47 offset0:150 offset1:215
	s_waitcnt lgkmcnt(0)
	v_cvt_pk_bf16_f32 v51, v52, v53
	ds_read2_b32 v[52:53], v31 offset0:24 offset1:89
	global_store_dwordx4 v[56:57], v[48:51], off
	v_lshlrev_b32_e32 v0, 1, v10
	v_lshl_add_u64 v[56:57], v[54:55], 0, v[0:1]
	s_waitcnt lgkmcnt(0)
	v_cvt_pk_bf16_f32 v48, v52, v53
	ds_read2_b32 v[50:51], v31 offset0:154 offset1:219
	s_waitcnt lgkmcnt(0)
	v_cvt_pk_bf16_f32 v49, v50, v51
	ds_read2_b32 v[50:51], v47 offset0:28 offset1:93
	s_waitcnt lgkmcnt(0)
	v_cvt_pk_bf16_f32 v50, v50, v51
	ds_read2_b32 v[52:53], v47 offset0:158 offset1:223
	s_waitcnt lgkmcnt(0)
	v_cvt_pk_bf16_f32 v51, v52, v53
	ds_read2_b32 v[52:53], v31 offset0:32 offset1:97
	global_store_dwordx4 v[56:57], v[48:51], off
	v_lshlrev_b32_e32 v0, 1, v12
	v_lshl_add_u64 v[56:57], v[54:55], 0, v[0:1]
	s_waitcnt lgkmcnt(0)
	v_cvt_pk_bf16_f32 v48, v52, v53
	ds_read2_b32 v[50:51], v31 offset0:162 offset1:227
	s_waitcnt lgkmcnt(0)
	v_cvt_pk_bf16_f32 v49, v50, v51
	ds_read2_b32 v[50:51], v47 offset0:36 offset1:101
	s_waitcnt lgkmcnt(0)
	v_cvt_pk_bf16_f32 v50, v50, v51
	ds_read2_b32 v[52:53], v47 offset0:166 offset1:231
	s_waitcnt lgkmcnt(0)
	v_cvt_pk_bf16_f32 v51, v52, v53
	ds_read2_b32 v[52:53], v31 offset0:40 offset1:105
	global_store_dwordx4 v[56:57], v[48:51], off
	v_lshlrev_b32_e32 v0, 1, v14
	v_lshl_add_u64 v[56:57], v[54:55], 0, v[0:1]
	s_waitcnt lgkmcnt(0)
	v_cvt_pk_bf16_f32 v48, v52, v53
	ds_read2_b32 v[50:51], v31 offset0:170 offset1:235
	s_waitcnt lgkmcnt(0)
	v_cvt_pk_bf16_f32 v49, v50, v51
	ds_read2_b32 v[50:51], v47 offset0:44 offset1:109
	s_waitcnt lgkmcnt(0)
	v_cvt_pk_bf16_f32 v50, v50, v51
	ds_read2_b32 v[52:53], v47 offset0:174 offset1:239
	s_waitcnt lgkmcnt(0)
	v_cvt_pk_bf16_f32 v51, v52, v53
	ds_read2_b32 v[52:53], v31 offset0:48 offset1:113
	global_store_dwordx4 v[56:57], v[48:51], off
	v_lshlrev_b32_e32 v0, 1, v16
	v_lshl_add_u64 v[56:57], v[54:55], 0, v[0:1]
	s_waitcnt lgkmcnt(0)
	v_cvt_pk_bf16_f32 v48, v52, v53
	ds_read2_b32 v[50:51], v31 offset0:178 offset1:243
	s_waitcnt lgkmcnt(0)
	v_cvt_pk_bf16_f32 v49, v50, v51
	ds_read2_b32 v[50:51], v47 offset0:52 offset1:117
	s_waitcnt lgkmcnt(0)
	v_cvt_pk_bf16_f32 v50, v50, v51
	ds_read2_b32 v[52:53], v47 offset0:182 offset1:247
	s_waitcnt lgkmcnt(0)
	v_cvt_pk_bf16_f32 v51, v52, v53
	ds_read2_b32 v[52:53], v31 offset0:56 offset1:121
	global_store_dwordx4 v[56:57], v[48:51], off
	v_lshlrev_b32_e32 v0, 1, v18
	s_mov_b64 s[4:5], 0
	s_waitcnt lgkmcnt(0)
	v_cvt_pk_bf16_f32 v48, v52, v53
	ds_read2_b32 v[50:51], v31 offset0:186 offset1:251
	s_waitcnt lgkmcnt(0)
	v_cvt_pk_bf16_f32 v49, v50, v51
	ds_read2_b32 v[50:51], v47 offset0:60 offset1:125
	s_waitcnt lgkmcnt(0)
	v_cvt_pk_bf16_f32 v50, v50, v51
	ds_read2_b32 v[52:53], v47 offset0:190 offset1:255
	s_waitcnt lgkmcnt(0)
	v_cvt_pk_bf16_f32 v51, v52, v53
	v_lshl_add_u64 v[52:53], v[54:55], 0, v[0:1]
	global_store_dwordx4 v[52:53], v[48:51], off
	s_waitcnt lgkmcnt(0)
; #define LAS __attribute__((address_space(3)))
; __device__ __forceinline__ void transpose_item(const float* W, int N, bf16_t* WT, int nkt, int k0, int n0, int r0, int kbd, LAS float* scr, int lane) {
;     const size_t dst_off = ((size_t)(r0 >> 8) * nkt + kbd) * 16384 + (size_t)(r0 & 255) * 64;
;     const int l15 = lane & 15, lq = lane >> 4;
;     f32x4 v[16];
; #pragma unroll
;     for (int i = 0; i < 16; ++i) v[i] = *(const f32x4*)(W + (size_t)(k0 + 4 * i + lq) * N + n0 + 4 * l15);
; #pragma unroll
;     for (int i = 0; i < 16; ++i) { LAS float* d = scr + (4 * i + lq) * 65 + 4 * l15; d[0] = v[i][0]; d[1] = v[i][1]; d[2] = v[i][2]; d[3] = v[i][3]; }
; __device__ __forceinline__ void phase_convert_late(const Params& p, LAS float* scr, int cw, int NCW, int lane) {
;     ...
;         if (r < I4) { const int nb = r % 64, kb = r / 64; transpose_item(p.in[17], 4096, (bf16_t*)(ws + WS_W_BP), 32, kb * 64, nb * 64, nb * 64, kb, scr, lane); continue; } r -= I4;
.LBB0_320:
	s_andn2_b64 vcc, exec, s[4:5]
	s_cbranch_vccnz .LBB0_322
	s_add_i32 s4, s35, 0xffff9d00
	s_and_b32 s0, s4, 0xffffffc0
	v_or_b32_e32 v0, s0, v3
	s_lshl_b32 s0, s33, 2
	v_or_b32_e32 v50, 4, v0
	v_mov_b32_e32 v51, v1
	v_or_b32_e32 v56, 8, v0
	v_mov_b32_e32 v57, v1
	v_or_b32_e32 v58, 12, v0
	v_mov_b32_e32 v59, v1
	v_or_b32_e32 v64, 16, v0
	v_mov_b32_e32 v65, v1
	v_or_b32_e32 v66, 20, v0
	v_mov_b32_e32 v67, v1
	v_or_b32_e32 v72, 24, v0
	v_mov_b32_e32 v73, v1
	v_or_b32_e32 v74, 28, v0
	v_mov_b32_e32 v75, v1
	v_or_b32_e32 v80, 32, v0
	v_mov_b32_e32 v81, v1
	v_or_b32_e32 v82, 36, v0
	v_mov_b32_e32 v83, v1
	v_lshl_add_u64 v[108:109], v[22:23], 0, s[0:1]
	v_lshlrev_b64 v[48:49], 14, v[0:1]
	v_lshlrev_b64 v[50:51], 14, v[50:51]
	v_lshlrev_b64 v[56:57], 14, v[56:57]
	v_lshlrev_b64 v[58:59], 14, v[58:59]
	v_lshlrev_b64 v[64:65], 14, v[64:65]
	v_lshlrev_b64 v[66:67], 14, v[66:67]
	v_lshlrev_b64 v[72:73], 14, v[72:73]
	v_lshlrev_b64 v[74:75], 14, v[74:75]
	v_lshlrev_b64 v[80:81], 14, v[80:81]
	v_lshlrev_b64 v[82:83], 14, v[82:83]
	v_or_b32_e32 v88, 40, v0
	v_mov_b32_e32 v89, v1
	v_or_b32_e32 v90, 44, v0
	v_mov_b32_e32 v91, v1
	v_lshl_add_u64 v[48:49], v[108:109], 0, v[48:49]
	v_lshl_add_u64 v[52:53], v[108:109], 0, v[50:51]
	v_lshl_add_u64 v[56:57], v[108:109], 0, v[56:57]
	v_lshl_add_u64 v[60:61], v[108:109], 0, v[58:59]
	v_lshl_add_u64 v[64:65], v[108:109], 0, v[64:65]
	v_lshl_add_u64 v[68:69], v[108:109], 0, v[66:67]
	v_lshl_add_u64 v[72:73], v[108:109], 0, v[72:73]
	v_lshl_add_u64 v[76:77], v[108:109], 0, v[74:75]
	v_lshl_add_u64 v[80:81], v[108:109], 0, v[80:81]
	v_lshl_add_u64 v[84:85], v[108:109], 0, v[82:83]
	v_lshlrev_b64 v[88:89], 14, v[88:89]
	v_lshlrev_b64 v[90:91], 14, v[90:91]
	global_load_dwordx4 v[48:51], v[48:49], off nt
	s_nop 0
	global_load_dwordx4 v[52:55], v[52:53], off nt
	s_nop 0
	global_load_dwordx4 v[56:59], v[56:57], off nt
	s_nop 0
	global_load_dwordx4 v[60:63], v[60:61], off nt
	s_nop 0
	global_load_dwordx4 v[64:67], v[64:65], off nt
	s_nop 0
	global_load_dwordx4 v[68:71], v[68:69], off nt
	s_nop 0
	global_load_dwordx4 v[72:75], v[72:73], off nt
	s_nop 0
	global_load_dwordx4 v[76:79], v[76:77], off nt
	s_nop 0
	global_load_dwordx4 v[80:83], v[80:81], off nt
	s_nop 0
	global_load_dwordx4 v[84:87], v[84:85], off nt
	v_lshl_add_u64 v[88:89], v[108:109], 0, v[88:89]
	v_lshl_add_u64 v[92:93], v[108:109], 0, v[90:91]
	global_load_dwordx4 v[88:91], v[88:89], off nt
	s_nop 0
	global_load_dwordx4 v[92:95], v[92:93], off nt
	v_or_b32_e32 v96, 48, v0
	v_mov_b32_e32 v97, v1
	v_lshlrev_b64 v[96:97], 14, v[96:97]
	v_lshl_add_u64 v[96:97], v[108:109], 0, v[96:97]
	v_or_b32_e32 v100, 52, v0
	v_mov_b32_e32 v101, v1
	global_load_dwordx4 v[96:99], v[96:97], off nt
	v_lshlrev_b64 v[100:101], 14, v[100:101]
	v_lshl_add_u64 v[100:101], v[108:109], 0, v[100:101]
	v_or_b32_e32 v104, 56, v0
	v_mov_b32_e32 v105, v1
	global_load_dwordx4 v[100:103], v[100:101], off nt
	v_lshlrev_b64 v[104:105], 14, v[104:105]
	v_lshl_add_u64 v[104:105], v[108:109], 0, v[104:105]
	v_or_b32_e32 v0, 60, v0
	global_load_dwordx4 v[104:107], v[104:105], off nt
	v_lshlrev_b64 v[110:111], 14, v[0:1]
	v_lshl_add_u64 v[108:109], v[108:109], 0, v[110:111]
	global_load_dwordx4 v[108:111], v[108:109], off nt
	v_add_u32_e32 v0, 0xf0a0, v5
	s_lshr_b32 s0, s4, 6
	s_and_b32 s4, s20, 0x3000
	s_and_b32 s5, s26, 0x1e0
	s_add_i32 s0, s5, s0
	s_lshl_b32 s4, s4, 1
	s_add_u32 s33, s9, s4
	v_add_u32_e32 v31, 0xc800, v9
	s_addc_u32 s62, s10, 0
	s_lshl_b64 s[4:5], s[0:1], 15
	s_waitcnt vmcnt(15)
	ds_write2_b32 v7, v48, v49 offset1:1
	ds_write2_b32 v11, v50, v51 offset1:1
	s_waitcnt vmcnt(14)
	ds_write2_b32 v13, v52, v53 offset1:1
	ds_write2_b32 v15, v54, v55 offset1:1
	s_waitcnt vmcnt(13)
	ds_write2_b32 v17, v56, v57 offset1:1
	ds_write2_b32 v19, v58, v59 offset1:1
	s_waitcnt vmcnt(12)
	ds_write2_b32 v32, v60, v61 offset1:1
	ds_write2_b32 v33, v62, v63 offset1:1
	s_waitcnt vmcnt(11)
	ds_write2_b32 v34, v64, v65 offset1:1
	ds_write2_b32 v36, v66, v67 offset1:1
	s_waitcnt vmcnt(10)
	ds_write2_b32 v37, v68, v69 offset1:1
	ds_write2_b32 v38, v70, v71 offset1:1
	s_waitcnt vmcnt(9)
	ds_write2_b32 v39, v72, v73 offset1:1
	ds_write2_b32 v40, v74, v75 offset1:1
	s_waitcnt vmcnt(8)
	ds_write2_b32 v41, v76, v77 offset1:1
	ds_write2_b32 v42, v78, v79 offset1:1
	s_waitcnt vmcnt(7)
	ds_write2_b32 v43, v80, v81 offset1:1
	ds_write2_b32 v44, v82, v83 offset1:1
	s_waitcnt vmcnt(6)
	ds_write2_b32 v45, v84, v85 offset1:1
	ds_write2_b32 v46, v86, v87 offset1:1
	s_add_u32 s4, s33, s4
	s_waitcnt vmcnt(5)
	ds_write2_b32 v0, v88, v89 offset1:1
	v_add_u32_e32 v0, 0xf0a8, v5
	ds_write2_b32 v0, v90, v91 offset1:1
	v_add_u32_e32 v0, 0xf4b0, v5
	s_waitcnt vmcnt(4)
	ds_write2_b32 v0, v92, v93 offset1:1
	v_add_u32_e32 v0, 0xf4b8, v5
	ds_write2_b32 v0, v94, v95 offset1:1
	v_add_u32_e32 v0, 0xf8c0, v5
	s_waitcnt vmcnt(3)
	ds_write2_b32 v0, v96, v97 offset1:1
	v_add_u32_e32 v0, 0xf8c8, v5
	ds_write2_b32 v0, v98, v99 offset1:1
	v_add_u32_e32 v0, 0xfcd0, v5
	v_add_u32_e32 v47, 0xcc00, v9
	s_waitcnt vmcnt(2)
; #define LAS __attribute__((address_space(3)))
; __device__ __forceinline__ unsigned cvt_pk_bf16(float lo, float hi) { unsigned r; asm volatile("v_cvt_pk_bf16_f32 %0, %1, %2" : "=v"(r) : "v"(lo), "v"(hi)); return r; }
; #define LDS_WAIT() asm volatile("s_waitcnt lgkmcnt(0)" ::: "memory")
; __device__ __forceinline__ void transpose_item(const float* W, int N, bf16_t* WT, int nkt, int k0, int n0, int r0, int kbd, LAS float* scr, int lane) {
;     ...
;     for (int i = 0; i < 16; ++i) { LAS float* d = scr + (4 * i + lq) * 65 + 4 * l15; d[0] = v[i][0]; d[1] = v[i][1]; d[2] = v[i][2]; d[3] = v[i][3]; }
;     LDS_WAIT();
;     const int c = lane & 7;
; #pragma unroll
;     for (int j = 0; j < 8; ++j) { const int n = (lane >> 3) + 8 * j; const LAS float* s = scr + (8 * c) * 65 + n;
;         u32x4 o; o.x = cvt_pk_bf16(s[0], s[65]); o.y = cvt_pk_bf16(s[2 * 65], s[3 * 65]); o.z = cvt_pk_bf16(s[4 * 65], s[5 * 65]); o.w = cvt_pk_bf16(s[6 * 65], s[7 * 65]);
;         *(u32x4*)(WT + dst_off + (size_t)n * 64 + 8 * c) = o; }
;     LDS_WAIT();
; }
	ds_write2_b32 v0, v100, v101 offset1:1
	v_add_u32_e32 v0, 0xfcd8, v5
	ds_write2_b32 v0, v102, v103 offset1:1
	v_add_u32_e32 v0, 0x38e0, v7
	s_waitcnt vmcnt(1)
	ds_write2_b32 v0, v104, v105 offset1:1
	v_add_u32_e32 v0, 0x38e8, v7
	ds_write2_b32 v0, v106, v107 offset1:1
	v_add_u32_e32 v0, 0x3cf0, v7
	s_waitcnt vmcnt(0)
	ds_write2_b32 v0, v108, v109 offset1:1
	v_add_u32_e32 v0, 0x3cf8, v7
	ds_write2_b32 v0, v110, v111 offset1:1
	s_waitcnt lgkmcnt(0)
	ds_read2_b32 v[48:49], v31 offset1:65
	s_waitcnt lgkmcnt(0)
	v_cvt_pk_bf16_f32 v48, v48, v49
	ds_read2_b32 v[50:51], v31 offset0:130 offset1:195
	s_addc_u32 s5, s62, s5
	v_lshlrev_b32_e32 v0, 1, v2
	s_waitcnt lgkmcnt(0)
	v_cvt_pk_bf16_f32 v49, v50, v51
	ds_read2_b32 v[50:51], v47 offset0:4 offset1:69
	v_lshl_add_u64 v[54:55], s[4:5], 0, v[0:1]
	v_lshlrev_b32_e32 v0, 1, v4
	s_waitcnt lgkmcnt(0)
	v_cvt_pk_bf16_f32 v50, v50, v51
	ds_read2_b32 v[52:53], v47 offset0:134 offset1:199
	s_waitcnt lgkmcnt(0)
	v_cvt_pk_bf16_f32 v51, v52, v53
	v_lshl_add_u64 v[56:57], v[54:55], 0, v[0:1]
	ds_read2_b32 v[52:53], v31 offset0:8 offset1:73
	global_store_dwordx4 v[56:57], v[48:51], off
	v_lshlrev_b32_e32 v0, 1, v6
	v_lshl_add_u64 v[56:57], v[54:55], 0, v[0:1]
	s_waitcnt lgkmcnt(0)
	v_cvt_pk_bf16_f32 v48, v52, v53
	ds_read2_b32 v[50:51], v31 offset0:138 offset1:203
	s_waitcnt lgkmcnt(0)
	v_cvt_pk_bf16_f32 v49, v50, v51
	ds_read2_b32 v[50:51], v47 offset0:12 offset1:77
	s_waitcnt lgkmcnt(0)
	v_cvt_pk_bf16_f32 v50, v50, v51
	ds_read2_b32 v[52:53], v47 offset0:142 offset1:207
	s_waitcnt lgkmcnt(0)
	v_cvt_pk_bf16_f32 v51, v52, v53
	ds_read2_b32 v[52:53], v31 offset0:16 offset1:81
	global_store_dwordx4 v[56:57], v[48:51], off
	v_lshlrev_b32_e32 v0, 1, v8
	v_lshl_add_u64 v[56:57], v[54:55], 0, v[0:1]
	s_waitcnt lgkmcnt(0)
	v_cvt_pk_bf16_f32 v48, v52, v53
	ds_read2_b32 v[50:51], v31 offset0:146 offset1:211
	s_waitcnt lgkmcnt(0)
	v_cvt_pk_bf16_f32 v49, v50, v51
	ds_read2_b32 v[50:51], v47 offset0:20 offset1:85
	s_waitcnt lgkmcnt(0)
	v_cvt_pk_bf16_f32 v50, v50, v51
	ds_read2_b32 v[52:53], v47 offset0:150 offset1:215
	s_waitcnt lgkmcnt(0)
	v_cvt_pk_bf16_f32 v51, v52, v53
	ds_read2_b32 v[52:53], v31 offset0:24 offset1:89
	global_store_dwordx4 v[56:57], v[48:51], off
	v_lshlrev_b32_e32 v0, 1, v10
	v_lshl_add_u64 v[56:57], v[54:55], 0, v[0:1]
	s_waitcnt lgkmcnt(0)
	v_cvt_pk_bf16_f32 v48, v52, v53
	ds_read2_b32 v[50:51], v31 offset0:154 offset1:219
	s_waitcnt lgkmcnt(0)
	v_cvt_pk_bf16_f32 v49, v50, v51
	ds_read2_b32 v[50:51], v47 offset0:28 offset1:93
	s_waitcnt lgkmcnt(0)
	v_cvt_pk_bf16_f32 v50, v50, v51
	ds_read2_b32 v[52:53], v47 offset0:158 offset1:223
	s_waitcnt lgkmcnt(0)
	v_cvt_pk_bf16_f32 v51, v52, v53
	ds_read2_b32 v[52:53], v31 offset0:32 offset1:97
	global_store_dwordx4 v[56:57], v[48:51], off
	v_lshlrev_b32_e32 v0, 1, v12
	v_lshl_add_u64 v[56:57], v[54:55], 0, v[0:1]
	s_waitcnt lgkmcnt(0)
	v_cvt_pk_bf16_f32 v48, v52, v53
	ds_read2_b32 v[50:51], v31 offset0:162 offset1:227
	s_waitcnt lgkmcnt(0)
	v_cvt_pk_bf16_f32 v49, v50, v51
	ds_read2_b32 v[50:51], v47 offset0:36 offset1:101
	s_waitcnt lgkmcnt(0)
	v_cvt_pk_bf16_f32 v50, v50, v51
	ds_read2_b32 v[52:53], v47 offset0:166 offset1:231
	s_waitcnt lgkmcnt(0)
	v_cvt_pk_bf16_f32 v51, v52, v53
	ds_read2_b32 v[52:53], v31 offset0:40 offset1:105
	global_store_dwordx4 v[56:57], v[48:51], off
	v_lshlrev_b32_e32 v0, 1, v14
	v_lshl_add_u64 v[56:57], v[54:55], 0, v[0:1]
	s_waitcnt lgkmcnt(0)
	v_cvt_pk_bf16_f32 v48, v52, v53
	ds_read2_b32 v[50:51], v31 offset0:170 offset1:235
	s_waitcnt lgkmcnt(0)
	v_cvt_pk_bf16_f32 v49, v50, v51
	ds_read2_b32 v[50:51], v47 offset0:44 offset1:109
	s_waitcnt lgkmcnt(0)
	v_cvt_pk_bf16_f32 v50, v50, v51
	ds_read2_b32 v[52:53], v47 offset0:174 offset1:239
	s_waitcnt lgkmcnt(0)
	v_cvt_pk_bf16_f32 v51, v52, v53
	ds_read2_b32 v[52:53], v31 offset0:48 offset1:113
	global_store_dwordx4 v[56:57], v[48:51], off
	v_lshlrev_b32_e32 v0, 1, v16
	v_lshl_add_u64 v[56:57], v[54:55], 0, v[0:1]
	s_waitcnt lgkmcnt(0)
	v_cvt_pk_bf16_f32 v48, v52, v53
	ds_read2_b32 v[50:51], v31 offset0:178 offset1:243
	s_waitcnt lgkmcnt(0)
	v_cvt_pk_bf16_f32 v49, v50, v51
	ds_read2_b32 v[50:51], v47 offset0:52 offset1:117
	s_waitcnt lgkmcnt(0)
	v_cvt_pk_bf16_f32 v50, v50, v51
	ds_read2_b32 v[52:53], v47 offset0:182 offset1:247
	s_waitcnt lgkmcnt(0)
	v_cvt_pk_bf16_f32 v51, v52, v53
	ds_read2_b32 v[52:53], v31 offset0:56 offset1:121
	global_store_dwordx4 v[56:57], v[48:51], off
	v_lshlrev_b32_e32 v0, 1, v18
	s_waitcnt lgkmcnt(0)
	v_cvt_pk_bf16_f32 v48, v52, v53
	ds_read2_b32 v[50:51], v31 offset0:186 offset1:251
	s_waitcnt lgkmcnt(0)
	v_cvt_pk_bf16_f32 v49, v50, v51
	ds_read2_b32 v[50:51], v47 offset0:60 offset1:125
	s_waitcnt lgkmcnt(0)
	v_cvt_pk_bf16_f32 v50, v50, v51
	ds_read2_b32 v[52:53], v47 offset0:190 offset1:255
	s_waitcnt lgkmcnt(0)
	v_cvt_pk_bf16_f32 v51, v52, v53
	v_lshl_add_u64 v[52:53], v[54:55], 0, v[0:1]
	global_store_dwordx4 v[52:53], v[48:51], off
	s_waitcnt lgkmcnt(0)

; #define LAS __attribute__((address_space(3)))
; __device__ __forceinline__ void transpose_item(const float* W, int N, bf16_t* WT, int nkt, int k0, int n0, int r0, int kbd, LAS float* scr, int lane) {
;     const size_t dst_off = ((size_t)(r0 >> 8) * nkt + kbd) * 16384 + (size_t)(r0 & 255) * 64;
;     const int l15 = lane & 15, lq = lane >> 4;
;     f32x4 v[16];
; #pragma unroll
;     for (int i = 0; i < 16; ++i) v[i] = *(const f32x4*)(W + (size_t)(k0 + 4 * i + lq) * N + n0 + 4 * l15);
; #pragma unroll
;     for (int i = 0; i < 16; ++i) { LAS float* d = scr + (4 * i + lq) * 65 + 4 * l15; d[0] = v[i][0]; d[1] = v[i][1]; d[2] = v[i][2]; d[3] = v[i][3]; }
; __device__ __forceinline__ void phase_convert_late(const Params& p, LAS float* scr, int cw, int NCW, int lane) {
;     ...
;         if (r < I3) { const int nb = r % 64, kb = r / 64; transpose_item(p.in[16], 4096, (bf16_t*)(ws + WS_W_BS), 32, kb * 64, nb * 64, nb * 64, kb, scr, lane); continue; } r -= I3;
.LBB0_323:
	s_andn2_b64 vcc, exec, s[4:5]
	s_cbranch_vccnz .LBB0_325
	s_add_i32 s4, s35, 0xffffa500
	s_and_b32 s0, s4, 0xffffffc0
	s_and_b32 s5, s16, 0xfc0
	v_or_b32_e32 v0, s0, v3
	s_lshl_b32 s0, s5, 2
	v_or_b32_e32 v50, 4, v0
	v_mov_b32_e32 v51, v1
	v_or_b32_e32 v56, 8, v0
	v_mov_b32_e32 v57, v1
	v_or_b32_e32 v58, 12, v0
	v_mov_b32_e32 v59, v1
	v_or_b32_e32 v64, 16, v0
	v_mov_b32_e32 v65, v1
	v_or_b32_e32 v66, 20, v0
	v_mov_b32_e32 v67, v1
	v_or_b32_e32 v72, 24, v0
	v_mov_b32_e32 v73, v1
	v_or_b32_e32 v74, 28, v0
	v_mov_b32_e32 v75, v1
	v_or_b32_e32 v80, 32, v0
	v_mov_b32_e32 v81, v1
	v_or_b32_e32 v82, 36, v0
	v_mov_b32_e32 v83, v1
	v_lshl_add_u64 v[108:109], v[24:25], 0, s[0:1]
	v_lshlrev_b64 v[48:49], 14, v[0:1]
	v_lshlrev_b64 v[50:51], 14, v[50:51]
	v_lshlrev_b64 v[56:57], 14, v[56:57]
	v_lshlrev_b64 v[58:59], 14, v[58:59]
	v_lshlrev_b64 v[64:65], 14, v[64:65]
	v_lshlrev_b64 v[66:67], 14, v[66:67]
	v_lshlrev_b64 v[72:73], 14, v[72:73]
	v_lshlrev_b64 v[74:75], 14, v[74:75]
	v_lshlrev_b64 v[80:81], 14, v[80:81]
	v_lshlrev_b64 v[82:83], 14, v[82:83]
	v_or_b32_e32 v88, 40, v0
	v_mov_b32_e32 v89, v1
	v_or_b32_e32 v90, 44, v0
	v_mov_b32_e32 v91, v1
	v_lshl_add_u64 v[48:49], v[108:109], 0, v[48:49]
	v_lshl_add_u64 v[52:53], v[108:109], 0, v[50:51]
	v_lshl_add_u64 v[56:57], v[108:109], 0, v[56:57]
	v_lshl_add_u64 v[60:61], v[108:109], 0, v[58:59]
	v_lshl_add_u64 v[64:65], v[108:109], 0, v[64:65]
	v_lshl_add_u64 v[68:69], v[108:109], 0, v[66:67]
	v_lshl_add_u64 v[72:73], v[108:109], 0, v[72:73]
	v_lshl_add_u64 v[76:77], v[108:109], 0, v[74:75]
	v_lshl_add_u64 v[80:81], v[108:109], 0, v[80:81]
	v_lshl_add_u64 v[84:85], v[108:109], 0, v[82:83]
	v_lshlrev_b64 v[88:89], 14, v[88:89]
	v_lshlrev_b64 v[90:91], 14, v[90:91]
	global_load_dwordx4 v[48:51], v[48:49], off nt
	s_nop 0
	global_load_dwordx4 v[52:55], v[52:53], off nt
	s_nop 0
	global_load_dwordx4 v[56:59], v[56:57], off nt
	s_nop 0
	global_load_dwordx4 v[60:63], v[60:61], off nt
	s_nop 0
	global_load_dwordx4 v[64:67], v[64:65], off nt
	s_nop 0
	global_load_dwordx4 v[68:71], v[68:69], off nt
	s_nop 0
	global_load_dwordx4 v[72:75], v[72:73], off nt
	s_nop 0
	global_load_dwordx4 v[76:79], v[76:77], off nt
	s_nop 0
	global_load_dwordx4 v[80:83], v[80:81], off nt
	s_nop 0
	global_load_dwordx4 v[84:87], v[84:85], off nt
	v_lshl_add_u64 v[88:89], v[108:109], 0, v[88:89]
	v_lshl_add_u64 v[92:93], v[108:109], 0, v[90:91]
	global_load_dwordx4 v[88:91], v[88:89], off nt
	s_nop 0
	global_load_dwordx4 v[92:95], v[92:93], off nt
	v_or_b32_e32 v96, 48, v0
	v_mov_b32_e32 v97, v1
	v_lshlrev_b64 v[96:97], 14, v[96:97]
	v_lshl_add_u64 v[96:97], v[108:109], 0, v[96:97]
	v_or_b32_e32 v100, 52, v0
	v_mov_b32_e32 v101, v1
	global_load_dwordx4 v[96:99], v[96:97], off nt
	v_lshlrev_b64 v[100:101], 14, v[100:101]
	v_lshl_add_u64 v[100:101], v[108:109], 0, v[100:101]
	v_or_b32_e32 v104, 56, v0
	v_mov_b32_e32 v105, v1
	global_load_dwordx4 v[100:103], v[100:101], off nt
	v_lshlrev_b64 v[104:105], 14, v[104:105]
	v_lshl_add_u64 v[104:105], v[108:109], 0, v[104:105]
	v_or_b32_e32 v0, 60, v0
	global_load_dwordx4 v[104:107], v[104:105], off nt
	v_lshlrev_b64 v[110:111], 14, v[0:1]
	v_lshl_add_u64 v[108:109], v[108:109], 0, v[110:111]
	global_load_dwordx4 v[108:111], v[108:109], off nt
	v_add_u32_e32 v0, 0xf0a0, v5
	s_lshr_b32 s0, s4, 6
	s_and_b32 s4, s20, 0x3000
	s_and_b32 s5, s26, 0x1e0
	s_add_i32 s0, s5, s0
	s_lshl_b32 s4, s4, 1
	s_add_u32 s33, s11, s4
	v_add_u32_e32 v31, 0xc800, v9
	s_addc_u32 s62, s14, 0
	s_waitcnt vmcnt(15)
	ds_write2_b32 v7, v48, v49 offset1:1
	ds_write2_b32 v11, v50, v51 offset1:1
	s_waitcnt vmcnt(14)
	ds_write2_b32 v13, v52, v53 offset1:1
	ds_write2_b32 v15, v54, v55 offset1:1
	s_waitcnt vmcnt(13)
	ds_write2_b32 v17, v56, v57 offset1:1
	ds_write2_b32 v19, v58, v59 offset1:1
	s_waitcnt vmcnt(12)
	ds_write2_b32 v32, v60, v61 offset1:1
	ds_write2_b32 v33, v62, v63 offset1:1
	s_waitcnt vmcnt(11)
	ds_write2_b32 v34, v64, v65 offset1:1
	ds_write2_b32 v36, v66, v67 offset1:1
	s_waitcnt vmcnt(10)
	ds_write2_b32 v37, v68, v69 offset1:1
	ds_write2_b32 v38, v70, v71 offset1:1
	s_waitcnt vmcnt(9)
	ds_write2_b32 v39, v72, v73 offset1:1
	ds_write2_b32 v40, v74, v75 offset1:1
	s_waitcnt vmcnt(8)
	ds_write2_b32 v41, v76, v77 offset1:1
	ds_write2_b32 v42, v78, v79 offset1:1
	s_waitcnt vmcnt(7)
	ds_write2_b32 v43, v80, v81 offset1:1
	ds_write2_b32 v44, v82, v83 offset1:1
	s_waitcnt vmcnt(6)
	ds_write2_b32 v45, v84, v85 offset1:1
	ds_write2_b32 v46, v86, v87 offset1:1
	s_lshl_b64 s[4:5], s[0:1], 15
	s_waitcnt vmcnt(5)
	ds_write2_b32 v0, v88, v89 offset1:1
	v_add_u32_e32 v0, 0xf0a8, v5
	ds_write2_b32 v0, v90, v91 offset1:1
	v_add_u32_e32 v0, 0xf4b0, v5
	s_waitcnt vmcnt(4)
	ds_write2_b32 v0, v92, v93 offset1:1
	v_add_u32_e32 v0, 0xf4b8, v5
	ds_write2_b32 v0, v94, v95 offset1:1
	v_add_u32_e32 v0, 0xf8c0, v5
	s_waitcnt vmcnt(3)
	ds_write2_b32 v0, v96, v97 offset1:1
	v_add_u32_e32 v0, 0xf8c8, v5
	ds_write2_b32 v0, v98, v99 offset1:1
	v_add_u32_e32 v0, 0xfcd0, v5
	s_add_u32 s4, s33, s4
	s_waitcnt vmcnt(2)
; #define LAS __attribute__((address_space(3)))
; __device__ __forceinline__ unsigned cvt_pk_bf16(float lo, float hi) { unsigned r; asm volatile("v_cvt_pk_bf16_f32 %0, %1, %2" : "=v"(r) : "v"(lo), "v"(hi)); return r; }
; #define LDS_WAIT() asm volatile("s_waitcnt lgkmcnt(0)" ::: "memory")
; __device__ __forceinline__ void transpose_item(const float* W, int N, bf16_t* WT, int nkt, int k0, int n0, int r0, int kbd, LAS float* scr, int lane) {
;     ...
;     for (int i = 0; i < 16; ++i) { LAS float* d = scr + (4 * i + lq) * 65 + 4 * l15; d[0] = v[i][0]; d[1] = v[i][1]; d[2] = v[i][2]; d[3] = v[i][3]; }
;     LDS_WAIT();
;     const int c = lane & 7;
; #pragma unroll
;     for (int j = 0; j < 8; ++j) { const int n = (lane >> 3) + 8 * j; const LAS float* s = scr + (8 * c) * 65 + n;
;         u32x4 o; o.x = cvt_pk_bf16(s[0], s[65]); o.y = cvt_pk_bf16(s[2 * 65], s[3 * 65]); o.z = cvt_pk_bf16(s[4 * 65], s[5 * 65]); o.w = cvt_pk_bf16(s[6 * 65], s[7 * 65]);
;         *(u32x4*)(WT + dst_off + (size_t)n * 64 + 8 * c) = o; }
;     LDS_WAIT();
; }
	ds_write2_b32 v0, v100, v101 offset1:1
	v_add_u32_e32 v0, 0xfcd8, v5
	ds_write2_b32 v0, v102, v103 offset1:1
	v_add_u32_e32 v0, 0x38e0, v7
	s_waitcnt vmcnt(1)
	ds_write2_b32 v0, v104, v105 offset1:1
	v_add_u32_e32 v0, 0x38e8, v7
	ds_write2_b32 v0, v106, v107 offset1:1
	v_add_u32_e32 v0, 0x3cf0, v7
	s_waitcnt vmcnt(0)
	ds_write2_b32 v0, v108, v109 offset1:1
	v_add_u32_e32 v0, 0x3cf8, v7
	ds_write2_b32 v0, v110, v111 offset1:1
	s_waitcnt lgkmcnt(0)
	ds_read2_b32 v[48:49], v31 offset1:65
	s_waitcnt lgkmcnt(0)
	v_cvt_pk_bf16_f32 v48, v48, v49
	ds_read2_b32 v[50:51], v31 offset0:130 offset1:195
	v_add_u32_e32 v47, 0xcc00, v9
	s_addc_u32 s5, s62, s5
	v_lshlrev_b32_e32 v0, 1, v2
	s_waitcnt lgkmcnt(0)
	v_cvt_pk_bf16_f32 v49, v50, v51
	ds_read2_b32 v[50:51], v47 offset0:4 offset1:69
	v_lshl_add_u64 v[54:55], s[4:5], 0, v[0:1]
	v_lshlrev_b32_e32 v0, 1, v4
	s_waitcnt lgkmcnt(0)
	v_cvt_pk_bf16_f32 v50, v50, v51
	ds_read2_b32 v[52:53], v47 offset0:134 offset1:199
	s_waitcnt lgkmcnt(0)
	v_cvt_pk_bf16_f32 v51, v52, v53
	v_lshl_add_u64 v[56:57], v[54:55], 0, v[0:1]
	ds_read2_b32 v[52:53], v31 offset0:8 offset1:73
	global_store_dwordx4 v[56:57], v[48:51], off
	v_lshlrev_b32_e32 v0, 1, v6
	v_lshl_add_u64 v[56:57], v[54:55], 0, v[0:1]
	s_waitcnt lgkmcnt(0)
	v_cvt_pk_bf16_f32 v48, v52, v53
	ds_read2_b32 v[50:51], v31 offset0:138 offset1:203
	s_waitcnt lgkmcnt(0)
	v_cvt_pk_bf16_f32 v49, v50, v51
	ds_read2_b32 v[50:51], v47 offset0:12 offset1:77
	s_waitcnt lgkmcnt(0)
	v_cvt_pk_bf16_f32 v50, v50, v51
	ds_read2_b32 v[52:53], v47 offset0:142 offset1:207
	s_waitcnt lgkmcnt(0)
	v_cvt_pk_bf16_f32 v51, v52, v53
	ds_read2_b32 v[52:53], v31 offset0:16 offset1:81
	global_store_dwordx4 v[56:57], v[48:51], off
	v_lshlrev_b32_e32 v0, 1, v8
	v_lshl_add_u64 v[56:57], v[54:55], 0, v[0:1]
	s_waitcnt lgkmcnt(0)
	v_cvt_pk_bf16_f32 v48, v52, v53
	ds_read2_b32 v[50:51], v31 offset0:146 offset1:211
	s_waitcnt lgkmcnt(0)
	v_cvt_pk_bf16_f32 v49, v50, v51
	ds_read2_b32 v[50:51], v47 offset0:20 offset1:85
	s_waitcnt lgkmcnt(0)
	v_cvt_pk_bf16_f32 v50, v50, v51
	ds_read2_b32 v[52:53], v47 offset0:150 offset1:215
	s_waitcnt lgkmcnt(0)
	v_cvt_pk_bf16_f32 v51, v52, v53
	ds_read2_b32 v[52:53], v31 offset0:24 offset1:89
	global_store_dwordx4 v[56:57], v[48:51], off
	v_lshlrev_b32_e32 v0, 1, v10
	v_lshl_add_u64 v[56:57], v[54:55], 0, v[0:1]
	s_waitcnt lgkmcnt(0)
	v_cvt_pk_bf16_f32 v48, v52, v53
	ds_read2_b32 v[50:51], v31 offset0:154 offset1:219
	s_waitcnt lgkmcnt(0)
	v_cvt_pk_bf16_f32 v49, v50, v51
	ds_read2_b32 v[50:51], v47 offset0:28 offset1:93
	s_waitcnt lgkmcnt(0)
	v_cvt_pk_bf16_f32 v50, v50, v51
	ds_read2_b32 v[52:53], v47 offset0:158 offset1:223
	s_waitcnt lgkmcnt(0)
	v_cvt_pk_bf16_f32 v51, v52, v53
	ds_read2_b32 v[52:53], v31 offset0:32 offset1:97
	global_store_dwordx4 v[56:57], v[48:51], off
	v_lshlrev_b32_e32 v0, 1, v12
	v_lshl_add_u64 v[56:57], v[54:55], 0, v[0:1]
	s_waitcnt lgkmcnt(0)
	v_cvt_pk_bf16_f32 v48, v52, v53
	ds_read2_b32 v[50:51], v31 offset0:162 offset1:227
	s_waitcnt lgkmcnt(0)
	v_cvt_pk_bf16_f32 v49, v50, v51
	ds_read2_b32 v[50:51], v47 offset0:36 offset1:101
	s_waitcnt lgkmcnt(0)
	v_cvt_pk_bf16_f32 v50, v50, v51
	ds_read2_b32 v[52:53], v47 offset0:166 offset1:231
	s_waitcnt lgkmcnt(0)
	v_cvt_pk_bf16_f32 v51, v52, v53
	ds_read2_b32 v[52:53], v31 offset0:40 offset1:105
	global_store_dwordx4 v[56:57], v[48:51], off
	v_lshlrev_b32_e32 v0, 1, v14
	v_lshl_add_u64 v[56:57], v[54:55], 0, v[0:1]
	s_waitcnt lgkmcnt(0)
	v_cvt_pk_bf16_f32 v48, v52, v53
	ds_read2_b32 v[50:51], v31 offset0:170 offset1:235
	s_waitcnt lgkmcnt(0)
	v_cvt_pk_bf16_f32 v49, v50, v51
	ds_read2_b32 v[50:51], v47 offset0:44 offset1:109
	s_waitcnt lgkmcnt(0)
	v_cvt_pk_bf16_f32 v50, v50, v51
	ds_read2_b32 v[52:53], v47 offset0:174 offset1:239
	s_waitcnt lgkmcnt(0)
	v_cvt_pk_bf16_f32 v51, v52, v53
	ds_read2_b32 v[52:53], v31 offset0:48 offset1:113
	global_store_dwordx4 v[56:57], v[48:51], off
	v_lshlrev_b32_e32 v0, 1, v16
	v_lshl_add_u64 v[56:57], v[54:55], 0, v[0:1]
	s_waitcnt lgkmcnt(0)
	v_cvt_pk_bf16_f32 v48, v52, v53
	ds_read2_b32 v[50:51], v31 offset0:178 offset1:243
	s_waitcnt lgkmcnt(0)
	v_cvt_pk_bf16_f32 v49, v50, v51
	ds_read2_b32 v[50:51], v47 offset0:52 offset1:117
	s_waitcnt lgkmcnt(0)
	v_cvt_pk_bf16_f32 v50, v50, v51
	ds_read2_b32 v[52:53], v47 offset0:182 offset1:247
	s_waitcnt lgkmcnt(0)
	v_cvt_pk_bf16_f32 v51, v52, v53
	ds_read2_b32 v[52:53], v31 offset0:56 offset1:121
	global_store_dwordx4 v[56:57], v[48:51], off
	v_lshlrev_b32_e32 v0, 1, v18
	s_waitcnt lgkmcnt(0)
	v_cvt_pk_bf16_f32 v48, v52, v53
	ds_read2_b32 v[50:51], v31 offset0:186 offset1:251
	s_waitcnt lgkmcnt(0)
	v_cvt_pk_bf16_f32 v49, v50, v51
	ds_read2_b32 v[50:51], v47 offset0:60 offset1:125
	s_waitcnt lgkmcnt(0)
	v_cvt_pk_bf16_f32 v50, v50, v51
	ds_read2_b32 v[52:53], v47 offset0:190 offset1:255
	s_waitcnt lgkmcnt(0)
	v_cvt_pk_bf16_f32 v51, v52, v53
	v_lshl_add_u64 v[52:53], v[54:55], 0, v[0:1]
	global_store_dwordx4 v[52:53], v[48:51], off
	s_waitcnt lgkmcnt(0)

; #define LAS __attribute__((address_space(3)))
; __device__ __forceinline__ void transpose_item(const float* W, int N, bf16_t* WT, int nkt, int k0, int n0, int r0, int kbd, LAS float* scr, int lane) {
;     const size_t dst_off = ((size_t)(r0 >> 8) * nkt + kbd) * 16384 + (size_t)(r0 & 255) * 64;
;     const int l15 = lane & 15, lq = lane >> 4;
;     f32x4 v[16];
; #pragma unroll
;     for (int i = 0; i < 16; ++i) v[i] = *(const f32x4*)(W + (size_t)(k0 + 4 * i + lq) * N + n0 + 4 * l15);
; #pragma unroll
;     for (int i = 0; i < 16; ++i) { LAS float* d = scr + (4 * i + lq) * 65 + 4 * l15; d[0] = v[i][0]; d[1] = v[i][1]; d[2] = v[i][2]; d[3] = v[i][3]; }
; __device__ __forceinline__ void phase_convert_late(const Params& p, LAS float* scr, int cw, int NCW, int lane) {
;     ...
;         if (r < I2) { const int g = r >> 6, q = r & 63, nb = q & 7, kb = q >> 3; transpose_item(p.in[13] + (size_t)g * 512 * 512, 512, (bf16_t*)(ws + WS_W_POOL), 32, kb * 64, nb * 64, nb * 64, g * 8 + kb, scr, lane); continue; } r -= I2;
.LBB0_326:
	s_andn2_b64 vcc, exec, s[4:5]
	s_cbranch_vccnz .LBB0_328
	s_add_i32 s0, s35, 0xffffa600
	s_lshr_b32 s0, s0, 6
	s_bfe_u32 s33, s35, 0x30003
	s_lshl_b64 s[4:5], s[0:1], 20
	s_add_u32 s4, s46, s4
	s_addc_u32 s5, s47, s5
	s_and_b32 s62, s16, 0x1c0
	s_lshl_b32 s0, s0, 3
	s_and_b32 s63, s20, 0x3000
	s_lshl_b32 s62, s62, 2
	s_add_u32 s4, s4, s62
	s_addc_u32 s5, s5, 0
	v_mov_b32_e32 v31, v1
	v_lshl_add_u64 v[48:49], s[4:5], 0, v[30:31]
	v_lshl_or_b32 v0, s33, 17, v35
	v_lshl_add_u64 v[108:109], v[48:49], 0, v[0:1]
	v_add_co_u32_e32 v52, vcc, s43, v108
	v_add_u32_e32 v0, 0xf0a0, v5
	s_nop 0
	v_addc_co_u32_e32 v53, vcc, 0, v109, vcc
	v_add_co_u32_e32 v56, vcc, s61, v108
	global_load_dwordx4 v[48:51], v[108:109], off nt
	s_nop 0
	global_load_dwordx4 v[52:55], v[52:53], off nt
	v_addc_co_u32_e32 v57, vcc, 0, v109, vcc
	v_add_co_u32_e32 v60, vcc, s42, v108
	s_and_b32 s4, s26, 32
	s_nop 0
	v_addc_co_u32_e32 v61, vcc, 0, v109, vcc
	v_add_co_u32_e32 v64, vcc, s66, v108
	global_load_dwordx4 v[56:59], v[56:57], off nt
	s_nop 0
	global_load_dwordx4 v[60:63], v[60:61], off nt
	v_addc_co_u32_e32 v65, vcc, 0, v109, vcc
	v_add_co_u32_e32 v68, vcc, s67, v108
	s_or_b32 s4, s4, s33
	s_nop 0
	v_addc_co_u32_e32 v69, vcc, 0, v109, vcc
	v_add_co_u32_e32 v72, vcc, s68, v108
	global_load_dwordx4 v[64:67], v[64:65], off nt
	s_nop 0
	global_load_dwordx4 v[68:71], v[68:69], off nt
	v_addc_co_u32_e32 v73, vcc, 0, v109, vcc
	v_add_co_u32_e32 v76, vcc, s69, v108
	s_add_i32 s0, s4, s0
	s_nop 0
	v_addc_co_u32_e32 v77, vcc, 0, v109, vcc
	v_add_co_u32_e32 v80, vcc, s70, v108
	global_load_dwordx4 v[72:75], v[72:73], off nt
	s_nop 0
	global_load_dwordx4 v[76:79], v[76:77], off nt
	v_addc_co_u32_e32 v81, vcc, 0, v109, vcc
	v_add_co_u32_e32 v84, vcc, s71, v108
	s_lshl_b32 s4, s63, 1
	s_nop 0
	v_addc_co_u32_e32 v85, vcc, 0, v109, vcc
	v_add_co_u32_e32 v88, vcc, s72, v108
	global_load_dwordx4 v[80:83], v[80:81], off nt
	s_nop 0
	global_load_dwordx4 v[84:87], v[84:85], off nt
	v_addc_co_u32_e32 v89, vcc, 0, v109, vcc
	v_add_co_u32_e32 v92, vcc, s73, v108
	s_add_u32 s33, s15, s4
	s_nop 0
	v_addc_co_u32_e32 v93, vcc, 0, v109, vcc
	global_load_dwordx4 v[88:91], v[88:89], off nt
	s_nop 0
	global_load_dwordx4 v[92:95], v[92:93], off nt
	v_add_co_u32_e32 v96, vcc, s74, v108
	v_add_u32_e32 v31, 0xc800, v9
	s_nop 0
	v_addc_co_u32_e32 v97, vcc, 0, v109, vcc
	global_load_dwordx4 v[96:99], v[96:97], off nt
	v_add_co_u32_e32 v100, vcc, s75, v108
	s_addc_u32 s62, s36, 0
	s_nop 0
	v_addc_co_u32_e32 v101, vcc, 0, v109, vcc
	global_load_dwordx4 v[100:103], v[100:101], off nt
	v_add_co_u32_e32 v104, vcc, s76, v108
	s_lshl_b64 s[4:5], s[0:1], 15
	s_nop 0
	v_addc_co_u32_e32 v105, vcc, 0, v109, vcc
	global_load_dwordx4 v[104:107], v[104:105], off nt
	v_add_co_u32_e32 v108, vcc, s77, v108
	s_add_u32 s4, s33, s4
	s_nop 0
	v_addc_co_u32_e32 v109, vcc, 0, v109, vcc
	global_load_dwordx4 v[108:111], v[108:109], off nt
	v_add_u32_e32 v47, 0xcc00, v9
	s_addc_u32 s5, s62, s5
	s_waitcnt vmcnt(15)
	ds_write2_b32 v7, v48, v49 offset1:1
	ds_write2_b32 v11, v50, v51 offset1:1
	s_waitcnt vmcnt(14)
	ds_write2_b32 v13, v52, v53 offset1:1
	ds_write2_b32 v15, v54, v55 offset1:1
	s_waitcnt vmcnt(13)
	ds_write2_b32 v17, v56, v57 offset1:1
	ds_write2_b32 v19, v58, v59 offset1:1
	s_waitcnt vmcnt(12)
	ds_write2_b32 v32, v60, v61 offset1:1
	ds_write2_b32 v33, v62, v63 offset1:1
	s_waitcnt vmcnt(11)
	ds_write2_b32 v34, v64, v65 offset1:1
	ds_write2_b32 v36, v66, v67 offset1:1
	s_waitcnt vmcnt(10)
	ds_write2_b32 v37, v68, v69 offset1:1
	ds_write2_b32 v38, v70, v71 offset1:1
	s_waitcnt vmcnt(9)
	ds_write2_b32 v39, v72, v73 offset1:1
	ds_write2_b32 v40, v74, v75 offset1:1
	s_waitcnt vmcnt(8)
	ds_write2_b32 v41, v76, v77 offset1:1
	ds_write2_b32 v42, v78, v79 offset1:1
	s_waitcnt vmcnt(7)
	ds_write2_b32 v43, v80, v81 offset1:1
	ds_write2_b32 v44, v82, v83 offset1:1
	s_waitcnt vmcnt(6)
	ds_write2_b32 v45, v84, v85 offset1:1
	ds_write2_b32 v46, v86, v87 offset1:1
	s_waitcnt vmcnt(5)
	ds_write2_b32 v0, v88, v89 offset1:1
	v_add_u32_e32 v0, 0xf0a8, v5
	ds_write2_b32 v0, v90, v91 offset1:1
	v_add_u32_e32 v0, 0xf4b0, v5
	s_waitcnt vmcnt(4)
	ds_write2_b32 v0, v92, v93 offset1:1
	v_add_u32_e32 v0, 0xf4b8, v5
	ds_write2_b32 v0, v94, v95 offset1:1
	v_add_u32_e32 v0, 0xf8c0, v5
	s_waitcnt vmcnt(3)
	ds_write2_b32 v0, v96, v97 offset1:1
	v_add_u32_e32 v0, 0xf8c8, v5
	ds_write2_b32 v0, v98, v99 offset1:1
	v_add_u32_e32 v0, 0xfcd0, v5
	s_waitcnt vmcnt(2)
	ds_write2_b32 v0, v100, v101 offset1:1
	v_add_u32_e32 v0, 0xfcd8, v5
	ds_write2_b32 v0, v102, v103 offset1:1
	v_add_u32_e32 v0, 0x38e0, v7
	s_waitcnt vmcnt(1)
; #define LAS __attribute__((address_space(3)))
; __device__ __forceinline__ unsigned cvt_pk_bf16(float lo, float hi) { unsigned r; asm volatile("v_cvt_pk_bf16_f32 %0, %1, %2" : "=v"(r) : "v"(lo), "v"(hi)); return r; }
; #define LDS_WAIT() asm volatile("s_waitcnt lgkmcnt(0)" ::: "memory")
; __device__ __forceinline__ void transpose_item(const float* W, int N, bf16_t* WT, int nkt, int k0, int n0, int r0, int kbd, LAS float* scr, int lane) {
;     ...
;     for (int i = 0; i < 16; ++i) { LAS float* d = scr + (4 * i + lq) * 65 + 4 * l15; d[0] = v[i][0]; d[1] = v[i][1]; d[2] = v[i][2]; d[3] = v[i][3]; }
;     LDS_WAIT();
;     const int c = lane & 7;
; #pragma unroll
;     for (int j = 0; j < 8; ++j) { const int n = (lane >> 3) + 8 * j; const LAS float* s = scr + (8 * c) * 65 + n;
;         u32x4 o; o.x = cvt_pk_bf16(s[0], s[65]); o.y = cvt_pk_bf16(s[2 * 65], s[3 * 65]); o.z = cvt_pk_bf16(s[4 * 65], s[5 * 65]); o.w = cvt_pk_bf16(s[6 * 65], s[7 * 65]);
;         *(u32x4*)(WT + dst_off + (size_t)n * 64 + 8 * c) = o; }
;     LDS_WAIT();
; }
	ds_write2_b32 v0, v104, v105 offset1:1
	v_add_u32_e32 v0, 0x38e8, v7
	ds_write2_b32 v0, v106, v107 offset1:1
	v_add_u32_e32 v0, 0x3cf0, v7
	s_waitcnt vmcnt(0)
	ds_write2_b32 v0, v108, v109 offset1:1
	v_add_u32_e32 v0, 0x3cf8, v7
	ds_write2_b32 v0, v110, v111 offset1:1
	s_waitcnt lgkmcnt(0)
	ds_read2_b32 v[48:49], v31 offset1:65
	s_waitcnt lgkmcnt(0)
	v_cvt_pk_bf16_f32 v48, v48, v49
	ds_read2_b32 v[50:51], v31 offset0:130 offset1:195
	v_lshlrev_b32_e32 v0, 1, v2
	s_waitcnt lgkmcnt(0)
	v_cvt_pk_bf16_f32 v49, v50, v51
	ds_read2_b32 v[50:51], v47 offset0:4 offset1:69
	v_lshl_add_u64 v[54:55], s[4:5], 0, v[0:1]
	v_lshlrev_b32_e32 v0, 1, v4
	s_waitcnt lgkmcnt(0)
	v_cvt_pk_bf16_f32 v50, v50, v51
	ds_read2_b32 v[52:53], v47 offset0:134 offset1:199
	s_waitcnt lgkmcnt(0)
	v_cvt_pk_bf16_f32 v51, v52, v53
	v_lshl_add_u64 v[56:57], v[54:55], 0, v[0:1]
	ds_read2_b32 v[52:53], v31 offset0:8 offset1:73
	global_store_dwordx4 v[56:57], v[48:51], off
	v_lshlrev_b32_e32 v0, 1, v6
	v_lshl_add_u64 v[56:57], v[54:55], 0, v[0:1]
	s_waitcnt lgkmcnt(0)
	v_cvt_pk_bf16_f32 v48, v52, v53
	ds_read2_b32 v[50:51], v31 offset0:138 offset1:203
	s_waitcnt lgkmcnt(0)
	v_cvt_pk_bf16_f32 v49, v50, v51
	ds_read2_b32 v[50:51], v47 offset0:12 offset1:77
	s_waitcnt lgkmcnt(0)
	v_cvt_pk_bf16_f32 v50, v50, v51
	ds_read2_b32 v[52:53], v47 offset0:142 offset1:207
	s_waitcnt lgkmcnt(0)
	v_cvt_pk_bf16_f32 v51, v52, v53
	ds_read2_b32 v[52:53], v31 offset0:16 offset1:81
	global_store_dwordx4 v[56:57], v[48:51], off
	v_lshlrev_b32_e32 v0, 1, v8
	v_lshl_add_u64 v[56:57], v[54:55], 0, v[0:1]
	s_waitcnt lgkmcnt(0)
	v_cvt_pk_bf16_f32 v48, v52, v53
	ds_read2_b32 v[50:51], v31 offset0:146 offset1:211
	s_waitcnt lgkmcnt(0)
	v_cvt_pk_bf16_f32 v49, v50, v51
	ds_read2_b32 v[50:51], v47 offset0:20 offset1:85
	s_waitcnt lgkmcnt(0)
	v_cvt_pk_bf16_f32 v50, v50, v51
	ds_read2_b32 v[52:53], v47 offset0:150 offset1:215
	s_waitcnt lgkmcnt(0)
	v_cvt_pk_bf16_f32 v51, v52, v53
	ds_read2_b32 v[52:53], v31 offset0:24 offset1:89
	global_store_dwordx4 v[56:57], v[48:51], off
	v_lshlrev_b32_e32 v0, 1, v10
	v_lshl_add_u64 v[56:57], v[54:55], 0, v[0:1]
	s_waitcnt lgkmcnt(0)
	v_cvt_pk_bf16_f32 v48, v52, v53
	ds_read2_b32 v[50:51], v31 offset0:154 offset1:219
	s_waitcnt lgkmcnt(0)
	v_cvt_pk_bf16_f32 v49, v50, v51
	ds_read2_b32 v[50:51], v47 offset0:28 offset1:93
	s_waitcnt lgkmcnt(0)
	v_cvt_pk_bf16_f32 v50, v50, v51
	ds_read2_b32 v[52:53], v47 offset0:158 offset1:223
	s_waitcnt lgkmcnt(0)
	v_cvt_pk_bf16_f32 v51, v52, v53
	ds_read2_b32 v[52:53], v31 offset0:32 offset1:97
	global_store_dwordx4 v[56:57], v[48:51], off
	v_lshlrev_b32_e32 v0, 1, v12
	v_lshl_add_u64 v[56:57], v[54:55], 0, v[0:1]
	s_waitcnt lgkmcnt(0)
	v_cvt_pk_bf16_f32 v48, v52, v53
	ds_read2_b32 v[50:51], v31 offset0:162 offset1:227
	s_waitcnt lgkmcnt(0)
	v_cvt_pk_bf16_f32 v49, v50, v51
	ds_read2_b32 v[50:51], v47 offset0:36 offset1:101
	s_waitcnt lgkmcnt(0)
	v_cvt_pk_bf16_f32 v50, v50, v51
	ds_read2_b32 v[52:53], v47 offset0:166 offset1:231
	s_waitcnt lgkmcnt(0)
	v_cvt_pk_bf16_f32 v51, v52, v53
	ds_read2_b32 v[52:53], v31 offset0:40 offset1:105
	global_store_dwordx4 v[56:57], v[48:51], off
	v_lshlrev_b32_e32 v0, 1, v14
	v_lshl_add_u64 v[56:57], v[54:55], 0, v[0:1]
	s_waitcnt lgkmcnt(0)
	v_cvt_pk_bf16_f32 v48, v52, v53
	ds_read2_b32 v[50:51], v31 offset0:170 offset1:235
	s_waitcnt lgkmcnt(0)
	v_cvt_pk_bf16_f32 v49, v50, v51
	ds_read2_b32 v[50:51], v47 offset0:44 offset1:109
	s_waitcnt lgkmcnt(0)
	v_cvt_pk_bf16_f32 v50, v50, v51
	ds_read2_b32 v[52:53], v47 offset0:174 offset1:239
	s_waitcnt lgkmcnt(0)
	v_cvt_pk_bf16_f32 v51, v52, v53
	ds_read2_b32 v[52:53], v31 offset0:48 offset1:113
	global_store_dwordx4 v[56:57], v[48:51], off
	v_lshlrev_b32_e32 v0, 1, v16
	v_lshl_add_u64 v[56:57], v[54:55], 0, v[0:1]
	s_waitcnt lgkmcnt(0)
	v_cvt_pk_bf16_f32 v48, v52, v53
	ds_read2_b32 v[50:51], v31 offset0:178 offset1:243
	s_waitcnt lgkmcnt(0)
	v_cvt_pk_bf16_f32 v49, v50, v51
	ds_read2_b32 v[50:51], v47 offset0:52 offset1:117
	s_waitcnt lgkmcnt(0)
	v_cvt_pk_bf16_f32 v50, v50, v51
	ds_read2_b32 v[52:53], v47 offset0:182 offset1:247
	s_waitcnt lgkmcnt(0)
	v_cvt_pk_bf16_f32 v51, v52, v53
	ds_read2_b32 v[52:53], v31 offset0:56 offset1:121
	global_store_dwordx4 v[56:57], v[48:51], off
	v_lshlrev_b32_e32 v0, 1, v18
	s_waitcnt lgkmcnt(0)
	v_cvt_pk_bf16_f32 v48, v52, v53
	ds_read2_b32 v[50:51], v31 offset0:186 offset1:251
	s_waitcnt lgkmcnt(0)
	v_cvt_pk_bf16_f32 v49, v50, v51
	ds_read2_b32 v[50:51], v47 offset0:60 offset1:125
	s_waitcnt lgkmcnt(0)
	v_cvt_pk_bf16_f32 v50, v50, v51
	ds_read2_b32 v[52:53], v47 offset0:190 offset1:255
	s_waitcnt lgkmcnt(0)
	v_cvt_pk_bf16_f32 v51, v52, v53
	v_lshl_add_u64 v[52:53], v[54:55], 0, v[0:1]
	global_store_dwordx4 v[52:53], v[48:51], off
	s_waitcnt lgkmcnt(0)

; #define LAS __attribute__((address_space(3)))
; __device__ __forceinline__ void transpose_item(const float* W, int N, bf16_t* WT, int nkt, int k0, int n0, int r0, int kbd, LAS float* scr, int lane) {
;     const size_t dst_off = ((size_t)(r0 >> 8) * nkt + kbd) * 16384 + (size_t)(r0 & 255) * 64;
;     const int l15 = lane & 15, lq = lane >> 4;
;     f32x4 v[16];
; #pragma unroll
;     for (int i = 0; i < 16; ++i) v[i] = *(const f32x4*)(W + (size_t)(k0 + 4 * i + lq) * N + n0 + 4 * l15);
; #pragma unroll
;     for (int i = 0; i < 16; ++i) { LAS float* d = scr + (4 * i + lq) * 65 + 4 * l15; d[0] = v[i][0]; d[1] = v[i][1]; d[2] = v[i][2]; d[3] = v[i][3]; }
; __device__ __forceinline__ void phase_convert_late(const Params& p, LAS float* scr, int cw, int NCW, int lane) {
;     ...
;         if (r < I1) { const int nb = r % 32, kb = r / 32; transpose_item(p.in[11], 2048, (bf16_t*)(ws + WS_W_GLU), 32, kb * 64, nb * 64, nb * 64, kb, scr, lane); continue; } r -= I1;
.LBB0_329:
	s_andn2_b64 vcc, exec, s[4:5]
	s_cbranch_vccnz .LBB0_331
	s_add_i32 s0, s35, 0xffffaa00
	s_lshr_b32 s4, s0, 5
	s_and_b32 s0, s16, 0x7c0
	v_lshl_or_b32 v0, s4, 6, v3
	s_lshl_b32 s0, s0, 2
	v_or_b32_e32 v50, 4, v0
	v_mov_b32_e32 v51, v1
	v_or_b32_e32 v56, 8, v0
	v_mov_b32_e32 v57, v1
	v_or_b32_e32 v58, 12, v0
	v_mov_b32_e32 v59, v1
	v_or_b32_e32 v64, 16, v0
	v_mov_b32_e32 v65, v1
	v_or_b32_e32 v66, 20, v0
	v_mov_b32_e32 v67, v1
	v_or_b32_e32 v72, 24, v0
	v_mov_b32_e32 v73, v1
	v_or_b32_e32 v74, 28, v0
	v_mov_b32_e32 v75, v1
	v_or_b32_e32 v80, 32, v0
	v_mov_b32_e32 v81, v1
	v_or_b32_e32 v82, 36, v0
	v_mov_b32_e32 v83, v1
	v_lshl_add_u64 v[108:109], v[26:27], 0, s[0:1]
	v_lshlrev_b64 v[48:49], 13, v[0:1]
	v_lshlrev_b64 v[50:51], 13, v[50:51]
	v_lshlrev_b64 v[56:57], 13, v[56:57]
	v_lshlrev_b64 v[58:59], 13, v[58:59]
	v_lshlrev_b64 v[64:65], 13, v[64:65]
	v_lshlrev_b64 v[66:67], 13, v[66:67]
	v_lshlrev_b64 v[72:73], 13, v[72:73]
	v_lshlrev_b64 v[74:75], 13, v[74:75]
	v_lshlrev_b64 v[80:81], 13, v[80:81]
	v_lshlrev_b64 v[82:83], 13, v[82:83]
	v_or_b32_e32 v88, 40, v0
	v_mov_b32_e32 v89, v1
	v_or_b32_e32 v90, 44, v0
	v_mov_b32_e32 v91, v1
	v_lshl_add_u64 v[48:49], v[108:109], 0, v[48:49]
	v_lshl_add_u64 v[52:53], v[108:109], 0, v[50:51]
	v_lshl_add_u64 v[56:57], v[108:109], 0, v[56:57]
	v_lshl_add_u64 v[60:61], v[108:109], 0, v[58:59]
	v_lshl_add_u64 v[64:65], v[108:109], 0, v[64:65]
	v_lshl_add_u64 v[68:69], v[108:109], 0, v[66:67]
	v_lshl_add_u64 v[72:73], v[108:109], 0, v[72:73]
	v_lshl_add_u64 v[76:77], v[108:109], 0, v[74:75]
	v_lshl_add_u64 v[80:81], v[108:109], 0, v[80:81]
	v_lshl_add_u64 v[84:85], v[108:109], 0, v[82:83]
	v_lshlrev_b64 v[88:89], 13, v[88:89]
	v_lshlrev_b64 v[90:91], 13, v[90:91]
	global_load_dwordx4 v[48:51], v[48:49], off nt
	s_nop 0
	global_load_dwordx4 v[52:55], v[52:53], off nt
	s_nop 0
	global_load_dwordx4 v[56:59], v[56:57], off nt
	s_nop 0
	global_load_dwordx4 v[60:63], v[60:61], off nt
	s_nop 0
	global_load_dwordx4 v[64:67], v[64:65], off nt
	s_nop 0
	global_load_dwordx4 v[68:71], v[68:69], off nt
	s_nop 0
	global_load_dwordx4 v[72:75], v[72:73], off nt
	s_nop 0
	global_load_dwordx4 v[76:79], v[76:77], off nt
	s_nop 0
	global_load_dwordx4 v[80:83], v[80:81], off nt
	s_nop 0
	global_load_dwordx4 v[84:87], v[84:85], off nt
	v_lshl_add_u64 v[88:89], v[108:109], 0, v[88:89]
	v_lshl_add_u64 v[92:93], v[108:109], 0, v[90:91]
	global_load_dwordx4 v[88:91], v[88:89], off nt
	s_nop 0
	global_load_dwordx4 v[92:95], v[92:93], off nt
	v_or_b32_e32 v96, 48, v0
	v_mov_b32_e32 v97, v1
	v_lshlrev_b64 v[96:97], 13, v[96:97]
	v_lshl_add_u64 v[96:97], v[108:109], 0, v[96:97]
	v_or_b32_e32 v100, 52, v0
	v_mov_b32_e32 v101, v1
	global_load_dwordx4 v[96:99], v[96:97], off nt
	v_lshlrev_b64 v[100:101], 13, v[100:101]
	v_lshl_add_u64 v[100:101], v[108:109], 0, v[100:101]
	v_or_b32_e32 v104, 56, v0
	v_mov_b32_e32 v105, v1
	global_load_dwordx4 v[100:103], v[100:101], off nt
	v_lshlrev_b64 v[104:105], 13, v[104:105]
	v_lshl_add_u64 v[104:105], v[108:109], 0, v[104:105]
	v_or_b32_e32 v0, 60, v0
	global_load_dwordx4 v[104:107], v[104:105], off nt
	v_lshlrev_b64 v[110:111], 13, v[0:1]
	v_lshl_add_u64 v[108:109], v[108:109], 0, v[110:111]
	global_load_dwordx4 v[108:111], v[108:109], off nt
	v_add_u32_e32 v0, 0xf0a0, v5
	s_and_b32 s5, s20, 0x3000
	s_and_b32 s0, s26, 0xe0
	s_add_i32 s0, s0, s4
	s_lshl_b32 s4, s5, 1
	s_add_u32 s33, s37, s4
	v_add_u32_e32 v31, 0xc800, v9
	s_addc_u32 s62, s38, 0
	s_lshl_b64 s[4:5], s[0:1], 15
	s_waitcnt vmcnt(15)
	ds_write2_b32 v7, v48, v49 offset1:1
	ds_write2_b32 v11, v50, v51 offset1:1
	s_waitcnt vmcnt(14)
	ds_write2_b32 v13, v52, v53 offset1:1
	ds_write2_b32 v15, v54, v55 offset1:1
	s_waitcnt vmcnt(13)
	ds_write2_b32 v17, v56, v57 offset1:1
	ds_write2_b32 v19, v58, v59 offset1:1
	s_waitcnt vmcnt(12)
	ds_write2_b32 v32, v60, v61 offset1:1
	ds_write2_b32 v33, v62, v63 offset1:1
	s_waitcnt vmcnt(11)
	ds_write2_b32 v34, v64, v65 offset1:1
	ds_write2_b32 v36, v66, v67 offset1:1
	s_waitcnt vmcnt(10)
	ds_write2_b32 v37, v68, v69 offset1:1
	ds_write2_b32 v38, v70, v71 offset1:1
	s_waitcnt vmcnt(9)
	ds_write2_b32 v39, v72, v73 offset1:1
	ds_write2_b32 v40, v74, v75 offset1:1
	s_waitcnt vmcnt(8)
	ds_write2_b32 v41, v76, v77 offset1:1
	ds_write2_b32 v42, v78, v79 offset1:1
	s_waitcnt vmcnt(7)
	ds_write2_b32 v43, v80, v81 offset1:1
	ds_write2_b32 v44, v82, v83 offset1:1
	s_waitcnt vmcnt(6)
	ds_write2_b32 v45, v84, v85 offset1:1
	ds_write2_b32 v46, v86, v87 offset1:1
	s_add_u32 s4, s33, s4
	s_waitcnt vmcnt(5)
	ds_write2_b32 v0, v88, v89 offset1:1
	v_add_u32_e32 v0, 0xf0a8, v5
	ds_write2_b32 v0, v90, v91 offset1:1
	v_add_u32_e32 v0, 0xf4b0, v5
	s_waitcnt vmcnt(4)
	ds_write2_b32 v0, v92, v93 offset1:1
	v_add_u32_e32 v0, 0xf4b8, v5
	ds_write2_b32 v0, v94, v95 offset1:1
	v_add_u32_e32 v0, 0xf8c0, v5
	s_waitcnt vmcnt(3)
	ds_write2_b32 v0, v96, v97 offset1:1
	v_add_u32_e32 v0, 0xf8c8, v5
	ds_write2_b32 v0, v98, v99 offset1:1
	v_add_u32_e32 v0, 0xfcd0, v5
	v_add_u32_e32 v47, 0xcc00, v9
	s_waitcnt vmcnt(2)
; #define LAS __attribute__((address_space(3)))
; __device__ __forceinline__ unsigned cvt_pk_bf16(float lo, float hi) { unsigned r; asm volatile("v_cvt_pk_bf16_f32 %0, %1, %2" : "=v"(r) : "v"(lo), "v"(hi)); return r; }
; #define LDS_WAIT() asm volatile("s_waitcnt lgkmcnt(0)" ::: "memory")
; __device__ __forceinline__ void transpose_item(const float* W, int N, bf16_t* WT, int nkt, int k0, int n0, int r0, int kbd, LAS float* scr, int lane) {
;     ...
;     for (int i = 0; i < 16; ++i) { LAS float* d = scr + (4 * i + lq) * 65 + 4 * l15; d[0] = v[i][0]; d[1] = v[i][1]; d[2] = v[i][2]; d[3] = v[i][3]; }
;     LDS_WAIT();
;     const int c = lane & 7;
; #pragma unroll
;     for (int j = 0; j < 8; ++j) { const int n = (lane >> 3) + 8 * j; const LAS float* s = scr + (8 * c) * 65 + n;
;         u32x4 o; o.x = cvt_pk_bf16(s[0], s[65]); o.y = cvt_pk_bf16(s[2 * 65], s[3 * 65]); o.z = cvt_pk_bf16(s[4 * 65], s[5 * 65]); o.w = cvt_pk_bf16(s[6 * 65], s[7 * 65]);
;         *(u32x4*)(WT + dst_off + (size_t)n * 64 + 8 * c) = o; }
;     LDS_WAIT();
; }
	ds_write2_b32 v0, v100, v101 offset1:1
	v_add_u32_e32 v0, 0xfcd8, v5
	ds_write2_b32 v0, v102, v103 offset1:1
	v_add_u32_e32 v0, 0x38e0, v7
	s_waitcnt vmcnt(1)
	ds_write2_b32 v0, v104, v105 offset1:1
	v_add_u32_e32 v0, 0x38e8, v7
	ds_write2_b32 v0, v106, v107 offset1:1
	v_add_u32_e32 v0, 0x3cf0, v7
	s_waitcnt vmcnt(0)
	ds_write2_b32 v0, v108, v109 offset1:1
	v_add_u32_e32 v0, 0x3cf8, v7
	ds_write2_b32 v0, v110, v111 offset1:1
	s_waitcnt lgkmcnt(0)
	ds_read2_b32 v[48:49], v31 offset1:65
	s_waitcnt lgkmcnt(0)
	v_cvt_pk_bf16_f32 v48, v48, v49
	ds_read2_b32 v[50:51], v31 offset0:130 offset1:195
	s_addc_u32 s5, s62, s5
	v_lshlrev_b32_e32 v0, 1, v2
	s_waitcnt lgkmcnt(0)
	v_cvt_pk_bf16_f32 v49, v50, v51
	ds_read2_b32 v[50:51], v47 offset0:4 offset1:69
	v_lshl_add_u64 v[54:55], s[4:5], 0, v[0:1]
	v_lshlrev_b32_e32 v0, 1, v4
	s_waitcnt lgkmcnt(0)
	v_cvt_pk_bf16_f32 v50, v50, v51
	ds_read2_b32 v[52:53], v47 offset0:134 offset1:199
	s_waitcnt lgkmcnt(0)
	v_cvt_pk_bf16_f32 v51, v52, v53
	v_lshl_add_u64 v[56:57], v[54:55], 0, v[0:1]
	ds_read2_b32 v[52:53], v31 offset0:8 offset1:73
	global_store_dwordx4 v[56:57], v[48:51], off
	v_lshlrev_b32_e32 v0, 1, v6
	v_lshl_add_u64 v[56:57], v[54:55], 0, v[0:1]
	s_waitcnt lgkmcnt(0)
	v_cvt_pk_bf16_f32 v48, v52, v53
	ds_read2_b32 v[50:51], v31 offset0:138 offset1:203
	s_waitcnt lgkmcnt(0)
	v_cvt_pk_bf16_f32 v49, v50, v51
	ds_read2_b32 v[50:51], v47 offset0:12 offset1:77
	s_waitcnt lgkmcnt(0)
	v_cvt_pk_bf16_f32 v50, v50, v51
	ds_read2_b32 v[52:53], v47 offset0:142 offset1:207
	s_waitcnt lgkmcnt(0)
	v_cvt_pk_bf16_f32 v51, v52, v53
	ds_read2_b32 v[52:53], v31 offset0:16 offset1:81
	global_store_dwordx4 v[56:57], v[48:51], off
	v_lshlrev_b32_e32 v0, 1, v8
	v_lshl_add_u64 v[56:57], v[54:55], 0, v[0:1]
	s_waitcnt lgkmcnt(0)
	v_cvt_pk_bf16_f32 v48, v52, v53
	ds_read2_b32 v[50:51], v31 offset0:146 offset1:211
	s_waitcnt lgkmcnt(0)
	v_cvt_pk_bf16_f32 v49, v50, v51
	ds_read2_b32 v[50:51], v47 offset0:20 offset1:85
	s_waitcnt lgkmcnt(0)
	v_cvt_pk_bf16_f32 v50, v50, v51
	ds_read2_b32 v[52:53], v47 offset0:150 offset1:215
	s_waitcnt lgkmcnt(0)
	v_cvt_pk_bf16_f32 v51, v52, v53
	ds_read2_b32 v[52:53], v31 offset0:24 offset1:89
	global_store_dwordx4 v[56:57], v[48:51], off
	v_lshlrev_b32_e32 v0, 1, v10
	v_lshl_add_u64 v[56:57], v[54:55], 0, v[0:1]
	s_waitcnt lgkmcnt(0)
	v_cvt_pk_bf16_f32 v48, v52, v53
	ds_read2_b32 v[50:51], v31 offset0:154 offset1:219
	s_waitcnt lgkmcnt(0)
	v_cvt_pk_bf16_f32 v49, v50, v51
	ds_read2_b32 v[50:51], v47 offset0:28 offset1:93
	s_waitcnt lgkmcnt(0)
	v_cvt_pk_bf16_f32 v50, v50, v51
	ds_read2_b32 v[52:53], v47 offset0:158 offset1:223
	s_waitcnt lgkmcnt(0)
	v_cvt_pk_bf16_f32 v51, v52, v53
	ds_read2_b32 v[52:53], v31 offset0:32 offset1:97
	global_store_dwordx4 v[56:57], v[48:51], off
	v_lshlrev_b32_e32 v0, 1, v12
	v_lshl_add_u64 v[56:57], v[54:55], 0, v[0:1]
	s_waitcnt lgkmcnt(0)
	v_cvt_pk_bf16_f32 v48, v52, v53
	ds_read2_b32 v[50:51], v31 offset0:162 offset1:227
	s_waitcnt lgkmcnt(0)
	v_cvt_pk_bf16_f32 v49, v50, v51
	ds_read2_b32 v[50:51], v47 offset0:36 offset1:101
	s_waitcnt lgkmcnt(0)
	v_cvt_pk_bf16_f32 v50, v50, v51
	ds_read2_b32 v[52:53], v47 offset0:166 offset1:231
	s_waitcnt lgkmcnt(0)
	v_cvt_pk_bf16_f32 v51, v52, v53
	ds_read2_b32 v[52:53], v31 offset0:40 offset1:105
	global_store_dwordx4 v[56:57], v[48:51], off
	v_lshlrev_b32_e32 v0, 1, v14
	v_lshl_add_u64 v[56:57], v[54:55], 0, v[0:1]
	s_waitcnt lgkmcnt(0)
	v_cvt_pk_bf16_f32 v48, v52, v53
	ds_read2_b32 v[50:51], v31 offset0:170 offset1:235
	s_waitcnt lgkmcnt(0)
	v_cvt_pk_bf16_f32 v49, v50, v51
	ds_read2_b32 v[50:51], v47 offset0:44 offset1:109
	s_waitcnt lgkmcnt(0)
	v_cvt_pk_bf16_f32 v50, v50, v51
	ds_read2_b32 v[52:53], v47 offset0:174 offset1:239
	s_waitcnt lgkmcnt(0)
	v_cvt_pk_bf16_f32 v51, v52, v53
	ds_read2_b32 v[52:53], v31 offset0:48 offset1:113
	global_store_dwordx4 v[56:57], v[48:51], off
	v_lshlrev_b32_e32 v0, 1, v16
	v_lshl_add_u64 v[56:57], v[54:55], 0, v[0:1]
	s_waitcnt lgkmcnt(0)
	v_cvt_pk_bf16_f32 v48, v52, v53
	ds_read2_b32 v[50:51], v31 offset0:178 offset1:243
	s_waitcnt lgkmcnt(0)
	v_cvt_pk_bf16_f32 v49, v50, v51
	ds_read2_b32 v[50:51], v47 offset0:52 offset1:117
	s_waitcnt lgkmcnt(0)
	v_cvt_pk_bf16_f32 v50, v50, v51
	ds_read2_b32 v[52:53], v47 offset0:182 offset1:247
	s_waitcnt lgkmcnt(0)
	v_cvt_pk_bf16_f32 v51, v52, v53
	ds_read2_b32 v[52:53], v31 offset0:56 offset1:121
	global_store_dwordx4 v[56:57], v[48:51], off
	v_lshlrev_b32_e32 v0, 1, v18
	s_waitcnt lgkmcnt(0)
	v_cvt_pk_bf16_f32 v48, v52, v53
	ds_read2_b32 v[50:51], v31 offset0:186 offset1:251
	s_waitcnt lgkmcnt(0)
	v_cvt_pk_bf16_f32 v49, v50, v51
	ds_read2_b32 v[50:51], v47 offset0:60 offset1:125
	s_waitcnt lgkmcnt(0)
	v_cvt_pk_bf16_f32 v50, v50, v51
	ds_read2_b32 v[52:53], v47 offset0:190 offset1:255
	s_waitcnt lgkmcnt(0)
	v_cvt_pk_bf16_f32 v51, v52, v53
	v_lshl_add_u64 v[52:53], v[54:55], 0, v[0:1]
	global_store_dwordx4 v[52:53], v[48:51], off
	s_waitcnt lgkmcnt(0)

; #define LAS __attribute__((address_space(3)))
; __device__ __forceinline__ void transpose_item(const float* W, int N, bf16_t* WT, int nkt, int k0, int n0, int r0, int kbd, LAS float* scr, int lane) {
;     const size_t dst_off = ((size_t)(r0 >> 8) * nkt + kbd) * 16384 + (size_t)(r0 & 255) * 64;
;     const int l15 = lane & 15, lq = lane >> 4;
;     f32x4 v[16];
; #pragma unroll
;     for (int i = 0; i < 16; ++i) v[i] = *(const f32x4*)(W + (size_t)(k0 + 4 * i + lq) * N + n0 + 4 * l15);
; #pragma unroll
;     for (int i = 0; i < 16; ++i) { LAS float* d = scr + (4 * i + lq) * 65 + 4 * l15; d[0] = v[i][0]; d[1] = v[i][1]; d[2] = v[i][2]; d[3] = v[i][3]; }
; __device__ __forceinline__ void phase_convert_late(const Params& p, LAS float* scr, int cw, int NCW, int lane) {
;     ...
;         if (r < I6) { const int nb = r % 344, kb = r / 344; const int n0 = nb * 64; const int nn = n0 < FF ? n0 : n0 - FF; const int r0 = (nn >> 7) * 256 + (n0 < FF ? 0 : 128) + (nn & 127);
;             transpose_item(p.in[21], FF2, (bf16_t*)(ws + WS_W_UP), 64, kb * 64, n0, r0, kb, scr, lane); continue; } r -= I6;
.LBB0_332:
	s_andn2_b64 vcc, exec, s[4:5]
	s_cbranch_vccnz .LBB0_313
	s_mul_hi_i32 s0, s35, 0x2fa0be83
	s_lshr_b32 s4, s0, 31
	s_ashr_i32 s0, s0, 6
	s_add_i32 s4, s0, s4
	s_mul_i32 s5, s4, 0xffffaa00
	s_mul_i32 s0, s4, 0xfffffea8
	s_add_i32 s62, s16, s5
	s_add_i32 s0, s35, s0
	s_add_i32 s5, s62, 0xffffd500
	s_cmpk_lt_i32 s0, 0xac
	s_cselect_b32 s0, s62, s5
	s_cselect_b32 s5, 0, 0xac
	v_lshl_or_b32 v0, s4, 6, v3
	s_ashr_i32 s63, s62, 31
	v_lshl_add_u64 v[108:109], s[62:63], 2, v[28:29]
	v_or_b32_e32 v31, 4, v0
	v_mad_i64_i32 v[52:53], s[62:63], v31, s78, v[108:109]
	v_or_b32_e32 v31, 8, v0
	v_mad_i64_i32 v[56:57], s[62:63], v31, s78, v[108:109]
	v_or_b32_e32 v31, 12, v0
	v_mad_i64_i32 v[60:61], s[62:63], v31, s78, v[108:109]
	v_or_b32_e32 v31, 16, v0
	v_mad_i64_i32 v[64:65], s[62:63], v31, s78, v[108:109]
	v_or_b32_e32 v31, 20, v0
	v_mad_i64_i32 v[68:69], s[62:63], v31, s78, v[108:109]
	v_or_b32_e32 v31, 24, v0
	v_mad_i64_i32 v[72:73], s[62:63], v31, s78, v[108:109]
	v_or_b32_e32 v31, 28, v0
	v_mad_i64_i32 v[76:77], s[62:63], v31, s78, v[108:109]
	v_or_b32_e32 v31, 32, v0
	v_mad_i64_i32 v[80:81], s[62:63], v31, s78, v[108:109]
	v_or_b32_e32 v31, 36, v0
	v_mad_i64_i32 v[84:85], s[62:63], v31, s78, v[108:109]
	v_or_b32_e32 v31, 40, v0
	v_mad_i64_i32 v[48:49], s[62:63], v0, s78, v[108:109]
	v_mad_i64_i32 v[88:89], s[62:63], v31, s78, v[108:109]
	global_load_dwordx4 v[48:51], v[48:49], off nt
	s_nop 0
	global_load_dwordx4 v[52:55], v[52:53], off nt
	s_nop 0
	global_load_dwordx4 v[56:59], v[56:57], off nt
	s_nop 0
	global_load_dwordx4 v[60:63], v[60:61], off nt
	s_nop 0
	global_load_dwordx4 v[64:67], v[64:65], off nt
	s_nop 0
	global_load_dwordx4 v[68:71], v[68:69], off nt
	s_nop 0
	global_load_dwordx4 v[72:75], v[72:73], off nt
	s_nop 0
	global_load_dwordx4 v[76:79], v[76:77], off nt
	s_nop 0
	global_load_dwordx4 v[80:83], v[80:81], off nt
	s_nop 0
	global_load_dwordx4 v[84:87], v[84:85], off nt
	v_or_b32_e32 v31, 44, v0
	global_load_dwordx4 v[88:91], v[88:89], off nt
	v_mad_i64_i32 v[92:93], s[62:63], v31, s78, v[108:109]
	global_load_dwordx4 v[92:95], v[92:93], off nt
	v_or_b32_e32 v31, 48, v0
	v_mad_i64_i32 v[96:97], s[62:63], v31, s78, v[108:109]
	global_load_dwordx4 v[96:99], v[96:97], off nt
	v_or_b32_e32 v31, 52, v0
	v_mad_i64_i32 v[100:101], s[62:63], v31, s78, v[108:109]
	global_load_dwordx4 v[100:103], v[100:101], off nt
	v_or_b32_e32 v31, 56, v0
	v_mad_i64_i32 v[104:105], s[62:63], v31, s78, v[108:109]
	global_load_dwordx4 v[104:107], v[104:105], off nt
	v_or_b32_e32 v0, 60, v0
	v_mad_i64_i32 v[108:109], s[62:63], v0, s78, v[108:109]
	global_load_dwordx4 v[108:111], v[108:109], off nt
	v_add_u32_e32 v0, 0xf0a0, v5
	s_and_b32 s33, s0, 64
	s_or_b32 s33, s33, s5
	s_ashr_i32 s62, s0, 7
	s_lshl_b32 s0, s33, 7
	s_ashr_i32 s5, s4, 31
	s_ashr_i32 s63, s62, 31
	s_and_b32 s0, s0, 0x6000
	s_add_u32 s0, s39, s0
	s_addc_u32 s33, s41, 0
	s_lshl_b64 s[62:63], s[62:63], 21
	s_lshl_b64 s[4:5], s[4:5], 15
	s_add_u32 s0, s0, s62
	v_add_u32_e32 v31, 0xc800, v9
	s_addc_u32 s33, s33, s63
	s_add_u32 s4, s0, s4
	v_add_u32_e32 v47, 0xcc00, v9
	s_addc_u32 s5, s33, s5
	s_waitcnt vmcnt(15)
	ds_write2_b32 v7, v48, v49 offset1:1
	ds_write2_b32 v11, v50, v51 offset1:1
	s_waitcnt vmcnt(14)
	ds_write2_b32 v13, v52, v53 offset1:1
	ds_write2_b32 v15, v54, v55 offset1:1
	s_waitcnt vmcnt(13)
	ds_write2_b32 v17, v56, v57 offset1:1
	ds_write2_b32 v19, v58, v59 offset1:1
	s_waitcnt vmcnt(12)
	ds_write2_b32 v32, v60, v61 offset1:1
	ds_write2_b32 v33, v62, v63 offset1:1
	s_waitcnt vmcnt(11)
	ds_write2_b32 v34, v64, v65 offset1:1
	ds_write2_b32 v36, v66, v67 offset1:1
	s_waitcnt vmcnt(10)
	ds_write2_b32 v37, v68, v69 offset1:1
	ds_write2_b32 v38, v70, v71 offset1:1
	s_waitcnt vmcnt(9)
	ds_write2_b32 v39, v72, v73 offset1:1
	ds_write2_b32 v40, v74, v75 offset1:1
	s_waitcnt vmcnt(8)
	ds_write2_b32 v41, v76, v77 offset1:1
	ds_write2_b32 v42, v78, v79 offset1:1
	s_waitcnt vmcnt(7)
	ds_write2_b32 v43, v80, v81 offset1:1
	ds_write2_b32 v44, v82, v83 offset1:1
	s_waitcnt vmcnt(6)
	ds_write2_b32 v45, v84, v85 offset1:1
	ds_write2_b32 v46, v86, v87 offset1:1
	s_waitcnt vmcnt(5)
	ds_write2_b32 v0, v88, v89 offset1:1
	v_add_u32_e32 v0, 0xf0a8, v5
	ds_write2_b32 v0, v90, v91 offset1:1
	v_add_u32_e32 v0, 0xf4b0, v5
	s_waitcnt vmcnt(4)
	ds_write2_b32 v0, v92, v93 offset1:1
	v_add_u32_e32 v0, 0xf4b8, v5
	ds_write2_b32 v0, v94, v95 offset1:1
	v_add_u32_e32 v0, 0xf8c0, v5
	s_waitcnt vmcnt(3)
	ds_write2_b32 v0, v96, v97 offset1:1
	v_add_u32_e32 v0, 0xf8c8, v5
	ds_write2_b32 v0, v98, v99 offset1:1
	v_add_u32_e32 v0, 0xfcd0, v5
	s_waitcnt vmcnt(2)
	ds_write2_b32 v0, v100, v101 offset1:1
	v_add_u32_e32 v0, 0xfcd8, v5
	ds_write2_b32 v0, v102, v103 offset1:1
	v_add_u32_e32 v0, 0x38e0, v7
	s_waitcnt vmcnt(1)
; #define LAS __attribute__((address_space(3)))
; __device__ __forceinline__ unsigned cvt_pk_bf16(float lo, float hi) { unsigned r; asm volatile("v_cvt_pk_bf16_f32 %0, %1, %2" : "=v"(r) : "v"(lo), "v"(hi)); return r; }
; #define LDS_WAIT() asm volatile("s_waitcnt lgkmcnt(0)" ::: "memory")
; __device__ __forceinline__ void transpose_item(const float* W, int N, bf16_t* WT, int nkt, int k0, int n0, int r0, int kbd, LAS float* scr, int lane) {
;     ...
;     for (int i = 0; i < 16; ++i) { LAS float* d = scr + (4 * i + lq) * 65 + 4 * l15; d[0] = v[i][0]; d[1] = v[i][1]; d[2] = v[i][2]; d[3] = v[i][3]; }
;     LDS_WAIT();
;     const int c = lane & 7;
; #pragma unroll
;     for (int j = 0; j < 8; ++j) { const int n = (lane >> 3) + 8 * j; const LAS float* s = scr + (8 * c) * 65 + n;
;         u32x4 o; o.x = cvt_pk_bf16(s[0], s[65]); o.y = cvt_pk_bf16(s[2 * 65], s[3 * 65]); o.z = cvt_pk_bf16(s[4 * 65], s[5 * 65]); o.w = cvt_pk_bf16(s[6 * 65], s[7 * 65]);
;         *(u32x4*)(WT + dst_off + (size_t)n * 64 + 8 * c) = o; }
;     LDS_WAIT();
; }
	ds_write2_b32 v0, v104, v105 offset1:1
	v_add_u32_e32 v0, 0x38e8, v7
	ds_write2_b32 v0, v106, v107 offset1:1
	v_add_u32_e32 v0, 0x3cf0, v7
	s_waitcnt vmcnt(0)
	ds_write2_b32 v0, v108, v109 offset1:1
	v_add_u32_e32 v0, 0x3cf8, v7
	ds_write2_b32 v0, v110, v111 offset1:1
	s_waitcnt lgkmcnt(0)
	ds_read2_b32 v[48:49], v31 offset1:65
	s_waitcnt lgkmcnt(0)
	v_cvt_pk_bf16_f32 v48, v48, v49
	ds_read2_b32 v[50:51], v31 offset0:130 offset1:195
	v_lshlrev_b32_e32 v0, 1, v2
	s_waitcnt lgkmcnt(0)
	v_cvt_pk_bf16_f32 v49, v50, v51
	ds_read2_b32 v[50:51], v47 offset0:4 offset1:69
	v_lshl_add_u64 v[54:55], s[4:5], 0, v[0:1]
	v_lshlrev_b32_e32 v0, 1, v4
	s_waitcnt lgkmcnt(0)
	v_cvt_pk_bf16_f32 v50, v50, v51
	ds_read2_b32 v[52:53], v47 offset0:134 offset1:199
	s_waitcnt lgkmcnt(0)
	v_cvt_pk_bf16_f32 v51, v52, v53
	v_lshl_add_u64 v[56:57], v[54:55], 0, v[0:1]
	ds_read2_b32 v[52:53], v31 offset0:8 offset1:73
	global_store_dwordx4 v[56:57], v[48:51], off
	v_lshlrev_b32_e32 v0, 1, v6
	v_lshl_add_u64 v[56:57], v[54:55], 0, v[0:1]
	s_waitcnt lgkmcnt(0)
	v_cvt_pk_bf16_f32 v48, v52, v53
	ds_read2_b32 v[50:51], v31 offset0:138 offset1:203
	s_waitcnt lgkmcnt(0)
	v_cvt_pk_bf16_f32 v49, v50, v51
	ds_read2_b32 v[50:51], v47 offset0:12 offset1:77
	s_waitcnt lgkmcnt(0)
	v_cvt_pk_bf16_f32 v50, v50, v51
	ds_read2_b32 v[52:53], v47 offset0:142 offset1:207
	s_waitcnt lgkmcnt(0)
	v_cvt_pk_bf16_f32 v51, v52, v53
	ds_read2_b32 v[52:53], v31 offset0:16 offset1:81
	global_store_dwordx4 v[56:57], v[48:51], off
	v_lshlrev_b32_e32 v0, 1, v8
	v_lshl_add_u64 v[56:57], v[54:55], 0, v[0:1]
	s_waitcnt lgkmcnt(0)
	v_cvt_pk_bf16_f32 v48, v52, v53
	ds_read2_b32 v[50:51], v31 offset0:146 offset1:211
	s_waitcnt lgkmcnt(0)
	v_cvt_pk_bf16_f32 v49, v50, v51
	ds_read2_b32 v[50:51], v47 offset0:20 offset1:85
	s_waitcnt lgkmcnt(0)
	v_cvt_pk_bf16_f32 v50, v50, v51
	ds_read2_b32 v[52:53], v47 offset0:150 offset1:215
	s_waitcnt lgkmcnt(0)
	v_cvt_pk_bf16_f32 v51, v52, v53
	ds_read2_b32 v[52:53], v31 offset0:24 offset1:89
	global_store_dwordx4 v[56:57], v[48:51], off
	v_lshlrev_b32_e32 v0, 1, v10
	v_lshl_add_u64 v[56:57], v[54:55], 0, v[0:1]
	s_waitcnt lgkmcnt(0)
	v_cvt_pk_bf16_f32 v48, v52, v53
	ds_read2_b32 v[50:51], v31 offset0:154 offset1:219
	s_waitcnt lgkmcnt(0)
	v_cvt_pk_bf16_f32 v49, v50, v51
	ds_read2_b32 v[50:51], v47 offset0:28 offset1:93
	s_waitcnt lgkmcnt(0)
	v_cvt_pk_bf16_f32 v50, v50, v51
	ds_read2_b32 v[52:53], v47 offset0:158 offset1:223
	s_waitcnt lgkmcnt(0)
	v_cvt_pk_bf16_f32 v51, v52, v53
	ds_read2_b32 v[52:53], v31 offset0:32 offset1:97
	global_store_dwordx4 v[56:57], v[48:51], off
	v_lshlrev_b32_e32 v0, 1, v12
	v_lshl_add_u64 v[56:57], v[54:55], 0, v[0:1]
	s_waitcnt lgkmcnt(0)
	v_cvt_pk_bf16_f32 v48, v52, v53
	ds_read2_b32 v[50:51], v31 offset0:162 offset1:227
	s_waitcnt lgkmcnt(0)
	v_cvt_pk_bf16_f32 v49, v50, v51
	ds_read2_b32 v[50:51], v47 offset0:36 offset1:101
	s_waitcnt lgkmcnt(0)
	v_cvt_pk_bf16_f32 v50, v50, v51
	ds_read2_b32 v[52:53], v47 offset0:166 offset1:231
	s_waitcnt lgkmcnt(0)
	v_cvt_pk_bf16_f32 v51, v52, v53
	ds_read2_b32 v[52:53], v31 offset0:40 offset1:105
	global_store_dwordx4 v[56:57], v[48:51], off
	v_lshlrev_b32_e32 v0, 1, v14
	v_lshl_add_u64 v[56:57], v[54:55], 0, v[0:1]
	s_waitcnt lgkmcnt(0)
	v_cvt_pk_bf16_f32 v48, v52, v53
	ds_read2_b32 v[50:51], v31 offset0:170 offset1:235
	s_waitcnt lgkmcnt(0)
	v_cvt_pk_bf16_f32 v49, v50, v51
	ds_read2_b32 v[50:51], v47 offset0:44 offset1:109
	s_waitcnt lgkmcnt(0)
	v_cvt_pk_bf16_f32 v50, v50, v51
	ds_read2_b32 v[52:53], v47 offset0:174 offset1:239
	s_waitcnt lgkmcnt(0)
	v_cvt_pk_bf16_f32 v51, v52, v53
	ds_read2_b32 v[52:53], v31 offset0:48 offset1:113
	global_store_dwordx4 v[56:57], v[48:51], off
	v_lshlrev_b32_e32 v0, 1, v16
	v_lshl_add_u64 v[56:57], v[54:55], 0, v[0:1]
	s_waitcnt lgkmcnt(0)
	v_cvt_pk_bf16_f32 v48, v52, v53
	ds_read2_b32 v[50:51], v31 offset0:178 offset1:243
	s_waitcnt lgkmcnt(0)
	v_cvt_pk_bf16_f32 v49, v50, v51
	ds_read2_b32 v[50:51], v47 offset0:52 offset1:117
	s_waitcnt lgkmcnt(0)
	v_cvt_pk_bf16_f32 v50, v50, v51
	ds_read2_b32 v[52:53], v47 offset0:182 offset1:247
	s_waitcnt lgkmcnt(0)
	v_cvt_pk_bf16_f32 v51, v52, v53
	ds_read2_b32 v[52:53], v31 offset0:56 offset1:121
	global_store_dwordx4 v[56:57], v[48:51], off
	v_lshlrev_b32_e32 v0, 1, v18
	s_waitcnt lgkmcnt(0)
	v_cvt_pk_bf16_f32 v48, v52, v53
	ds_read2_b32 v[50:51], v31 offset0:186 offset1:251
	s_waitcnt lgkmcnt(0)
	v_cvt_pk_bf16_f32 v49, v50, v51
	ds_read2_b32 v[50:51], v47 offset0:60 offset1:125
	s_waitcnt lgkmcnt(0)
	v_cvt_pk_bf16_f32 v50, v50, v51
	ds_read2_b32 v[52:53], v47 offset0:190 offset1:255
	s_waitcnt lgkmcnt(0)
	v_cvt_pk_bf16_f32 v51, v52, v53
	v_lshl_add_u64 v[52:53], v[54:55], 0, v[0:1]
	global_store_dwordx4 v[52:53], v[48:51], off
	s_waitcnt lgkmcnt(0)
	s_branch .LBB0_313

; #define LAS __attribute__((address_space(3)))
; __device__ __forceinline__ void transpose_item(const float* W, int N, bf16_t* WT, int nkt, int k0, int n0, int r0, int kbd, LAS float* scr, int lane) {
;     const size_t dst_off = ((size_t)(r0 >> 8) * nkt + kbd) * 16384 + (size_t)(r0 & 255) * 64;
;     const int l15 = lane & 15, lq = lane >> 4;
;     f32x4 v[16];
; #pragma unroll
;     for (int i = 0; i < 16; ++i) v[i] = *(const f32x4*)(W + (size_t)(k0 + 4 * i + lq) * N + n0 + 4 * l15);
; #pragma unroll
;     for (int i = 0; i < 16; ++i) { LAS float* d = scr + (4 * i + lq) * 65 + 4 * l15; d[0] = v[i][0]; d[1] = v[i][1]; d[2] = v[i][2]; d[3] = v[i][3]; }
; __device__ __forceinline__ void phase_convert_wdown(const Params& p, LAS float* scr, int cw, int NCW, int lane) {
;     unsigned char* ws = p.ws;
;     for (int it = cw; it < 172 * 64; it += NCW) { const int nb = it % 64, kb = it / 64; transpose_item(p.in[24], 4096, (bf16_t*)(ws + WS_W_DOWN), 172, kb * 64, nb * 64, nb * 64, kb, scr, lane); }
; }
.LBB0_801:
	s_ashr_i32 s9, s0, 31
	s_lshr_b32 s9, s9, 26
	s_add_i32 s9, s0, s9
	s_and_b32 s12, s7, 0x3000
	s_ashr_i32 s15, s9, 6
	s_andn2_b32 s9, s9, 63
	s_lshl_b32 s14, s12, 1
	s_lshl_b32 s12, s15, 12
	v_or_b32_e32 v20, s9, v22
	s_sub_i32 s12, s5, s12
	v_or_b32_e32 v56, 4, v20
	v_or_b32_e32 v58, 8, v20
	v_or_b32_e32 v60, 12, v20
	v_or_b32_e32 v62, 16, v20
	v_or_b32_e32 v64, 20, v20
	v_or_b32_e32 v66, 24, v20
	v_or_b32_e32 v68, 28, v20
	v_or_b32_e32 v70, 32, v20
	v_or_b32_e32 v72, 36, v20
	v_or_b32_e32 v74, 40, v20
	v_or_b32_e32 v76, 44, v20
	v_or_b32_e32 v78, 48, v20
	v_or_b32_e32 v80, 52, v20
	v_or_b32_e32 v82, 56, v20
	v_ashrrev_i32_e32 v21, 31, v20
	v_or_b32_e32 v84, 60, v20
	s_ashr_i32 s13, s12, 31
	v_ashrrev_i32_e32 v57, 31, v56
	v_ashrrev_i32_e32 v59, 31, v58
	v_ashrrev_i32_e32 v61, 31, v60
	v_ashrrev_i32_e32 v63, 31, v62
	v_ashrrev_i32_e32 v65, 31, v64
	v_ashrrev_i32_e32 v67, 31, v66
	v_ashrrev_i32_e32 v69, 31, v68
	v_ashrrev_i32_e32 v71, 31, v70
	v_ashrrev_i32_e32 v73, 31, v72
	v_ashrrev_i32_e32 v75, 31, v74
	v_ashrrev_i32_e32 v77, 31, v76
	v_ashrrev_i32_e32 v79, 31, v78
	v_ashrrev_i32_e32 v81, 31, v80
	v_ashrrev_i32_e32 v83, 31, v82
	v_lshlrev_b64 v[20:21], 14, v[20:21]
	v_ashrrev_i32_e32 v85, 31, v84
	v_lshl_add_u64 v[86:87], s[12:13], 2, v[2:3]
	v_lshlrev_b64 v[56:57], 14, v[56:57]
	v_lshlrev_b64 v[58:59], 14, v[58:59]
	v_lshlrev_b64 v[60:61], 14, v[60:61]
	v_lshlrev_b64 v[62:63], 14, v[62:63]
	v_lshlrev_b64 v[64:65], 14, v[64:65]
	v_lshlrev_b64 v[66:67], 14, v[66:67]
	v_lshlrev_b64 v[68:69], 14, v[68:69]
	v_lshlrev_b64 v[70:71], 14, v[70:71]
	v_lshlrev_b64 v[72:73], 14, v[72:73]
	v_lshlrev_b64 v[74:75], 14, v[74:75]
	v_lshlrev_b64 v[76:77], 14, v[76:77]
	v_lshlrev_b64 v[78:79], 14, v[78:79]
	v_lshlrev_b64 v[80:81], 14, v[80:81]
	v_lshlrev_b64 v[82:83], 14, v[82:83]
	v_lshlrev_b64 v[84:85], 14, v[84:85]
	v_lshl_add_u64 v[20:21], v[86:87], 0, v[20:21]
	v_lshl_add_u64 v[92:93], v[86:87], 0, v[56:57]
	v_lshl_add_u64 v[94:95], v[86:87], 0, v[58:59]
	v_lshl_add_u64 v[96:97], v[86:87], 0, v[60:61]
	v_lshl_add_u64 v[98:99], v[86:87], 0, v[62:63]
	v_lshl_add_u64 v[100:101], v[86:87], 0, v[64:65]
	v_lshl_add_u64 v[102:103], v[86:87], 0, v[66:67]
	v_lshl_add_u64 v[104:105], v[86:87], 0, v[68:69]
	v_lshl_add_u64 v[106:107], v[86:87], 0, v[70:71]
	v_lshl_add_u64 v[108:109], v[86:87], 0, v[72:73]
	v_lshl_add_u64 v[110:111], v[86:87], 0, v[74:75]
	v_lshl_add_u64 v[112:113], v[86:87], 0, v[76:77]
	v_lshl_add_u64 v[114:115], v[86:87], 0, v[78:79]
	v_lshl_add_u64 v[116:117], v[86:87], 0, v[80:81]
	v_lshl_add_u64 v[118:119], v[86:87], 0, v[82:83]
	v_lshl_add_u64 v[120:121], v[86:87], 0, v[84:85]
	global_load_dwordx4 v[56:59], v[20:21], off nt
	global_load_dwordx4 v[60:63], v[92:93], off nt
	global_load_dwordx4 v[64:67], v[94:95], off nt
	global_load_dwordx4 v[68:71], v[96:97], off nt
	global_load_dwordx4 v[72:75], v[98:99], off nt
	global_load_dwordx4 v[76:79], v[100:101], off nt
	global_load_dwordx4 v[80:83], v[102:103], off nt
	global_load_dwordx4 v[84:87], v[104:105], off nt
	global_load_dwordx4 v[88:91], v[106:107], off nt
	global_load_dwordx4 v[92:95], v[108:109], off nt
	global_load_dwordx4 v[96:99], v[110:111], off nt
	s_nop 0
	global_load_dwordx4 v[100:103], v[112:113], off nt
	global_load_dwordx4 v[104:107], v[114:115], off nt
	global_load_dwordx4 v[108:111], v[116:117], off nt
	s_nop 0
	global_load_dwordx4 v[112:115], v[118:119], off nt
	s_nop 0
	global_load_dwordx4 v[116:119], v[120:121], off nt
	s_sub_i32 s16, s0, s9
	s_lshr_b32 s9, s16, 2
	s_mulk_i32 s9, 0xac
	s_add_i32 s12, s9, s15
	s_ashr_i32 s13, s12, 31
	s_add_u32 s9, s3, s14
	s_addc_u32 s14, s4, 0
	s_lshl_b64 s[12:13], s[12:13], 15
	s_add_u32 s12, s9, s12
	s_addc_u32 s13, s14, s13
	v_lshl_add_u64 v[20:21], s[12:13], 0, v[0:1]
	v_lshl_add_u64 v[120:121], v[20:21], 0, v[4:5]
	v_lshl_add_u64 v[122:123], v[20:21], 0, v[6:7]
	s_waitcnt vmcnt(15)
	ds_write2_b32 v24, v56, v57 offset1:1
	ds_write2_b32 v24, v58, v59 offset0:2 offset1:3
	s_waitcnt vmcnt(14)
	ds_write2_b32 v25, v60, v61 offset1:1
	ds_write2_b32 v26, v62, v63 offset1:1
	s_waitcnt vmcnt(13)
	ds_write2_b32 v27, v64, v65 offset1:1
	ds_write2_b32 v28, v66, v67 offset1:1
	s_waitcnt vmcnt(12)
	ds_write2_b32 v29, v68, v69 offset1:1
	ds_write2_b32 v30, v70, v71 offset1:1
	s_waitcnt vmcnt(11)
	ds_write2_b32 v31, v72, v73 offset1:1
	ds_write2_b32 v32, v74, v75 offset1:1
	s_waitcnt vmcnt(10)
	ds_write2_b32 v33, v76, v77 offset1:1
	ds_write2_b32 v34, v78, v79 offset1:1
	s_waitcnt vmcnt(9)
	ds_write2_b32 v35, v80, v81 offset1:1
	ds_write2_b32 v36, v82, v83 offset1:1
	s_waitcnt vmcnt(8)
	ds_write2_b32 v37, v84, v85 offset1:1
	ds_write2_b32 v38, v86, v87 offset1:1
	s_waitcnt vmcnt(7)
	ds_write2_b32 v39, v88, v89 offset1:1
	ds_write2_b32 v40, v90, v91 offset1:1
	s_waitcnt vmcnt(6)
	ds_write2_b32 v41, v92, v93 offset1:1
	ds_write2_b32 v42, v94, v95 offset1:1
	s_waitcnt vmcnt(5)
; #define LAS __attribute__((address_space(3)))
; __device__ __forceinline__ unsigned cvt_pk_bf16(float lo, float hi) { unsigned r; asm volatile("v_cvt_pk_bf16_f32 %0, %1, %2" : "=v"(r) : "v"(lo), "v"(hi)); return r; }
; #define LDS_WAIT() asm volatile("s_waitcnt lgkmcnt(0)" ::: "memory")
; __device__ __forceinline__ void transpose_item(const float* W, int N, bf16_t* WT, int nkt, int k0, int n0, int r0, int kbd, LAS float* scr, int lane) {
;     ...
;     for (int i = 0; i < 16; ++i) { LAS float* d = scr + (4 * i + lq) * 65 + 4 * l15; d[0] = v[i][0]; d[1] = v[i][1]; d[2] = v[i][2]; d[3] = v[i][3]; }
;     LDS_WAIT();
;     const int c = lane & 7;
; #pragma unroll
;     for (int j = 0; j < 8; ++j) { const int n = (lane >> 3) + 8 * j; const LAS float* s = scr + (8 * c) * 65 + n;
;         u32x4 o; o.x = cvt_pk_bf16(s[0], s[65]); o.y = cvt_pk_bf16(s[2 * 65], s[3 * 65]); o.z = cvt_pk_bf16(s[4 * 65], s[5 * 65]); o.w = cvt_pk_bf16(s[6 * 65], s[7 * 65]);
;         *(u32x4*)(WT + dst_off + (size_t)n * 64 + 8 * c) = o; }
;     LDS_WAIT();
; }
; __device__ __forceinline__ void phase_convert_wdown(const Params& p, LAS float* scr, int cw, int NCW, int lane) {
;     ...
;     for (int it = cw; it < 172 * 64; it += NCW) { const int nb = it % 64, kb = it / 64; transpose_item(p.in[24], 4096, (bf16_t*)(ws + WS_W_DOWN), 172, kb * 64, nb * 64, nb * 64, kb, scr, lane); }
	ds_write2_b32 v43, v96, v97 offset1:1
	ds_write2_b32 v44, v98, v99 offset1:1
	s_waitcnt vmcnt(4)
	ds_write2_b32 v45, v100, v101 offset1:1
	ds_write2_b32 v46, v102, v103 offset1:1
	s_waitcnt vmcnt(3)
	ds_write2_b32 v47, v104, v105 offset1:1
	ds_write2_b32 v48, v106, v107 offset1:1
	s_waitcnt vmcnt(2)
	ds_write2_b32 v49, v108, v109 offset1:1
	ds_write2_b32 v50, v110, v111 offset1:1
	s_waitcnt vmcnt(1)
	ds_write2_b32 v51, v112, v113 offset1:1
	ds_write2_b32 v52, v114, v115 offset1:1
	s_waitcnt vmcnt(0)
	ds_write2_b32 v53, v116, v117 offset1:1
	ds_write2_b32 v54, v118, v119 offset1:1
	s_waitcnt lgkmcnt(0)
	ds_read2_b32 v[56:57], v23 offset1:65
	s_waitcnt lgkmcnt(0)
	v_cvt_pk_bf16_f32 v56, v56, v57
	ds_read2_b32 v[58:59], v23 offset0:130 offset1:195
	s_waitcnt lgkmcnt(0)
	v_cvt_pk_bf16_f32 v57, v58, v59
	ds_read2_b32 v[58:59], v55 offset0:4 offset1:69
	s_waitcnt lgkmcnt(0)
	v_cvt_pk_bf16_f32 v58, v58, v59
	ds_read2_b32 v[60:61], v55 offset0:134 offset1:199
	s_waitcnt lgkmcnt(0)
	v_cvt_pk_bf16_f32 v59, v60, v61
	ds_read2_b32 v[60:61], v23 offset0:8 offset1:73
	global_store_dwordx4 v[120:121], v[56:59], off
	v_lshl_add_u64 v[124:125], v[20:21], 0, v[8:9]
	v_lshl_add_u64 v[126:127], v[20:21], 0, v[10:11]
	s_waitcnt lgkmcnt(0)
	v_cvt_pk_bf16_f32 v56, v60, v61
	ds_read2_b32 v[58:59], v23 offset0:138 offset1:203
	s_waitcnt lgkmcnt(0)
	v_cvt_pk_bf16_f32 v57, v58, v59
	ds_read2_b32 v[58:59], v55 offset0:12 offset1:77
	s_waitcnt lgkmcnt(0)
	v_cvt_pk_bf16_f32 v58, v58, v59
	ds_read2_b32 v[60:61], v55 offset0:142 offset1:207
	s_waitcnt lgkmcnt(0)
	v_cvt_pk_bf16_f32 v59, v60, v61
	ds_read2_b32 v[60:61], v23 offset0:16 offset1:81
	global_store_dwordx4 v[122:123], v[56:59], off
	v_lshl_add_u64 v[128:129], v[20:21], 0, v[12:13]
	v_lshl_add_u64 v[130:131], v[20:21], 0, v[14:15]
	s_waitcnt lgkmcnt(0)
	v_cvt_pk_bf16_f32 v56, v60, v61
	ds_read2_b32 v[58:59], v23 offset0:146 offset1:211
	s_waitcnt lgkmcnt(0)
	v_cvt_pk_bf16_f32 v57, v58, v59
	ds_read2_b32 v[58:59], v55 offset0:20 offset1:85
	s_waitcnt lgkmcnt(0)
	v_cvt_pk_bf16_f32 v58, v58, v59
	ds_read2_b32 v[60:61], v55 offset0:150 offset1:215
	s_waitcnt lgkmcnt(0)
	v_cvt_pk_bf16_f32 v59, v60, v61
	ds_read2_b32 v[60:61], v23 offset0:24 offset1:89
	global_store_dwordx4 v[124:125], v[56:59], off
	v_lshl_add_u64 v[132:133], v[20:21], 0, v[16:17]
	v_lshl_add_u64 v[20:21], v[20:21], 0, v[18:19]
	s_waitcnt lgkmcnt(0)
	v_cvt_pk_bf16_f32 v56, v60, v61
	ds_read2_b32 v[58:59], v23 offset0:154 offset1:219
	s_waitcnt lgkmcnt(0)
	v_cvt_pk_bf16_f32 v57, v58, v59
	ds_read2_b32 v[58:59], v55 offset0:28 offset1:93
	s_waitcnt lgkmcnt(0)
	v_cvt_pk_bf16_f32 v58, v58, v59
	ds_read2_b32 v[60:61], v55 offset0:158 offset1:223
	s_waitcnt lgkmcnt(0)
	v_cvt_pk_bf16_f32 v59, v60, v61
	ds_read2_b32 v[60:61], v23 offset0:32 offset1:97
	global_store_dwordx4 v[126:127], v[56:59], off
	s_add_i32 s0, s0, s1
	s_add_i32 s5, s5, s6
	s_waitcnt lgkmcnt(0)
	v_cvt_pk_bf16_f32 v56, v60, v61
	ds_read2_b32 v[58:59], v23 offset0:162 offset1:227
	s_waitcnt lgkmcnt(0)
	v_cvt_pk_bf16_f32 v57, v58, v59
	ds_read2_b32 v[58:59], v55 offset0:36 offset1:101
	s_waitcnt lgkmcnt(0)
	v_cvt_pk_bf16_f32 v58, v58, v59
	ds_read2_b32 v[60:61], v55 offset0:166 offset1:231
	s_waitcnt lgkmcnt(0)
	v_cvt_pk_bf16_f32 v59, v60, v61
	ds_read2_b32 v[60:61], v23 offset0:40 offset1:105
	global_store_dwordx4 v[128:129], v[56:59], off
	s_add_i32 s7, s7, s8
	s_cmpk_lt_i32 s0, 0x2b00
	s_waitcnt lgkmcnt(0)
	v_cvt_pk_bf16_f32 v56, v60, v61
	ds_read2_b32 v[58:59], v23 offset0:170 offset1:235
	s_waitcnt lgkmcnt(0)
	v_cvt_pk_bf16_f32 v57, v58, v59
	ds_read2_b32 v[58:59], v55 offset0:44 offset1:109
	s_waitcnt lgkmcnt(0)
	v_cvt_pk_bf16_f32 v58, v58, v59
	ds_read2_b32 v[60:61], v55 offset0:174 offset1:239
	s_waitcnt lgkmcnt(0)
	v_cvt_pk_bf16_f32 v59, v60, v61
	ds_read2_b32 v[60:61], v23 offset0:48 offset1:113
	global_store_dwordx4 v[130:131], v[56:59], off
	s_waitcnt lgkmcnt(0)
	s_nop 0
	v_cvt_pk_bf16_f32 v56, v60, v61
	ds_read2_b32 v[58:59], v23 offset0:178 offset1:243
	s_waitcnt lgkmcnt(0)
	v_cvt_pk_bf16_f32 v57, v58, v59
	ds_read2_b32 v[58:59], v55 offset0:52 offset1:117
	s_waitcnt lgkmcnt(0)
	v_cvt_pk_bf16_f32 v58, v58, v59
	ds_read2_b32 v[60:61], v55 offset0:182 offset1:247
	s_waitcnt lgkmcnt(0)
	v_cvt_pk_bf16_f32 v59, v60, v61
	ds_read2_b32 v[60:61], v23 offset0:56 offset1:121
	global_store_dwordx4 v[132:133], v[56:59], off
	s_waitcnt lgkmcnt(0)
	s_nop 0
	v_cvt_pk_bf16_f32 v56, v60, v61
	ds_read2_b32 v[58:59], v23 offset0:186 offset1:251
	s_waitcnt lgkmcnt(0)
	v_cvt_pk_bf16_f32 v57, v58, v59
	ds_read2_b32 v[58:59], v55 offset0:60 offset1:125
	s_waitcnt lgkmcnt(0)
	v_cvt_pk_bf16_f32 v58, v58, v59
	ds_read2_b32 v[60:61], v55 offset0:190 offset1:255
	s_waitcnt lgkmcnt(0)
	v_cvt_pk_bf16_f32 v59, v60, v61
	global_store_dwordx4 v[20:21], v[56:59], off
	s_waitcnt lgkmcnt(0)
	s_cbranch_scc1 .LBB0_801

; __device__ __forceinline__ float bf_lo(unsigned w) { return __uint_as_float(w << 16); }
; __device__ __forceinline__ float bf_hi(unsigned w) { return __uint_as_float(w & 0xffff0000u); }
; __device__ __forceinline__ void phase_final(const Params& p, int gw, int NGW, int lane) {
;     unsigned char* ws = p.ws;
;     const bf16_t* DN = (const bf16_t*)(ws + WS_SD); const float* SSQ = (const float*)(ws + WS_SSQ2); const bf16_t* H1 = (const bf16_t*)(ws + WS_SC);
;     const f32x4* g = (const f32x4*)p.in[25];
;     for (int row = gw; row < MT; row += NGW) {
;         const float r = rsqrtf(wave_sum(SSQ[(size_t)lane * MT + row]) * (1.f / DM) + EPSN);
;         const u32x2* dr = (const u32x2*)(DN + (size_t)row * DM) + lane; const u32x2* hr = (const u32x2*)(H1 + (size_t)row * DM) + lane; f32x4* o = (f32x4*)(p.out + (size_t)row * DM) + lane;
;         const f32x4* gp = g + lane;
;         asm volatile("" : "+v"(gp), "+v"(dr), "+v"(hr), "+v"(o));
; #pragma unroll 8
;         for (int j = 0; j < 16; ++j) { const u32x2 dw = dr[64 * j]; const f32x4 dn = {bf_lo(dw.x), bf_hi(dw.x), bf_lo(dw.y), bf_hi(dw.y)}; const u32x2 hw = hr[64 * j]; const f32x4 hh = {bf_lo(hw.x), bf_hi(hw.x), bf_lo(hw.y), bf_hi(hw.y)}; o[64 * j] = hh + dn * r * gp[64 * j]; }
;     }
.Lfin_row:
	s_ashr_i32 s35, s34, 31
	s_lshl_b64 s[2:3], s[34:35], 13
	s_lshl_b64 s[6:7], s[34:35], 14
	s_add_i32 s10, s34, s60
	s_min_i32 s10, s10, 0x1fff
	s_ashr_i32 s11, s10, 31
	v_lshl_add_u64 v[10:11], s[10:11], 2, v[0:1]
	v_lshl_add_u64 v[12:13], v[2:3], 0, s[2:3]
	v_lshl_add_u64 v[14:15], v[4:5], 0, s[2:3]
	v_lshl_add_u64 v[16:17], v[8:9], 0, s[6:7]
	global_load_dword v33, v[10:11], off
	v_lshl_add_u64 v[22:23], v[16:17], 0, s[8:9]
	global_load_dwordx2 v[64:65], v[12:13], off offset:-4096 nt
	global_load_dwordx2 v[96:97], v[14:15], off offset:-4096 nt
	global_load_dwordx4 v[128:131], v[36:37], off offset:-4096
	global_load_dwordx2 v[66:67], v[12:13], off offset:-3584 nt
	global_load_dwordx2 v[98:99], v[14:15], off offset:-3584 nt
	global_load_dwordx4 v[132:135], v[36:37], off offset:-3072
	global_load_dwordx2 v[68:69], v[12:13], off offset:-3072 nt
	global_load_dwordx2 v[100:101], v[14:15], off offset:-3072 nt
	global_load_dwordx4 v[136:139], v[36:37], off offset:-2048
	global_load_dwordx2 v[70:71], v[12:13], off offset:-2560 nt
	global_load_dwordx2 v[102:103], v[14:15], off offset:-2560 nt
	global_load_dwordx4 v[140:143], v[36:37], off offset:-1024
	global_load_dwordx2 v[72:73], v[12:13], off offset:-2048 nt
	global_load_dwordx2 v[104:105], v[14:15], off offset:-2048 nt
	global_load_dwordx4 v[144:147], v[36:37], off
	global_load_dwordx2 v[74:75], v[12:13], off offset:-1536 nt
	global_load_dwordx2 v[106:107], v[14:15], off offset:-1536 nt
	global_load_dwordx4 v[148:151], v[36:37], off offset:1024
	global_load_dwordx2 v[76:77], v[12:13], off offset:-1024 nt
	global_load_dwordx2 v[108:109], v[14:15], off offset:-1024 nt
	global_load_dwordx4 v[152:155], v[36:37], off offset:2048
	global_load_dwordx2 v[78:79], v[12:13], off offset:-512 nt
	global_load_dwordx2 v[110:111], v[14:15], off offset:-512 nt
	global_load_dwordx4 v[156:159], v[36:37], off offset:3072
	global_load_dwordx2 v[80:81], v[12:13], off nt
	global_load_dwordx2 v[112:113], v[14:15], off nt
	global_load_dwordx4 v[160:163], v[38:39], off offset:-4096
	global_load_dwordx2 v[82:83], v[12:13], off offset:512 nt
	global_load_dwordx2 v[114:115], v[14:15], off offset:512 nt
	global_load_dwordx4 v[164:167], v[38:39], off offset:-3072
	global_load_dwordx2 v[84:85], v[12:13], off offset:1024 nt
	global_load_dwordx2 v[116:117], v[14:15], off offset:1024 nt
	global_load_dwordx4 v[168:171], v[38:39], off offset:-2048
	global_load_dwordx2 v[86:87], v[12:13], off offset:1536 nt
	global_load_dwordx2 v[118:119], v[14:15], off offset:1536 nt
	global_load_dwordx4 v[172:175], v[38:39], off offset:-1024
	global_load_dwordx2 v[88:89], v[12:13], off offset:2048 nt
	global_load_dwordx2 v[120:121], v[14:15], off offset:2048 nt
	global_load_dwordx4 v[176:179], v[38:39], off
	global_load_dwordx2 v[90:91], v[12:13], off offset:2560 nt
	global_load_dwordx2 v[122:123], v[14:15], off offset:2560 nt
	global_load_dwordx4 v[180:183], v[38:39], off offset:1024
	global_load_dwordx2 v[92:93], v[12:13], off offset:3072 nt
	global_load_dwordx2 v[124:125], v[14:15], off offset:3072 nt
	global_load_dwordx4 v[184:187], v[38:39], off offset:2048
	global_load_dwordx2 v[94:95], v[12:13], off offset:3584 nt
	global_load_dwordx2 v[126:127], v[14:15], off offset:3584 nt
	global_load_dwordx4 v[188:191], v[38:39], off offset:3072
	s_waitcnt vmcnt(45)
	v_lshlrev_b32_e32 v40, 16, v64
	v_and_b32_e32 v41, 0xffff0000, v64
	v_lshlrev_b32_e32 v42, 16, v65
	v_and_b32_e32 v43, 0xffff0000, v65
	v_lshlrev_b32_e32 v44, 16, v96
	v_and_b32_e32 v45, 0xffff0000, v96
	v_lshlrev_b32_e32 v46, 16, v97
	v_and_b32_e32 v47, 0xffff0000, v97
	v_pk_mul_f32 v[40:41], v[18:19], v[40:41]
	v_pk_mul_f32 v[42:43], v[18:19], v[42:43]
	v_pk_fma_f32 v[128:129], v[128:129], v[40:41], v[44:45]
	v_pk_fma_f32 v[130:131], v[130:131], v[42:43], v[46:47]
	global_store_dwordx4 v[16:17], v[128:131], off offset:-4096
	s_waitcnt vmcnt(43)
	v_lshlrev_b32_e32 v48, 16, v66
	v_and_b32_e32 v49, 0xffff0000, v66
	v_lshlrev_b32_e32 v50, 16, v67
	v_and_b32_e32 v51, 0xffff0000, v67
	v_lshlrev_b32_e32 v52, 16, v98
	v_and_b32_e32 v53, 0xffff0000, v98
	v_lshlrev_b32_e32 v54, 16, v99
	v_and_b32_e32 v55, 0xffff0000, v99
	v_pk_mul_f32 v[48:49], v[18:19], v[48:49]
	v_pk_mul_f32 v[50:51], v[18:19], v[50:51]
	v_pk_fma_f32 v[132:133], v[132:133], v[48:49], v[52:53]
	v_pk_fma_f32 v[134:135], v[134:135], v[50:51], v[54:55]
	global_store_dwordx4 v[16:17], v[132:135], off offset:-3072
	s_waitcnt vmcnt(41)
	v_lshlrev_b32_e32 v40, 16, v68
	v_and_b32_e32 v41, 0xffff0000, v68
	v_lshlrev_b32_e32 v42, 16, v69
	v_and_b32_e32 v43, 0xffff0000, v69
	v_lshlrev_b32_e32 v44, 16, v100
	v_and_b32_e32 v45, 0xffff0000, v100
	v_lshlrev_b32_e32 v46, 16, v101
	v_and_b32_e32 v47, 0xffff0000, v101
	v_pk_mul_f32 v[40:41], v[18:19], v[40:41]
	v_pk_mul_f32 v[42:43], v[18:19], v[42:43]
	v_pk_fma_f32 v[136:137], v[136:137], v[40:41], v[44:45]
	v_pk_fma_f32 v[138:139], v[138:139], v[42:43], v[46:47]
	global_store_dwordx4 v[16:17], v[136:139], off offset:-2048
	s_waitcnt vmcnt(39)
	v_lshlrev_b32_e32 v48, 16, v70
	v_and_b32_e32 v49, 0xffff0000, v70
	v_lshlrev_b32_e32 v50, 16, v71
	v_and_b32_e32 v51, 0xffff0000, v71
	v_lshlrev_b32_e32 v52, 16, v102
	v_and_b32_e32 v53, 0xffff0000, v102
	v_lshlrev_b32_e32 v54, 16, v103
	v_and_b32_e32 v55, 0xffff0000, v103
	v_pk_mul_f32 v[48:49], v[18:19], v[48:49]
	v_pk_mul_f32 v[50:51], v[18:19], v[50:51]
	v_pk_fma_f32 v[140:141], v[140:141], v[48:49], v[52:53]
	v_pk_fma_f32 v[142:143], v[142:143], v[50:51], v[54:55]
	global_store_dwordx4 v[16:17], v[140:143], off offset:-1024
	s_waitcnt vmcnt(37)
; __device__ __forceinline__ float bf_lo(unsigned w) { return __uint_as_float(w << 16); }
; __device__ __forceinline__ float bf_hi(unsigned w) { return __uint_as_float(w & 0xffff0000u); }
; __device__ __forceinline__ void phase_final(const Params& p, int gw, int NGW, int lane) {
;     ...
;         for (int j = 0; j < 16; ++j) { const u32x2 dw = dr[64 * j]; const f32x4 dn = {bf_lo(dw.x), bf_hi(dw.x), bf_lo(dw.y), bf_hi(dw.y)}; const u32x2 hw = hr[64 * j]; const f32x4 hh = {bf_lo(hw.x), bf_hi(hw.x), bf_lo(hw.y), bf_hi(hw.y)}; o[64 * j] = hh + dn * r * gp[64 * j]; }
	v_lshlrev_b32_e32 v40, 16, v72
	v_and_b32_e32 v41, 0xffff0000, v72
	v_lshlrev_b32_e32 v42, 16, v73
	v_and_b32_e32 v43, 0xffff0000, v73
	v_lshlrev_b32_e32 v44, 16, v104
	v_and_b32_e32 v45, 0xffff0000, v104
	v_lshlrev_b32_e32 v46, 16, v105
	v_and_b32_e32 v47, 0xffff0000, v105
	v_pk_mul_f32 v[40:41], v[18:19], v[40:41]
	v_pk_mul_f32 v[42:43], v[18:19], v[42:43]
	v_pk_fma_f32 v[144:145], v[144:145], v[40:41], v[44:45]
	v_pk_fma_f32 v[146:147], v[146:147], v[42:43], v[46:47]
	global_store_dwordx4 v[16:17], v[144:147], off
	s_waitcnt vmcnt(35)
	v_lshlrev_b32_e32 v48, 16, v74
	v_and_b32_e32 v49, 0xffff0000, v74
	v_lshlrev_b32_e32 v50, 16, v75
	v_and_b32_e32 v51, 0xffff0000, v75
	v_lshlrev_b32_e32 v52, 16, v106
	v_and_b32_e32 v53, 0xffff0000, v106
	v_lshlrev_b32_e32 v54, 16, v107
	v_and_b32_e32 v55, 0xffff0000, v107
	v_pk_mul_f32 v[48:49], v[18:19], v[48:49]
	v_pk_mul_f32 v[50:51], v[18:19], v[50:51]
	v_pk_fma_f32 v[148:149], v[148:149], v[48:49], v[52:53]
	v_pk_fma_f32 v[150:151], v[150:151], v[50:51], v[54:55]
	global_store_dwordx4 v[16:17], v[148:151], off offset:1024
	s_waitcnt vmcnt(33)
	v_lshlrev_b32_e32 v40, 16, v76
	v_and_b32_e32 v41, 0xffff0000, v76
	v_lshlrev_b32_e32 v42, 16, v77
	v_and_b32_e32 v43, 0xffff0000, v77
	v_lshlrev_b32_e32 v44, 16, v108
	v_and_b32_e32 v45, 0xffff0000, v108
	v_lshlrev_b32_e32 v46, 16, v109
	v_and_b32_e32 v47, 0xffff0000, v109
	v_pk_mul_f32 v[40:41], v[18:19], v[40:41]
	v_pk_mul_f32 v[42:43], v[18:19], v[42:43]
	v_pk_fma_f32 v[152:153], v[152:153], v[40:41], v[44:45]
	v_pk_fma_f32 v[154:155], v[154:155], v[42:43], v[46:47]
	global_store_dwordx4 v[16:17], v[152:155], off offset:2048
	s_waitcnt vmcnt(31)
	v_lshlrev_b32_e32 v48, 16, v78
	v_and_b32_e32 v49, 0xffff0000, v78
	v_lshlrev_b32_e32 v50, 16, v79
	v_and_b32_e32 v51, 0xffff0000, v79
	v_lshlrev_b32_e32 v52, 16, v110
	v_and_b32_e32 v53, 0xffff0000, v110
	v_lshlrev_b32_e32 v54, 16, v111
	v_and_b32_e32 v55, 0xffff0000, v111
	v_pk_mul_f32 v[48:49], v[18:19], v[48:49]
	v_pk_mul_f32 v[50:51], v[18:19], v[50:51]
	v_pk_fma_f32 v[156:157], v[156:157], v[48:49], v[52:53]
	v_pk_fma_f32 v[158:159], v[158:159], v[50:51], v[54:55]
	global_store_dwordx4 v[16:17], v[156:159], off offset:3072
	s_waitcnt vmcnt(29)
	v_lshlrev_b32_e32 v40, 16, v80
	v_and_b32_e32 v41, 0xffff0000, v80
	v_lshlrev_b32_e32 v42, 16, v81
	v_and_b32_e32 v43, 0xffff0000, v81
	v_lshlrev_b32_e32 v44, 16, v112
	v_and_b32_e32 v45, 0xffff0000, v112
	v_lshlrev_b32_e32 v46, 16, v113
	v_and_b32_e32 v47, 0xffff0000, v113
	v_pk_mul_f32 v[40:41], v[18:19], v[40:41]
	v_pk_mul_f32 v[42:43], v[18:19], v[42:43]
	v_pk_fma_f32 v[160:161], v[160:161], v[40:41], v[44:45]
	v_pk_fma_f32 v[162:163], v[162:163], v[42:43], v[46:47]
	global_store_dwordx4 v[22:23], v[160:163], off offset:-4096
	s_waitcnt vmcnt(27)
	v_lshlrev_b32_e32 v48, 16, v82
	v_and_b32_e32 v49, 0xffff0000, v82
	v_lshlrev_b32_e32 v50, 16, v83
	v_and_b32_e32 v51, 0xffff0000, v83
	v_lshlrev_b32_e32 v52, 16, v114
	v_and_b32_e32 v53, 0xffff0000, v114
	v_lshlrev_b32_e32 v54, 16, v115
	v_and_b32_e32 v55, 0xffff0000, v115
	v_pk_mul_f32 v[48:49], v[18:19], v[48:49]
	v_pk_mul_f32 v[50:51], v[18:19], v[50:51]
	v_pk_fma_f32 v[164:165], v[164:165], v[48:49], v[52:53]
	v_pk_fma_f32 v[166:167], v[166:167], v[50:51], v[54:55]
	global_store_dwordx4 v[22:23], v[164:167], off offset:-3072
	s_waitcnt vmcnt(25)
	v_lshlrev_b32_e32 v40, 16, v84
	v_and_b32_e32 v41, 0xffff0000, v84
	v_lshlrev_b32_e32 v42, 16, v85
	v_and_b32_e32 v43, 0xffff0000, v85
	v_lshlrev_b32_e32 v44, 16, v116
	v_and_b32_e32 v45, 0xffff0000, v116
	v_lshlrev_b32_e32 v46, 16, v117
	v_and_b32_e32 v47, 0xffff0000, v117
	v_pk_mul_f32 v[40:41], v[18:19], v[40:41]
	v_pk_mul_f32 v[42:43], v[18:19], v[42:43]
	v_pk_fma_f32 v[168:169], v[168:169], v[40:41], v[44:45]
	v_pk_fma_f32 v[170:171], v[170:171], v[42:43], v[46:47]
	global_store_dwordx4 v[22:23], v[168:171], off offset:-2048
	s_waitcnt vmcnt(23)
; __device__ __forceinline__ float bf_lo(unsigned w) { return __uint_as_float(w << 16); }
; __device__ __forceinline__ float bf_hi(unsigned w) { return __uint_as_float(w & 0xffff0000u); }
; __device__ __forceinline__ float wave_sum(float v) {
; #pragma unroll
;     for (int o = 1; o < 64; o <<= 1) v += __shfl_xor(v, o);
;     return v;
; }
; __device__ __forceinline__ void phase_final(const Params& p, int gw, int NGW, int lane) {
;     unsigned char* ws = p.ws;
;     const bf16_t* DN = (const bf16_t*)(ws + WS_SD); const float* SSQ = (const float*)(ws + WS_SSQ2); const bf16_t* H1 = (const bf16_t*)(ws + WS_SC);
;     const f32x4* g = (const f32x4*)p.in[25];
;     for (int row = gw; row < MT; row += NGW) {
;         const float r = rsqrtf(wave_sum(SSQ[(size_t)lane * MT + row]) * (1.f / DM) + EPSN);
;         const u32x2* dr = (const u32x2*)(DN + (size_t)row * DM) + lane; const u32x2* hr = (const u32x2*)(H1 + (size_t)row * DM) + lane; f32x4* o = (f32x4*)(p.out + (size_t)row * DM) + lane;
;         const f32x4* gp = g + lane;
;         asm volatile("" : "+v"(gp), "+v"(dr), "+v"(hr), "+v"(o));
; #pragma unroll 8
;         for (int j = 0; j < 16; ++j) { const u32x2 dw = dr[64 * j]; const f32x4 dn = {bf_lo(dw.x), bf_hi(dw.x), bf_lo(dw.y), bf_hi(dw.y)}; const u32x2 hw = hr[64 * j]; const f32x4 hh = {bf_lo(hw.x), bf_hi(hw.x), bf_lo(hw.y), bf_hi(hw.y)}; o[64 * j] = hh + dn * r * gp[64 * j]; }
;     }
	v_lshlrev_b32_e32 v48, 16, v86
	v_and_b32_e32 v49, 0xffff0000, v86
	v_lshlrev_b32_e32 v50, 16, v87
	v_and_b32_e32 v51, 0xffff0000, v87
	v_lshlrev_b32_e32 v52, 16, v118
	v_and_b32_e32 v53, 0xffff0000, v118
	v_lshlrev_b32_e32 v54, 16, v119
	v_and_b32_e32 v55, 0xffff0000, v119
	v_pk_mul_f32 v[48:49], v[18:19], v[48:49]
	v_pk_mul_f32 v[50:51], v[18:19], v[50:51]
	v_pk_fma_f32 v[172:173], v[172:173], v[48:49], v[52:53]
	v_pk_fma_f32 v[174:175], v[174:175], v[50:51], v[54:55]
	global_store_dwordx4 v[22:23], v[172:175], off offset:-1024
	s_waitcnt vmcnt(21)
	v_lshlrev_b32_e32 v40, 16, v88
	v_and_b32_e32 v41, 0xffff0000, v88
	v_lshlrev_b32_e32 v42, 16, v89
	v_and_b32_e32 v43, 0xffff0000, v89
	v_lshlrev_b32_e32 v44, 16, v120
	v_and_b32_e32 v45, 0xffff0000, v120
	v_lshlrev_b32_e32 v46, 16, v121
	v_and_b32_e32 v47, 0xffff0000, v121
	v_pk_mul_f32 v[40:41], v[18:19], v[40:41]
	v_pk_mul_f32 v[42:43], v[18:19], v[42:43]
	v_pk_fma_f32 v[176:177], v[176:177], v[40:41], v[44:45]
	v_pk_fma_f32 v[178:179], v[178:179], v[42:43], v[46:47]
	global_store_dwordx4 v[22:23], v[176:179], off
	s_waitcnt vmcnt(19)
	v_lshlrev_b32_e32 v48, 16, v90
	v_and_b32_e32 v49, 0xffff0000, v90
	v_lshlrev_b32_e32 v50, 16, v91
	v_and_b32_e32 v51, 0xffff0000, v91
	v_lshlrev_b32_e32 v52, 16, v122
	v_and_b32_e32 v53, 0xffff0000, v122
	v_lshlrev_b32_e32 v54, 16, v123
	v_and_b32_e32 v55, 0xffff0000, v123
	v_pk_mul_f32 v[48:49], v[18:19], v[48:49]
	v_pk_mul_f32 v[50:51], v[18:19], v[50:51]
	v_pk_fma_f32 v[180:181], v[180:181], v[48:49], v[52:53]
	v_pk_fma_f32 v[182:183], v[182:183], v[50:51], v[54:55]
	global_store_dwordx4 v[22:23], v[180:183], off offset:1024
	s_waitcnt vmcnt(17)
	v_lshlrev_b32_e32 v40, 16, v92
	v_and_b32_e32 v41, 0xffff0000, v92
	v_lshlrev_b32_e32 v42, 16, v93
	v_and_b32_e32 v43, 0xffff0000, v93
	v_lshlrev_b32_e32 v44, 16, v124
	v_and_b32_e32 v45, 0xffff0000, v124
	v_lshlrev_b32_e32 v46, 16, v125
	v_and_b32_e32 v47, 0xffff0000, v125
	v_pk_mul_f32 v[40:41], v[18:19], v[40:41]
	v_pk_mul_f32 v[42:43], v[18:19], v[42:43]
	v_pk_fma_f32 v[184:185], v[184:185], v[40:41], v[44:45]
	v_pk_fma_f32 v[186:187], v[186:187], v[42:43], v[46:47]
	global_store_dwordx4 v[22:23], v[184:187], off offset:2048
	s_waitcnt vmcnt(15)
	v_lshlrev_b32_e32 v48, 16, v94
	v_and_b32_e32 v49, 0xffff0000, v94
	v_lshlrev_b32_e32 v50, 16, v95
	v_and_b32_e32 v51, 0xffff0000, v95
	v_lshlrev_b32_e32 v52, 16, v126
	v_and_b32_e32 v53, 0xffff0000, v126
	v_lshlrev_b32_e32 v54, 16, v127
	v_and_b32_e32 v55, 0xffff0000, v127
	v_pk_mul_f32 v[48:49], v[18:19], v[48:49]
	v_pk_mul_f32 v[50:51], v[18:19], v[50:51]
	v_pk_fma_f32 v[188:189], v[188:189], v[48:49], v[52:53]
	v_pk_fma_f32 v[190:191], v[190:191], v[50:51], v[54:55]
	global_store_dwordx4 v[22:23], v[188:191], off offset:3072
	ds_bpermute_b32 v11, v26, v33
	s_waitcnt lgkmcnt(0)
	v_add_f32_e32 v10, v33, v11
	ds_bpermute_b32 v11, v27, v10
	s_waitcnt lgkmcnt(0)
	v_add_f32_e32 v10, v10, v11
	ds_bpermute_b32 v11, v28, v10
	s_waitcnt lgkmcnt(0)
	v_add_f32_e32 v10, v10, v11
	ds_bpermute_b32 v11, v29, v10
	s_waitcnt lgkmcnt(0)
	v_add_f32_e32 v10, v10, v11
	ds_bpermute_b32 v11, v30, v10
	s_waitcnt lgkmcnt(0)
	v_add_f32_e32 v10, v10, v11
	ds_bpermute_b32 v11, v31, v10
	s_waitcnt lgkmcnt(0)
	v_add_f32_e32 v10, v10, v11
	v_fmamk_f32 v14, v10, 0x39800000, v32
	v_mul_f32_e32 v15, 0x4b800000, v14
	v_cmp_gt_f32_e32 vcc, s4, v14
	s_nop 1
	v_cndmask_b32_e32 v14, v14, v15, vcc
	v_rsq_f32_e32 v18, v14
	s_nop 0
	v_mul_f32_e32 v19, 0x45800000, v18
	v_cndmask_b32_e32 v18, v18, v19, vcc
	v_mov_b32_e32 v19, v18
	s_add_i32 s34, s34, s60
	s_cmpk_gt_i32 s34, 0x1fff
	s_cbranch_scc0 .Lfin_row
